# MFMA issue order: every second accumulator pair issues its two K-steps in the opposite order so consecutive MFMAs share an operand quad or the accumulator
# baseline (speedup 1.0000x reference)
; #define PG8_STAGE(bufoff, gbase, voff) do { _Pragma("unroll") for (int _i = 0; _i < 2; ++_i) { \
;         const unsigned _m0 = ldsb + (unsigned)((bufoff) + _i * 8192); const char* _gb = (const char*)(gbase); \
;         asm volatile("s_mov_b32 m0, %0\n\ts_nop 0\n\tglobal_load_lds_dwordx4 %1, %2" :: "s"(_m0), "v"((voff)[_i]), "s"(_gb) : "m0", "memory"); } } while (0)
; #define PG8_LDA(dst, b, h) do { _Pragma("unroll") for (int m = 0; m < 4; ++m) _Pragma("unroll") for (int k = 0; k < 2; ++k) dst[m][k] = *(const LAS bf16x8*)(lds + PG8_SA(b, h) + aoff + m * 2048 + k * 1024); } while (0)
; #define PG8_LDB(dst, b, h) do { _Pragma("unroll") for (int n = 0; n < 2; ++n) _Pragma("unroll") for (int k = 0; k < 2; ++k) dst[n][k] = *(const LAS bf16x8*)(lds + PG8_SB(b, h) + boff + n * 2048 + k * 1024); } while (0)
; template <class Epi, bool ALIGN_EPI>
; __device__ __forceinline__ void gemm_phase(LAS unsigned char* lds, const Gemm g, const StaticOrder& S, const Epi& E) {
;     ...
;         for (int t = 0; t < nt; t += 2) {
;             const bool last = (t == nt - 2);
;             const char* a1 = cA + (size_t)(t + 1) * kstep;
;             const char* a2 = last ? nA : cA + (size_t)(t + 2) * kstep; const char* b2 = last ? nB : cB + (size_t)(t + 2) * kstep;
;             const char* a3 = a2 + kstep; const char* b3 = b2 + kstep;
;             PG8_LDB(B0, 0, 0); PG8_LDB(B1, 0, 1); PG8_SCHED; PG8_LDA(At, 0, 0); PG8_STAGE(PG8_SA(1, 1), a1 + hstepA, voffA);
;             PG8_WAIT_V(8); PG8_WAIT_L(0); PG8_BAR; PG8_MMA(0, 0, At, B0); PG8_MMA(0, 1, At, B1); PG8_BAR; PG8_SCHED;
;             PG8_LDA(At, 0, 1); PG8_STAGE(PG8_SB(0, 0), b2, voffB); PG8_STAGE(PG8_SB(0, 1), b2 + hstepB, voffB); PG8_STAGE(PG8_SA(0, 0), a2, voffA);
;             PG8_WAIT_V(8); PG8_WAIT_L(0); PG8_BAR; PG8_MMA(1, 0, At, B0); PG8_MMA(1, 1, At, B1); PG8_BAR; PG8_SCHED;
;             PG8_LDB(B0, 1, 0); PG8_LDB(B1, 1, 1); PG8_SCHED; PG8_LDA(At, 1, 0); PG8_STAGE(PG8_SA(0, 1), a2 + hstepA, voffA);
;             PG8_WAIT_V(8); PG8_WAIT_L(0); PG8_BAR; PG8_MMA(0, 0, At, B0); PG8_MMA(0, 1, At, B1); PG8_BAR; PG8_SCHED;
;             PG8_LDA(At, 1, 1); PG8_STAGE(PG8_SB(1, 0), b3, voffB); PG8_STAGE(PG8_SB(1, 1), b3 + hstepB, voffB); PG8_STAGE(PG8_SA(1, 0), a3, voffA);
;             PG8_WAIT_V(8); PG8_WAIT_L(0); PG8_BAR; PG8_MMA(1, 0, At, B0); PG8_MMA(1, 1, At, B1); PG8_BAR; PG8_SCHED;
.LBB0_150:
	s_add_u32 s4, s48, 0x100
	s_addc_u32 s5, s49, 0
	s_add_u32 s37, s54, 0x100
	s_addc_u32 s44, s55, 0
	s_mov_b32 s45, 0
	s_waitcnt lgkmcnt(0)
	s_add_i32 s51, s45, 2
	s_cmp_eq_u32 s67, s45
	s_cselect_b32 s56, s0, s37
	s_cselect_b32 s57, s1, s44
	s_cselect_b32 s54, s94, s4
	s_cselect_b32 s55, s95, s5
	s_add_u32 s48, s56, 0x80
	s_addc_u32 s49, s57, 0
	s_add_u32 s45, s37, s15
	s_addc_u32 s59, s44, 0
	s_add_u32 s58, s45, 0xffffff80
	s_addc_u32 s59, s59, -1
	s_mov_b32 m0, s68
	s_nop 0
	global_load_lds_dwordx4 v0, s[58:59]
	s_nop 0
	s_mov_b32 m0, s85
	s_nop 0
	global_load_lds_dwordx4 v240, s[58:59]
	s_waitcnt vmcnt(8)
	s_waitcnt lgkmcnt(0)
	s_setprio 1
	s_barrier
	v_mfma_f32_16x16x32_bf16 v[172:175], v[108:111], v[156:159], 0
	v_mfma_f32_16x16x32_bf16 v[172:175], v[120:123], v[160:163], v[172:175]
	v_mfma_f32_16x16x32_bf16 v[168:171], v[132:135], v[160:163], 0
	v_mfma_f32_16x16x32_bf16 v[168:171], v[128:131], v[156:159], v[168:171]
	v_mfma_f32_16x16x32_bf16 v[140:143], v[136:139], v[156:159], 0
	v_mfma_f32_16x16x32_bf16 v[140:143], v[144:147], v[160:163], v[140:143]
	v_mfma_f32_16x16x32_bf16 v[124:127], v[152:155], v[160:163], 0
	v_mfma_f32_16x16x32_bf16 v[124:127], v[148:151], v[156:159], v[124:127]
	v_mfma_f32_16x16x32_bf16 v[100:103], v[148:151], v[164:167], 0
	v_mfma_f32_16x16x32_bf16 v[100:103], v[152:155], v[176:179], v[100:103]
	v_mfma_f32_16x16x32_bf16 v[104:107], v[144:147], v[176:179], 0
	v_mfma_f32_16x16x32_bf16 v[104:107], v[136:139], v[164:167], v[104:107]
	v_mfma_f32_16x16x32_bf16 v[112:115], v[128:131], v[164:167], 0
	v_mfma_f32_16x16x32_bf16 v[112:115], v[132:135], v[176:179], v[112:115]
	v_mfma_f32_16x16x32_bf16 v[116:119], v[120:123], v[176:179], 0
	v_mfma_f32_16x16x32_bf16 v[116:119], v[108:111], v[164:167], v[116:119]
	v_mfma_f32_16x16x32_bf16 v[96:99], v[108:111], v[180:183], 0
	v_mfma_f32_16x16x32_bf16 v[96:99], v[120:123], v[184:187], v[96:99]
	v_mfma_f32_16x16x32_bf16 v[92:95], v[132:135], v[184:187], 0
	v_mfma_f32_16x16x32_bf16 v[92:95], v[128:131], v[180:183], v[92:95]
	v_mfma_f32_16x16x32_bf16 v[88:91], v[136:139], v[180:183], 0
	v_mfma_f32_16x16x32_bf16 v[88:91], v[144:147], v[184:187], v[88:91]
	v_mfma_f32_16x16x32_bf16 v[84:87], v[152:155], v[184:187], 0
	v_mfma_f32_16x16x32_bf16 v[84:87], v[148:151], v[180:183], v[84:87]
	v_mfma_f32_16x16x32_bf16 v[68:71], v[148:151], v[188:191], 0
	v_mfma_f32_16x16x32_bf16 v[68:71], v[152:155], v[202:205], v[68:71]
	v_mfma_f32_16x16x32_bf16 v[72:75], v[144:147], v[202:205], 0
	v_mfma_f32_16x16x32_bf16 v[72:75], v[136:139], v[188:191], v[72:75]
	v_mfma_f32_16x16x32_bf16 v[76:79], v[128:131], v[188:191], 0
	v_mfma_f32_16x16x32_bf16 v[76:79], v[132:135], v[202:205], v[76:79]
	v_mfma_f32_16x16x32_bf16 v[80:83], v[120:123], v[202:205], 0
	v_mfma_f32_16x16x32_bf16 v[80:83], v[108:111], v[188:191], v[80:83]
	s_barrier
	s_setprio 0
	ds_read_b128 v[156:159], v245 offset:16384
	ds_read_b128 v[160:163], v245 offset:17408
	ds_read_b128 v[164:167], v245 offset:18432
	ds_read_b128 v[176:179], v245 offset:19456
	ds_read_b128 v[180:183], v245 offset:20480
	ds_read_b128 v[184:187], v245 offset:21504
	ds_read_b128 v[188:191], v245 offset:22528
	ds_read_b128 v[202:205], v245 offset:23552
	s_mov_b32 m0, s27
	s_nop 0
	global_load_lds_dwordx4 v195, s[54:55]
	s_add_u32 s58, s54, s15
	s_mov_b32 m0, s28
	s_nop 0
	global_load_lds_dwordx4 v241, s[54:55]
	s_addc_u32 s59, s55, 0
	s_mov_b32 m0, s29
	s_nop 0
	global_load_lds_dwordx4 v195, s[58:59]
	s_nop 0
	s_mov_b32 m0, s30
	s_nop 0
	global_load_lds_dwordx4 v241, s[58:59]
	s_nop 0
	s_mov_b32 m0, s26
	s_nop 0
	global_load_lds_dwordx4 v0, s[56:57]
	s_nop 0
	s_mov_b32 m0, s31
	s_nop 0
	global_load_lds_dwordx4 v240, s[56:57]
	s_waitcnt vmcnt(8)
	s_waitcnt lgkmcnt(0)
	s_setprio 1
	s_barrier
	v_mfma_f32_16x16x32_bf16 v[64:67], v[108:111], v[156:159], 0
	v_mfma_f32_16x16x32_bf16 v[64:67], v[120:123], v[160:163], v[64:67]
	v_mfma_f32_16x16x32_bf16 v[60:63], v[132:135], v[160:163], 0
	v_mfma_f32_16x16x32_bf16 v[60:63], v[128:131], v[156:159], v[60:63]
	v_mfma_f32_16x16x32_bf16 v[56:59], v[136:139], v[156:159], 0
	v_mfma_f32_16x16x32_bf16 v[56:59], v[144:147], v[160:163], v[56:59]
	v_mfma_f32_16x16x32_bf16 v[52:55], v[152:155], v[160:163], 0
	v_mfma_f32_16x16x32_bf16 v[52:55], v[148:151], v[156:159], v[52:55]
	v_mfma_f32_16x16x32_bf16 v[36:39], v[148:151], v[164:167], 0
	v_mfma_f32_16x16x32_bf16 v[36:39], v[152:155], v[176:179], v[36:39]
	v_mfma_f32_16x16x32_bf16 v[40:43], v[144:147], v[176:179], 0
	v_mfma_f32_16x16x32_bf16 v[40:43], v[136:139], v[164:167], v[40:43]
	v_mfma_f32_16x16x32_bf16 v[44:47], v[128:131], v[164:167], 0
	v_mfma_f32_16x16x32_bf16 v[44:47], v[132:135], v[176:179], v[44:47]
	v_mfma_f32_16x16x32_bf16 v[48:51], v[120:123], v[176:179], 0
	v_mfma_f32_16x16x32_bf16 v[48:51], v[108:111], v[164:167], v[48:51]
	v_mfma_f32_16x16x32_bf16 v[32:35], v[108:111], v[180:183], 0
	v_mfma_f32_16x16x32_bf16 v[32:35], v[120:123], v[184:187], v[32:35]
	v_mfma_f32_16x16x32_bf16 v[28:31], v[132:135], v[184:187], 0
	v_mfma_f32_16x16x32_bf16 v[28:31], v[128:131], v[180:183], v[28:31]
	v_mfma_f32_16x16x32_bf16 v[24:27], v[136:139], v[180:183], 0
	v_mfma_f32_16x16x32_bf16 v[24:27], v[144:147], v[184:187], v[24:27]
	v_mfma_f32_16x16x32_bf16 v[20:23], v[152:155], v[184:187], 0
	v_mfma_f32_16x16x32_bf16 v[20:23], v[148:151], v[180:183], v[20:23]
	v_mfma_f32_16x16x32_bf16 v[4:7], v[148:151], v[188:191], 0
	v_mfma_f32_16x16x32_bf16 v[4:7], v[152:155], v[202:205], v[4:7]
	v_mfma_f32_16x16x32_bf16 v[8:11], v[144:147], v[202:205], 0
	v_mfma_f32_16x16x32_bf16 v[8:11], v[136:139], v[188:191], v[8:11]
	v_mfma_f32_16x16x32_bf16 v[12:15], v[128:131], v[188:191], 0
	v_mfma_f32_16x16x32_bf16 v[12:15], v[132:135], v[202:205], v[12:15]
	v_mfma_f32_16x16x32_bf16 v[16:19], v[120:123], v[202:205], 0
	v_mfma_f32_16x16x32_bf16 v[16:19], v[108:111], v[188:191], v[16:19]
	s_barrier
; #define PG8_STAGE(bufoff, gbase, voff) do { _Pragma("unroll") for (int _i = 0; _i < 2; ++_i) { \
;         const unsigned _m0 = ldsb + (unsigned)((bufoff) + _i * 8192); const char* _gb = (const char*)(gbase); \
;         asm volatile("s_mov_b32 m0, %0\n\ts_nop 0\n\tglobal_load_lds_dwordx4 %1, %2" :: "s"(_m0), "v"((voff)[_i]), "s"(_gb) : "m0", "memory"); } } while (0)
; #define PG8_LDA(dst, b, h) do { _Pragma("unroll") for (int m = 0; m < 4; ++m) _Pragma("unroll") for (int k = 0; k < 2; ++k) dst[m][k] = *(const LAS bf16x8*)(lds + PG8_SA(b, h) + aoff + m * 2048 + k * 1024); } while (0)
; #define PG8_LDB(dst, b, h) do { _Pragma("unroll") for (int n = 0; n < 2; ++n) _Pragma("unroll") for (int k = 0; k < 2; ++k) dst[n][k] = *(const LAS bf16x8*)(lds + PG8_SB(b, h) + boff + n * 2048 + k * 1024); } while (0)
; #define PG8_MMA(ai, bj, At, Bt) do { __builtin_amdgcn_s_setprio(1); _Pragma("unroll") for (int m = 0; m < 4; ++m) _Pragma("unroll") for (int n = 0; n < 2; ++n) _Pragma("unroll") for (int k = 0; k < 2; ++k) \
;         acc[ai][bj][m][n] = __builtin_amdgcn_mfma_f32_16x16x32_bf16(Bt[n][k], At[m][k], acc[ai][bj][m][n], 0, 0, 0); __builtin_amdgcn_s_setprio(0); } while (0)
; #define PG8_WAIT_V(n) asm volatile("s_waitcnt vmcnt(" #n ")" ::: "memory")
; #define PG8_WAIT_L(n) asm volatile("s_waitcnt lgkmcnt(" #n ")" ::: "memory")
; #define PG8_BAR __builtin_amdgcn_s_barrier()
; #define PG8_SCHED __builtin_amdgcn_sched_barrier(0)
; template <class Epi, bool ALIGN_EPI>
; __device__ __forceinline__ void gemm_phase(LAS unsigned char* lds, const Gemm g, const StaticOrder& S, const Epi& E) {
;     ...
;             PG8_LDA(At, 0, 1); PG8_STAGE(PG8_SB(0, 0), b2, voffB); PG8_STAGE(PG8_SB(0, 1), b2 + hstepB, voffB); PG8_STAGE(PG8_SA(0, 0), a2, voffA);
;             PG8_WAIT_V(8); PG8_WAIT_L(0); PG8_BAR; PG8_MMA(1, 0, At, B0); PG8_MMA(1, 1, At, B1); PG8_BAR; PG8_SCHED;
;             PG8_LDB(B0, 1, 0); PG8_LDB(B1, 1, 1); PG8_SCHED; PG8_LDA(At, 1, 0); PG8_STAGE(PG8_SA(0, 1), a2 + hstepA, voffA);
;             PG8_WAIT_V(8); PG8_WAIT_L(0); PG8_BAR; PG8_MMA(0, 0, At, B0); PG8_MMA(0, 1, At, B1); PG8_BAR; PG8_SCHED;
;             PG8_LDA(At, 1, 1); PG8_STAGE(PG8_SB(1, 0), b3, voffB); PG8_STAGE(PG8_SB(1, 1), b3 + hstepB, voffB); PG8_STAGE(PG8_SA(1, 0), a3, voffA);
;             PG8_WAIT_V(8); PG8_WAIT_L(0); PG8_BAR; PG8_MMA(1, 0, At, B0); PG8_MMA(1, 1, At, B1); PG8_BAR; PG8_SCHED;
	s_setprio 0
	v_add_u32_e32 v132, 0x18000, v244
	v_add_u32_e32 v152, 0x1c000, v244
	ds_read_b128 v[108:111], v132
	ds_read_b128 v[120:123], v132 offset:1024
	ds_read_b128 v[128:131], v132 offset:2048
	ds_read_b128 v[132:135], v132 offset:3072
	ds_read_b128 v[136:139], v152
	ds_read_b128 v[144:147], v152 offset:1024
	ds_read_b128 v[148:151], v152 offset:2048
	ds_read_b128 v[152:155], v152 offset:3072
	ds_read_b128 v[156:159], v245 offset:32768
	ds_read_b128 v[160:163], v245 offset:33792
	ds_read_b128 v[164:167], v245 offset:34816
	ds_read_b128 v[176:179], v245 offset:35840
	ds_read_b128 v[180:183], v245 offset:36864
	ds_read_b128 v[184:187], v245 offset:37888
	ds_read_b128 v[188:191], v245 offset:38912
	ds_read_b128 v[202:205], v245 offset:39936
	s_add_u32 s56, s56, s15
	s_addc_u32 s57, s57, 0
	s_mov_b32 m0, s41
	s_nop 0
	global_load_lds_dwordx4 v0, s[56:57]
	s_nop 0
	s_mov_b32 m0, s42
	s_nop 0
	global_load_lds_dwordx4 v240, s[56:57]
	s_waitcnt vmcnt(8)
	s_waitcnt lgkmcnt(0)
	s_setprio 1
	s_barrier
	v_mfma_f32_16x16x32_bf16 v[172:175], v[108:111], v[156:159], v[172:175]
	v_mfma_f32_16x16x32_bf16 v[172:175], v[120:123], v[160:163], v[172:175]
	v_mfma_f32_16x16x32_bf16 v[168:171], v[132:135], v[160:163], v[168:171]
	v_mfma_f32_16x16x32_bf16 v[168:171], v[128:131], v[156:159], v[168:171]
	v_mfma_f32_16x16x32_bf16 v[140:143], v[136:139], v[156:159], v[140:143]
	v_mfma_f32_16x16x32_bf16 v[140:143], v[144:147], v[160:163], v[140:143]
	v_mfma_f32_16x16x32_bf16 v[124:127], v[152:155], v[160:163], v[124:127]
	v_mfma_f32_16x16x32_bf16 v[124:127], v[148:151], v[156:159], v[124:127]
	v_mfma_f32_16x16x32_bf16 v[100:103], v[148:151], v[164:167], v[100:103]
	v_mfma_f32_16x16x32_bf16 v[100:103], v[152:155], v[176:179], v[100:103]
	v_mfma_f32_16x16x32_bf16 v[104:107], v[144:147], v[176:179], v[104:107]
	v_mfma_f32_16x16x32_bf16 v[104:107], v[136:139], v[164:167], v[104:107]
	v_mfma_f32_16x16x32_bf16 v[112:115], v[128:131], v[164:167], v[112:115]
	v_mfma_f32_16x16x32_bf16 v[112:115], v[132:135], v[176:179], v[112:115]
	v_mfma_f32_16x16x32_bf16 v[116:119], v[120:123], v[176:179], v[116:119]
	v_mfma_f32_16x16x32_bf16 v[116:119], v[108:111], v[164:167], v[116:119]
	v_mfma_f32_16x16x32_bf16 v[96:99], v[108:111], v[180:183], v[96:99]
	v_mfma_f32_16x16x32_bf16 v[96:99], v[120:123], v[184:187], v[96:99]
	v_mfma_f32_16x16x32_bf16 v[92:95], v[132:135], v[184:187], v[92:95]
	v_mfma_f32_16x16x32_bf16 v[92:95], v[128:131], v[180:183], v[92:95]
	v_mfma_f32_16x16x32_bf16 v[88:91], v[136:139], v[180:183], v[88:91]
	v_mfma_f32_16x16x32_bf16 v[88:91], v[144:147], v[184:187], v[88:91]
	v_mfma_f32_16x16x32_bf16 v[84:87], v[152:155], v[184:187], v[84:87]
	v_mfma_f32_16x16x32_bf16 v[84:87], v[148:151], v[180:183], v[84:87]
	v_mfma_f32_16x16x32_bf16 v[68:71], v[148:151], v[188:191], v[68:71]
	v_mfma_f32_16x16x32_bf16 v[68:71], v[152:155], v[202:205], v[68:71]
	v_mfma_f32_16x16x32_bf16 v[72:75], v[144:147], v[202:205], v[72:75]
	v_mfma_f32_16x16x32_bf16 v[72:75], v[136:139], v[188:191], v[72:75]
	v_mfma_f32_16x16x32_bf16 v[76:79], v[128:131], v[188:191], v[76:79]
	v_mfma_f32_16x16x32_bf16 v[76:79], v[132:135], v[202:205], v[76:79]
	v_mfma_f32_16x16x32_bf16 v[80:83], v[120:123], v[202:205], v[80:83]
	v_mfma_f32_16x16x32_bf16 v[80:83], v[108:111], v[188:191], v[80:83]
	s_barrier
	s_setprio 0
	ds_read_b128 v[156:159], v245 offset:49152
	ds_read_b128 v[160:163], v245 offset:50176
	ds_read_b128 v[164:167], v245 offset:51200
	ds_read_b128 v[176:179], v245 offset:52224
	ds_read_b128 v[180:183], v245 offset:53248
	ds_read_b128 v[184:187], v245 offset:54272
	ds_read_b128 v[188:191], v245 offset:55296
	ds_read_b128 v[202:205], v245 offset:56320
	s_add_u32 s54, s54, 0x80
	s_addc_u32 s55, s55, 0
	s_mov_b32 m0, s46
	s_nop 0
	global_load_lds_dwordx4 v195, s[54:55]
	s_nop 0
	s_mov_b32 m0, s50
	s_nop 0
	global_load_lds_dwordx4 v241, s[54:55]
	s_add_u32 s54, s58, 0x80
	s_addc_u32 s55, s59, 0
	s_mov_b32 m0, s61
	s_nop 0
	global_load_lds_dwordx4 v195, s[54:55]
	s_nop 0
	s_mov_b32 m0, s65
	s_nop 0
	global_load_lds_dwordx4 v241, s[54:55]
	s_nop 0
	s_mov_b32 m0, s53
	s_nop 0
	global_load_lds_dwordx4 v0, s[48:49]
	s_nop 0
	s_mov_b32 m0, s60
	s_nop 0
	global_load_lds_dwordx4 v240, s[48:49]
	s_waitcnt vmcnt(8)
	s_waitcnt lgkmcnt(0)
	s_setprio 1
	s_barrier
	v_mfma_f32_16x16x32_bf16 v[64:67], v[108:111], v[156:159], v[64:67]
	v_mfma_f32_16x16x32_bf16 v[64:67], v[120:123], v[160:163], v[64:67]
	v_mfma_f32_16x16x32_bf16 v[60:63], v[132:135], v[160:163], v[60:63]
	v_mfma_f32_16x16x32_bf16 v[60:63], v[128:131], v[156:159], v[60:63]
	v_mfma_f32_16x16x32_bf16 v[56:59], v[136:139], v[156:159], v[56:59]
	v_mfma_f32_16x16x32_bf16 v[56:59], v[144:147], v[160:163], v[56:59]
	v_mfma_f32_16x16x32_bf16 v[52:55], v[152:155], v[160:163], v[52:55]
	v_mfma_f32_16x16x32_bf16 v[52:55], v[148:151], v[156:159], v[52:55]
	v_mfma_f32_16x16x32_bf16 v[36:39], v[148:151], v[164:167], v[36:39]
	v_mfma_f32_16x16x32_bf16 v[36:39], v[152:155], v[176:179], v[36:39]
	v_mfma_f32_16x16x32_bf16 v[40:43], v[144:147], v[176:179], v[40:43]
	v_mfma_f32_16x16x32_bf16 v[40:43], v[136:139], v[164:167], v[40:43]
	v_mfma_f32_16x16x32_bf16 v[44:47], v[128:131], v[164:167], v[44:47]
	v_mfma_f32_16x16x32_bf16 v[44:47], v[132:135], v[176:179], v[44:47]
	v_mfma_f32_16x16x32_bf16 v[48:51], v[120:123], v[176:179], v[48:51]
	v_mfma_f32_16x16x32_bf16 v[48:51], v[108:111], v[164:167], v[48:51]
	v_mfma_f32_16x16x32_bf16 v[32:35], v[108:111], v[180:183], v[32:35]
	v_mfma_f32_16x16x32_bf16 v[32:35], v[120:123], v[184:187], v[32:35]
	v_mfma_f32_16x16x32_bf16 v[28:31], v[132:135], v[184:187], v[28:31]
	v_mfma_f32_16x16x32_bf16 v[28:31], v[128:131], v[180:183], v[28:31]
	v_mfma_f32_16x16x32_bf16 v[24:27], v[136:139], v[180:183], v[24:27]
	v_mfma_f32_16x16x32_bf16 v[24:27], v[144:147], v[184:187], v[24:27]
	v_mfma_f32_16x16x32_bf16 v[20:23], v[152:155], v[184:187], v[20:23]
	v_mfma_f32_16x16x32_bf16 v[20:23], v[148:151], v[180:183], v[20:23]
	v_mfma_f32_16x16x32_bf16 v[4:7], v[148:151], v[188:191], v[4:7]
	v_mfma_f32_16x16x32_bf16 v[4:7], v[152:155], v[202:205], v[4:7]
	v_mfma_f32_16x16x32_bf16 v[8:11], v[144:147], v[202:205], v[8:11]
	v_mfma_f32_16x16x32_bf16 v[8:11], v[136:139], v[188:191], v[8:11]
	v_mfma_f32_16x16x32_bf16 v[12:15], v[128:131], v[188:191], v[12:15]
	v_mfma_f32_16x16x32_bf16 v[12:15], v[132:135], v[202:205], v[12:15]
	v_mfma_f32_16x16x32_bf16 v[16:19], v[120:123], v[202:205], v[16:19]
	v_mfma_f32_16x16x32_bf16 v[16:19], v[108:111], v[188:191], v[16:19]
	s_barrier
	s_setprio 0
	s_add_u32 s4, s4, 0x100
	s_addc_u32 s5, s5, 0
	s_add_u32 s37, s37, 0x100
	s_addc_u32 s44, s44, 0
	s_cmp_ge_u32 s51, s43
	s_mov_b32 s45, s51
; #define PG8_STAGE(bufoff, gbase, voff) do { _Pragma("unroll") for (int _i = 0; _i < 2; ++_i) { \
;         const unsigned _m0 = ldsb + (unsigned)((bufoff) + _i * 8192); const char* _gb = (const char*)(gbase); \
;         asm volatile("s_mov_b32 m0, %0\n\ts_nop 0\n\tglobal_load_lds_dwordx4 %1, %2" :: "s"(_m0), "v"((voff)[_i]), "s"(_gb) : "m0", "memory"); } } while (0)
; #define PG8_LDA(dst, b, h) do { _Pragma("unroll") for (int m = 0; m < 4; ++m) _Pragma("unroll") for (int k = 0; k < 2; ++k) dst[m][k] = *(const LAS bf16x8*)(lds + PG8_SA(b, h) + aoff + m * 2048 + k * 1024); } while (0)
; #define PG8_LDB(dst, b, h) do { _Pragma("unroll") for (int n = 0; n < 2; ++n) _Pragma("unroll") for (int k = 0; k < 2; ++k) dst[n][k] = *(const LAS bf16x8*)(lds + PG8_SB(b, h) + boff + n * 2048 + k * 1024); } while (0)
; #define PG8_MMA(ai, bj, At, Bt) do { __builtin_amdgcn_s_setprio(1); _Pragma("unroll") for (int m = 0; m < 4; ++m) _Pragma("unroll") for (int n = 0; n < 2; ++n) _Pragma("unroll") for (int k = 0; k < 2; ++k) \
;         acc[ai][bj][m][n] = __builtin_amdgcn_mfma_f32_16x16x32_bf16(Bt[n][k], At[m][k], acc[ai][bj][m][n], 0, 0, 0); __builtin_amdgcn_s_setprio(0); } while (0)
; #define PG8_WAIT_V(n) asm volatile("s_waitcnt vmcnt(" #n ")" ::: "memory")
; #define PG8_WAIT_L(n) asm volatile("s_waitcnt lgkmcnt(" #n ")" ::: "memory")
; #define PG8_BAR __builtin_amdgcn_s_barrier()
; #define PG8_SCHED __builtin_amdgcn_sched_barrier(0)
; template <class Epi, bool ALIGN_EPI>
; __device__ __forceinline__ void gemm_phase(LAS unsigned char* lds, const Gemm g, const StaticOrder& S, const Epi& E) {
;     ...
;             PG8_LDB(B0, 0, 0); PG8_LDB(B1, 0, 1); PG8_SCHED; PG8_LDA(At, 0, 0); PG8_STAGE(PG8_SA(1, 1), a1 + hstepA, voffA);
;             PG8_WAIT_V(8); PG8_WAIT_L(0); PG8_BAR; PG8_MMA(0, 0, At, B0); PG8_MMA(0, 1, At, B1); PG8_BAR; PG8_SCHED;
;             PG8_LDA(At, 0, 1); PG8_STAGE(PG8_SB(0, 0), b2, voffB); PG8_STAGE(PG8_SB(0, 1), b2 + hstepB, voffB); PG8_STAGE(PG8_SA(0, 0), a2, voffA);
;             PG8_WAIT_V(8); PG8_WAIT_L(0); PG8_BAR; PG8_MMA(1, 0, At, B0); PG8_MMA(1, 1, At, B1); PG8_BAR; PG8_SCHED;
;             PG8_LDB(B0, 1, 0); PG8_LDB(B1, 1, 1); PG8_SCHED; PG8_LDA(At, 1, 0); PG8_STAGE(PG8_SA(0, 1), a2 + hstepA, voffA);
;             PG8_WAIT_V(8); PG8_WAIT_L(0); PG8_BAR; PG8_MMA(0, 0, At, B0); PG8_MMA(0, 1, At, B1); PG8_BAR; PG8_SCHED;
.LBB0_151:
	v_add_u32_e32 v132, 0x10000, v244
	v_add_u32_e32 v152, 0x14000, v244
	ds_read_b128 v[108:111], v132
	ds_read_b128 v[120:123], v132 offset:1024
	ds_read_b128 v[128:131], v132 offset:2048
	ds_read_b128 v[132:135], v132 offset:3072
	ds_read_b128 v[136:139], v152
	ds_read_b128 v[144:147], v152 offset:1024
	ds_read_b128 v[148:151], v152 offset:2048
	ds_read_b128 v[152:155], v152 offset:3072
	s_add_i32 s51, s45, 2
	s_cmp_eq_u32 s67, s45
	s_cselect_b32 s56, s0, s37
	s_cselect_b32 s57, s1, s44
	s_cselect_b32 s54, s94, s4
	s_cselect_b32 s55, s95, s5
	s_add_u32 s48, s56, 0x80
	s_addc_u32 s49, s57, 0
	ds_read_b128 v[156:159], v245
	ds_read_b128 v[160:163], v245 offset:1024
	ds_read_b128 v[164:167], v245 offset:2048
	ds_read_b128 v[176:179], v245 offset:3072
	ds_read_b128 v[180:183], v245 offset:4096
	ds_read_b128 v[184:187], v245 offset:5120
	ds_read_b128 v[188:191], v245 offset:6144
	ds_read_b128 v[202:205], v245 offset:7168
	s_add_u32 s45, s37, s15
	s_addc_u32 s59, s44, 0
	s_add_u32 s58, s45, 0xffffff80
	s_addc_u32 s59, s59, -1
	s_mov_b32 m0, s68
	s_nop 0
	global_load_lds_dwordx4 v0, s[58:59]
	s_nop 0
	s_mov_b32 m0, s85
	s_nop 0
	global_load_lds_dwordx4 v240, s[58:59]
	s_waitcnt vmcnt(8)
	s_waitcnt lgkmcnt(0)
	s_setprio 1
	s_barrier
	v_mfma_f32_16x16x32_bf16 v[172:175], v[108:111], v[156:159], v[172:175]
	v_mfma_f32_16x16x32_bf16 v[172:175], v[120:123], v[160:163], v[172:175]
	v_mfma_f32_16x16x32_bf16 v[168:171], v[132:135], v[160:163], v[168:171]
	v_mfma_f32_16x16x32_bf16 v[168:171], v[128:131], v[156:159], v[168:171]
	v_mfma_f32_16x16x32_bf16 v[140:143], v[136:139], v[156:159], v[140:143]
	v_mfma_f32_16x16x32_bf16 v[140:143], v[144:147], v[160:163], v[140:143]
	v_mfma_f32_16x16x32_bf16 v[124:127], v[152:155], v[160:163], v[124:127]
	v_mfma_f32_16x16x32_bf16 v[124:127], v[148:151], v[156:159], v[124:127]
	v_mfma_f32_16x16x32_bf16 v[100:103], v[148:151], v[164:167], v[100:103]
	v_mfma_f32_16x16x32_bf16 v[100:103], v[152:155], v[176:179], v[100:103]
	v_mfma_f32_16x16x32_bf16 v[104:107], v[144:147], v[176:179], v[104:107]
	v_mfma_f32_16x16x32_bf16 v[104:107], v[136:139], v[164:167], v[104:107]
	v_mfma_f32_16x16x32_bf16 v[112:115], v[128:131], v[164:167], v[112:115]
	v_mfma_f32_16x16x32_bf16 v[112:115], v[132:135], v[176:179], v[112:115]
	v_mfma_f32_16x16x32_bf16 v[116:119], v[120:123], v[176:179], v[116:119]
	v_mfma_f32_16x16x32_bf16 v[116:119], v[108:111], v[164:167], v[116:119]
	v_mfma_f32_16x16x32_bf16 v[96:99], v[108:111], v[180:183], v[96:99]
	v_mfma_f32_16x16x32_bf16 v[96:99], v[120:123], v[184:187], v[96:99]
	v_mfma_f32_16x16x32_bf16 v[92:95], v[132:135], v[184:187], v[92:95]
	v_mfma_f32_16x16x32_bf16 v[92:95], v[128:131], v[180:183], v[92:95]
	v_mfma_f32_16x16x32_bf16 v[88:91], v[136:139], v[180:183], v[88:91]
	v_mfma_f32_16x16x32_bf16 v[88:91], v[144:147], v[184:187], v[88:91]
	v_mfma_f32_16x16x32_bf16 v[84:87], v[152:155], v[184:187], v[84:87]
	v_mfma_f32_16x16x32_bf16 v[84:87], v[148:151], v[180:183], v[84:87]
	v_mfma_f32_16x16x32_bf16 v[68:71], v[148:151], v[188:191], v[68:71]
	v_mfma_f32_16x16x32_bf16 v[68:71], v[152:155], v[202:205], v[68:71]
	v_mfma_f32_16x16x32_bf16 v[72:75], v[144:147], v[202:205], v[72:75]
	v_mfma_f32_16x16x32_bf16 v[72:75], v[136:139], v[188:191], v[72:75]
	v_mfma_f32_16x16x32_bf16 v[76:79], v[128:131], v[188:191], v[76:79]
	v_mfma_f32_16x16x32_bf16 v[76:79], v[132:135], v[202:205], v[76:79]
	v_mfma_f32_16x16x32_bf16 v[80:83], v[120:123], v[202:205], v[80:83]
	v_mfma_f32_16x16x32_bf16 v[80:83], v[108:111], v[188:191], v[80:83]
	s_barrier
	s_setprio 0
	ds_read_b128 v[156:159], v245 offset:16384
	ds_read_b128 v[160:163], v245 offset:17408
	ds_read_b128 v[164:167], v245 offset:18432
	ds_read_b128 v[176:179], v245 offset:19456
	ds_read_b128 v[180:183], v245 offset:20480
	ds_read_b128 v[184:187], v245 offset:21504
	ds_read_b128 v[188:191], v245 offset:22528
	ds_read_b128 v[202:205], v245 offset:23552
	s_mov_b32 m0, s27
	s_nop 0
	global_load_lds_dwordx4 v195, s[54:55]
	s_add_u32 s58, s54, s15
	s_mov_b32 m0, s28
	s_nop 0
	global_load_lds_dwordx4 v241, s[54:55]
	s_addc_u32 s59, s55, 0
	s_mov_b32 m0, s29
	s_nop 0
	global_load_lds_dwordx4 v195, s[58:59]
	s_nop 0
	s_mov_b32 m0, s30
	s_nop 0
	global_load_lds_dwordx4 v241, s[58:59]
	s_nop 0
	s_mov_b32 m0, s26
	s_nop 0
	global_load_lds_dwordx4 v0, s[56:57]
	s_nop 0
	s_mov_b32 m0, s31
	s_nop 0
	global_load_lds_dwordx4 v240, s[56:57]
	s_waitcnt vmcnt(8)
	s_waitcnt lgkmcnt(0)
	s_setprio 1
	s_barrier
	v_mfma_f32_16x16x32_bf16 v[64:67], v[108:111], v[156:159], v[64:67]
	v_mfma_f32_16x16x32_bf16 v[64:67], v[120:123], v[160:163], v[64:67]
	v_mfma_f32_16x16x32_bf16 v[60:63], v[132:135], v[160:163], v[60:63]
	v_mfma_f32_16x16x32_bf16 v[60:63], v[128:131], v[156:159], v[60:63]
	v_mfma_f32_16x16x32_bf16 v[56:59], v[136:139], v[156:159], v[56:59]
	v_mfma_f32_16x16x32_bf16 v[56:59], v[144:147], v[160:163], v[56:59]
	v_mfma_f32_16x16x32_bf16 v[52:55], v[152:155], v[160:163], v[52:55]
	v_mfma_f32_16x16x32_bf16 v[52:55], v[148:151], v[156:159], v[52:55]
	v_mfma_f32_16x16x32_bf16 v[36:39], v[148:151], v[164:167], v[36:39]
	v_mfma_f32_16x16x32_bf16 v[36:39], v[152:155], v[176:179], v[36:39]
	v_mfma_f32_16x16x32_bf16 v[40:43], v[144:147], v[176:179], v[40:43]
	v_mfma_f32_16x16x32_bf16 v[40:43], v[136:139], v[164:167], v[40:43]
	v_mfma_f32_16x16x32_bf16 v[44:47], v[128:131], v[164:167], v[44:47]
	v_mfma_f32_16x16x32_bf16 v[44:47], v[132:135], v[176:179], v[44:47]
	v_mfma_f32_16x16x32_bf16 v[48:51], v[120:123], v[176:179], v[48:51]
	v_mfma_f32_16x16x32_bf16 v[48:51], v[108:111], v[164:167], v[48:51]
	v_mfma_f32_16x16x32_bf16 v[32:35], v[108:111], v[180:183], v[32:35]
	v_mfma_f32_16x16x32_bf16 v[32:35], v[120:123], v[184:187], v[32:35]
	v_mfma_f32_16x16x32_bf16 v[28:31], v[132:135], v[184:187], v[28:31]
	v_mfma_f32_16x16x32_bf16 v[28:31], v[128:131], v[180:183], v[28:31]
	v_mfma_f32_16x16x32_bf16 v[24:27], v[136:139], v[180:183], v[24:27]
	v_mfma_f32_16x16x32_bf16 v[24:27], v[144:147], v[184:187], v[24:27]
	v_mfma_f32_16x16x32_bf16 v[20:23], v[152:155], v[184:187], v[20:23]
	v_mfma_f32_16x16x32_bf16 v[20:23], v[148:151], v[180:183], v[20:23]
	v_mfma_f32_16x16x32_bf16 v[4:7], v[148:151], v[188:191], v[4:7]
	v_mfma_f32_16x16x32_bf16 v[4:7], v[152:155], v[202:205], v[4:7]
	v_mfma_f32_16x16x32_bf16 v[8:11], v[144:147], v[202:205], v[8:11]
	v_mfma_f32_16x16x32_bf16 v[8:11], v[136:139], v[188:191], v[8:11]
	v_mfma_f32_16x16x32_bf16 v[12:15], v[128:131], v[188:191], v[12:15]
	v_mfma_f32_16x16x32_bf16 v[12:15], v[132:135], v[202:205], v[12:15]
	v_mfma_f32_16x16x32_bf16 v[16:19], v[120:123], v[202:205], v[16:19]
	v_mfma_f32_16x16x32_bf16 v[16:19], v[108:111], v[188:191], v[16:19]
	s_barrier
; #define PG8_STAGE(bufoff, gbase, voff) do { _Pragma("unroll") for (int _i = 0; _i < 2; ++_i) { \
;         const unsigned _m0 = ldsb + (unsigned)((bufoff) + _i * 8192); const char* _gb = (const char*)(gbase); \
;         asm volatile("s_mov_b32 m0, %0\n\ts_nop 0\n\tglobal_load_lds_dwordx4 %1, %2" :: "s"(_m0), "v"((voff)[_i]), "s"(_gb) : "m0", "memory"); } } while (0)
; #define PG8_LDA(dst, b, h) do { _Pragma("unroll") for (int m = 0; m < 4; ++m) _Pragma("unroll") for (int k = 0; k < 2; ++k) dst[m][k] = *(const LAS bf16x8*)(lds + PG8_SA(b, h) + aoff + m * 2048 + k * 1024); } while (0)
; #define PG8_LDB(dst, b, h) do { _Pragma("unroll") for (int n = 0; n < 2; ++n) _Pragma("unroll") for (int k = 0; k < 2; ++k) dst[n][k] = *(const LAS bf16x8*)(lds + PG8_SB(b, h) + boff + n * 2048 + k * 1024); } while (0)
; #define PG8_WAIT_V(n) asm volatile("s_waitcnt vmcnt(" #n ")" ::: "memory")
; #define PG8_WAIT_L(n) asm volatile("s_waitcnt lgkmcnt(" #n ")" ::: "memory")
; #define PG8_BAR __builtin_amdgcn_s_barrier()
; #define PG8_SCHED __builtin_amdgcn_sched_barrier(0)
; template <class Epi, bool ALIGN_EPI>
; __device__ __forceinline__ void gemm_phase(LAS unsigned char* lds, const Gemm g, const StaticOrder& S, const Epi& E) {
;     ...
;             PG8_LDB(B0, 0, 0); PG8_LDB(B1, 0, 1); PG8_SCHED; PG8_LDA(At, 0, 0); PG8_STAGE(PG8_SA(1, 1), a1 + hstepA, voffA);
;             PG8_WAIT_V(8); PG8_WAIT_L(0); PG8_BAR; PG8_MMA(0, 0, At, B0); PG8_MMA(0, 1, At, B1); PG8_BAR; PG8_SCHED;
;             PG8_LDA(At, 0, 1); PG8_STAGE(PG8_SB(0, 0), b2, voffB); PG8_STAGE(PG8_SB(0, 1), b2 + hstepB, voffB); PG8_STAGE(PG8_SA(0, 0), a2, voffA);
;             PG8_WAIT_V(8); PG8_WAIT_L(0); PG8_BAR; PG8_MMA(1, 0, At, B0); PG8_MMA(1, 1, At, B1); PG8_BAR; PG8_SCHED;
;             PG8_LDB(B0, 1, 0); PG8_LDB(B1, 1, 1); PG8_SCHED; PG8_LDA(At, 1, 0); PG8_STAGE(PG8_SA(0, 1), a2 + hstepA, voffA);
;             PG8_WAIT_V(8); PG8_WAIT_L(0); PG8_BAR; PG8_MMA(0, 0, At, B0); PG8_MMA(0, 1, At, B1); PG8_BAR; PG8_SCHED;
;             PG8_LDA(At, 1, 1); PG8_STAGE(PG8_SB(1, 0), b3, voffB); PG8_STAGE(PG8_SB(1, 1), b3 + hstepB, voffB); PG8_STAGE(PG8_SA(1, 0), a3, voffA);
;             PG8_WAIT_V(8); PG8_WAIT_L(0); PG8_BAR; PG8_MMA(1, 0, At, B0); PG8_MMA(1, 1, At, B1); PG8_BAR; PG8_SCHED;
;         }
;         if constexpr (ALIGN_EPI) { if (wr == 0) PG8_BAR; }
	s_setprio 0
	v_add_u32_e32 v132, 0x18000, v244
	v_add_u32_e32 v152, 0x1c000, v244
	ds_read_b128 v[108:111], v132
	ds_read_b128 v[120:123], v132 offset:1024
	ds_read_b128 v[128:131], v132 offset:2048
	ds_read_b128 v[132:135], v132 offset:3072
	ds_read_b128 v[136:139], v152
	ds_read_b128 v[144:147], v152 offset:1024
	ds_read_b128 v[148:151], v152 offset:2048
	ds_read_b128 v[152:155], v152 offset:3072
	ds_read_b128 v[156:159], v245 offset:32768
	ds_read_b128 v[160:163], v245 offset:33792
	ds_read_b128 v[164:167], v245 offset:34816
	ds_read_b128 v[176:179], v245 offset:35840
	ds_read_b128 v[180:183], v245 offset:36864
	ds_read_b128 v[184:187], v245 offset:37888
	ds_read_b128 v[188:191], v245 offset:38912
	ds_read_b128 v[202:205], v245 offset:39936
	s_add_u32 s56, s56, s15
	s_addc_u32 s57, s57, 0
	s_mov_b32 m0, s41
	s_nop 0
	global_load_lds_dwordx4 v0, s[56:57]
	s_nop 0
	s_mov_b32 m0, s42
	s_nop 0
	global_load_lds_dwordx4 v240, s[56:57]
	s_waitcnt vmcnt(8)
	s_waitcnt lgkmcnt(0)
	s_setprio 1
	s_barrier
	v_mfma_f32_16x16x32_bf16 v[172:175], v[108:111], v[156:159], v[172:175]
	v_mfma_f32_16x16x32_bf16 v[172:175], v[120:123], v[160:163], v[172:175]
	v_mfma_f32_16x16x32_bf16 v[168:171], v[132:135], v[160:163], v[168:171]
	v_mfma_f32_16x16x32_bf16 v[168:171], v[128:131], v[156:159], v[168:171]
	v_mfma_f32_16x16x32_bf16 v[140:143], v[136:139], v[156:159], v[140:143]
	v_mfma_f32_16x16x32_bf16 v[140:143], v[144:147], v[160:163], v[140:143]
	v_mfma_f32_16x16x32_bf16 v[124:127], v[152:155], v[160:163], v[124:127]
	v_mfma_f32_16x16x32_bf16 v[124:127], v[148:151], v[156:159], v[124:127]
	v_mfma_f32_16x16x32_bf16 v[100:103], v[148:151], v[164:167], v[100:103]
	v_mfma_f32_16x16x32_bf16 v[100:103], v[152:155], v[176:179], v[100:103]
	v_mfma_f32_16x16x32_bf16 v[104:107], v[144:147], v[176:179], v[104:107]
	v_mfma_f32_16x16x32_bf16 v[104:107], v[136:139], v[164:167], v[104:107]
	v_mfma_f32_16x16x32_bf16 v[112:115], v[128:131], v[164:167], v[112:115]
	v_mfma_f32_16x16x32_bf16 v[112:115], v[132:135], v[176:179], v[112:115]
	v_mfma_f32_16x16x32_bf16 v[116:119], v[120:123], v[176:179], v[116:119]
	v_mfma_f32_16x16x32_bf16 v[116:119], v[108:111], v[164:167], v[116:119]
	v_mfma_f32_16x16x32_bf16 v[96:99], v[108:111], v[180:183], v[96:99]
	v_mfma_f32_16x16x32_bf16 v[96:99], v[120:123], v[184:187], v[96:99]
	v_mfma_f32_16x16x32_bf16 v[92:95], v[132:135], v[184:187], v[92:95]
	v_mfma_f32_16x16x32_bf16 v[92:95], v[128:131], v[180:183], v[92:95]
	v_mfma_f32_16x16x32_bf16 v[88:91], v[136:139], v[180:183], v[88:91]
	v_mfma_f32_16x16x32_bf16 v[88:91], v[144:147], v[184:187], v[88:91]
	v_mfma_f32_16x16x32_bf16 v[84:87], v[152:155], v[184:187], v[84:87]
	v_mfma_f32_16x16x32_bf16 v[84:87], v[148:151], v[180:183], v[84:87]
	v_mfma_f32_16x16x32_bf16 v[68:71], v[148:151], v[188:191], v[68:71]
	v_mfma_f32_16x16x32_bf16 v[68:71], v[152:155], v[202:205], v[68:71]
	v_mfma_f32_16x16x32_bf16 v[72:75], v[144:147], v[202:205], v[72:75]
	v_mfma_f32_16x16x32_bf16 v[72:75], v[136:139], v[188:191], v[72:75]
	v_mfma_f32_16x16x32_bf16 v[76:79], v[128:131], v[188:191], v[76:79]
	v_mfma_f32_16x16x32_bf16 v[76:79], v[132:135], v[202:205], v[76:79]
	v_mfma_f32_16x16x32_bf16 v[80:83], v[120:123], v[202:205], v[80:83]
	v_mfma_f32_16x16x32_bf16 v[80:83], v[108:111], v[188:191], v[80:83]
	s_barrier
	s_setprio 0
	ds_read_b128 v[156:159], v245 offset:49152
	ds_read_b128 v[160:163], v245 offset:50176
	ds_read_b128 v[164:167], v245 offset:51200
	ds_read_b128 v[176:179], v245 offset:52224
	ds_read_b128 v[180:183], v245 offset:53248
	ds_read_b128 v[184:187], v245 offset:54272
	ds_read_b128 v[188:191], v245 offset:55296
	ds_read_b128 v[202:205], v245 offset:56320
	s_add_u32 s54, s54, 0x80
	s_addc_u32 s55, s55, 0
	s_mov_b32 m0, s46
	s_nop 0
	global_load_lds_dwordx4 v195, s[54:55]
	s_nop 0
	s_mov_b32 m0, s50
	s_nop 0
	global_load_lds_dwordx4 v241, s[54:55]
	s_add_u32 s54, s58, 0x80
	s_addc_u32 s55, s59, 0
	s_mov_b32 m0, s61
	s_nop 0
	global_load_lds_dwordx4 v195, s[54:55]
	s_nop 0
	s_mov_b32 m0, s65
	s_nop 0
	global_load_lds_dwordx4 v241, s[54:55]
	s_nop 0
	s_mov_b32 m0, s53
	s_nop 0
	global_load_lds_dwordx4 v0, s[48:49]
	s_nop 0
	s_mov_b32 m0, s60
	s_nop 0
	global_load_lds_dwordx4 v240, s[48:49]
	s_waitcnt vmcnt(8)
	s_waitcnt lgkmcnt(0)
	s_setprio 1
	s_barrier
	v_mfma_f32_16x16x32_bf16 v[64:67], v[108:111], v[156:159], v[64:67]
	v_mfma_f32_16x16x32_bf16 v[64:67], v[120:123], v[160:163], v[64:67]
	v_mfma_f32_16x16x32_bf16 v[60:63], v[132:135], v[160:163], v[60:63]
	v_mfma_f32_16x16x32_bf16 v[60:63], v[128:131], v[156:159], v[60:63]
	v_mfma_f32_16x16x32_bf16 v[56:59], v[136:139], v[156:159], v[56:59]
	v_mfma_f32_16x16x32_bf16 v[56:59], v[144:147], v[160:163], v[56:59]
	v_mfma_f32_16x16x32_bf16 v[52:55], v[152:155], v[160:163], v[52:55]
	v_mfma_f32_16x16x32_bf16 v[52:55], v[148:151], v[156:159], v[52:55]
	v_mfma_f32_16x16x32_bf16 v[36:39], v[148:151], v[164:167], v[36:39]
	v_mfma_f32_16x16x32_bf16 v[36:39], v[152:155], v[176:179], v[36:39]
	v_mfma_f32_16x16x32_bf16 v[40:43], v[144:147], v[176:179], v[40:43]
	v_mfma_f32_16x16x32_bf16 v[40:43], v[136:139], v[164:167], v[40:43]
	v_mfma_f32_16x16x32_bf16 v[44:47], v[128:131], v[164:167], v[44:47]
	v_mfma_f32_16x16x32_bf16 v[44:47], v[132:135], v[176:179], v[44:47]
	v_mfma_f32_16x16x32_bf16 v[48:51], v[120:123], v[176:179], v[48:51]
	v_mfma_f32_16x16x32_bf16 v[48:51], v[108:111], v[164:167], v[48:51]
	v_mfma_f32_16x16x32_bf16 v[32:35], v[108:111], v[180:183], v[32:35]
	v_mfma_f32_16x16x32_bf16 v[32:35], v[120:123], v[184:187], v[32:35]
	v_mfma_f32_16x16x32_bf16 v[28:31], v[132:135], v[184:187], v[28:31]
	v_mfma_f32_16x16x32_bf16 v[28:31], v[128:131], v[180:183], v[28:31]
	v_mfma_f32_16x16x32_bf16 v[24:27], v[136:139], v[180:183], v[24:27]
	v_mfma_f32_16x16x32_bf16 v[24:27], v[144:147], v[184:187], v[24:27]
	v_mfma_f32_16x16x32_bf16 v[20:23], v[152:155], v[184:187], v[20:23]
	v_mfma_f32_16x16x32_bf16 v[20:23], v[148:151], v[180:183], v[20:23]
	v_mfma_f32_16x16x32_bf16 v[4:7], v[148:151], v[188:191], v[4:7]
	v_mfma_f32_16x16x32_bf16 v[4:7], v[152:155], v[202:205], v[4:7]
	v_mfma_f32_16x16x32_bf16 v[8:11], v[144:147], v[202:205], v[8:11]
	v_mfma_f32_16x16x32_bf16 v[8:11], v[136:139], v[188:191], v[8:11]
	v_mfma_f32_16x16x32_bf16 v[12:15], v[128:131], v[188:191], v[12:15]
	v_mfma_f32_16x16x32_bf16 v[12:15], v[132:135], v[202:205], v[12:15]
	v_mfma_f32_16x16x32_bf16 v[16:19], v[120:123], v[202:205], v[16:19]
	v_mfma_f32_16x16x32_bf16 v[16:19], v[108:111], v[188:191], v[16:19]
	s_barrier
	s_setprio 0
	s_add_u32 s4, s4, 0x100
	s_addc_u32 s5, s5, 0
	s_add_u32 s37, s37, 0x100
	s_addc_u32 s44, s44, 0
	s_cmp_ge_u32 s51, s43
	s_mov_b32 s45, s51
	s_cbranch_scc0 .LBB0_151
	s_and_b64 vcc, exec, s[92:93]
	s_cbranch_vccz .LBB0_154
	s_barrier

; #define PG8_STAGE(bufoff, gbase, voff) do { _Pragma("unroll") for (int _i = 0; _i < 2; ++_i) { \
;         const unsigned _m0 = ldsb + (unsigned)((bufoff) + _i * 8192); const char* _gb = (const char*)(gbase); \
;         asm volatile("s_mov_b32 m0, %0\n\ts_nop 0\n\tglobal_load_lds_dwordx4 %1, %2" :: "s"(_m0), "v"((voff)[_i]), "s"(_gb) : "m0", "memory"); } } while (0)
; #define PG8_LDA(dst, b, h) do { _Pragma("unroll") for (int m = 0; m < 4; ++m) _Pragma("unroll") for (int k = 0; k < 2; ++k) dst[m][k] = *(const LAS bf16x8*)(lds + PG8_SA(b, h) + aoff + m * 2048 + k * 1024); } while (0)
; #define PG8_LDB(dst, b, h) do { _Pragma("unroll") for (int n = 0; n < 2; ++n) _Pragma("unroll") for (int k = 0; k < 2; ++k) dst[n][k] = *(const LAS bf16x8*)(lds + PG8_SB(b, h) + boff + n * 2048 + k * 1024); } while (0)
; #define PG8_WAIT_V(n) asm volatile("s_waitcnt vmcnt(" #n ")" ::: "memory")
; #define PG8_WAIT_L(n) asm volatile("s_waitcnt lgkmcnt(" #n ")" ::: "memory")
; #define PG8_BAR __builtin_amdgcn_s_barrier()
; #define PG8_SCHED __builtin_amdgcn_sched_barrier(0)
; template <class Epi, bool ALIGN_EPI>
; __device__ __forceinline__ void gemm_phase(LAS unsigned char* lds, const Gemm g, const StaticOrder& S, const Epi& E) {
;     ...
;         const bool has_next = S.next(ui + 1, nxt);
;         const char* nA = has_next ? (const char*)g.A + (size_t)nxt.pm * tstepA + (size_t)nxt.pn * g.a_pn_off * 2 + (size_t)(nxt.pm >> 4) * g.a_adj : cA; const char* nB = has_next ? (const char*)g.Bt + (size_t)nxt.pn * tstepB : cB;
;         for (int t = 0; t < nt; t += 2) {
;             const bool last = (t == nt - 2);
;             const char* a1 = cA + (size_t)(t + 1) * kstep;
;             const char* a2 = last ? nA : cA + (size_t)(t + 2) * kstep; const char* b2 = last ? nB : cB + (size_t)(t + 2) * kstep;
;             const char* a3 = a2 + kstep; const char* b3 = b2 + kstep;
;             PG8_LDB(B0, 0, 0); PG8_LDB(B1, 0, 1); PG8_SCHED; PG8_LDA(At, 0, 0); PG8_STAGE(PG8_SA(1, 1), a1 + hstepA, voffA);
;             PG8_WAIT_V(8); PG8_WAIT_L(0); PG8_BAR; PG8_MMA(0, 0, At, B0); PG8_MMA(0, 1, At, B1); PG8_BAR; PG8_SCHED;
;             PG8_LDA(At, 0, 1); PG8_STAGE(PG8_SB(0, 0), b2, voffB); PG8_STAGE(PG8_SB(0, 1), b2 + hstepB, voffB); PG8_STAGE(PG8_SA(0, 0), a2, voffA);
;             PG8_WAIT_V(8); PG8_WAIT_L(0); PG8_BAR; PG8_MMA(1, 0, At, B0); PG8_MMA(1, 1, At, B1); PG8_BAR; PG8_SCHED;
.LBB0_200:
	s_add_u32 s4, s48, 0x100
	s_addc_u32 s5, s49, 0
	s_add_u32 s15, s54, 0x100
	s_addc_u32 s42, s55, 0
	s_mov_b32 s43, 0
	s_add_i32 s44, s43, 2
	s_cmp_eq_u32 s68, s43
	s_cselect_b32 s56, s0, s15
	s_cselect_b32 s57, s1, s42
	s_cselect_b32 s54, s94, s4
	s_cselect_b32 s55, s95, s5
	s_add_u32 s48, s56, 0x80
	s_addc_u32 s49, s57, 0
	s_add_u32 s43, s15, s38
	s_addc_u32 s45, s42, 0
	s_add_u32 s58, s43, 0xffffff80
	s_addc_u32 s59, s45, -1
	s_mov_b32 m0, s37
	s_nop 0
	global_load_lds_dwordx4 v0, s[58:59]
	s_nop 0
	s_mov_b32 m0, s41
	s_nop 0
	global_load_lds_dwordx4 v206, s[58:59]
	s_waitcnt vmcnt(8)
	s_waitcnt lgkmcnt(0)
	s_setprio 1
	s_barrier
	v_mfma_f32_16x16x32_bf16 v[126:129], v[130:133], v[162:165], 0
	v_mfma_f32_16x16x32_bf16 v[126:129], v[134:137], v[166:169], v[126:129]
	v_mfma_f32_16x16x32_bf16 v[122:125], v[142:145], v[166:169], 0
	v_mfma_f32_16x16x32_bf16 v[122:125], v[138:141], v[162:165], v[122:125]
	v_mfma_f32_16x16x32_bf16 v[118:121], v[146:149], v[162:165], 0
	v_mfma_f32_16x16x32_bf16 v[118:121], v[150:153], v[166:169], v[118:121]
	v_mfma_f32_16x16x32_bf16 v[114:117], v[158:161], v[166:169], 0
	v_mfma_f32_16x16x32_bf16 v[114:117], v[154:157], v[162:165], v[114:117]
	v_mfma_f32_16x16x32_bf16 v[98:101], v[154:157], v[170:173], 0
	v_mfma_f32_16x16x32_bf16 v[98:101], v[158:161], v[174:177], v[98:101]
	v_mfma_f32_16x16x32_bf16 v[102:105], v[150:153], v[174:177], 0
	v_mfma_f32_16x16x32_bf16 v[102:105], v[146:149], v[170:173], v[102:105]
	v_mfma_f32_16x16x32_bf16 v[106:109], v[138:141], v[170:173], 0
	v_mfma_f32_16x16x32_bf16 v[106:109], v[142:145], v[174:177], v[106:109]
	v_mfma_f32_16x16x32_bf16 v[110:113], v[134:137], v[174:177], 0
	v_mfma_f32_16x16x32_bf16 v[110:113], v[130:133], v[170:173], v[110:113]
	v_mfma_f32_16x16x32_bf16 v[94:97], v[130:133], v[178:181], 0
	v_mfma_f32_16x16x32_bf16 v[94:97], v[134:137], v[182:185], v[94:97]
	v_mfma_f32_16x16x32_bf16 v[90:93], v[142:145], v[182:185], 0
	v_mfma_f32_16x16x32_bf16 v[90:93], v[138:141], v[178:181], v[90:93]
	v_mfma_f32_16x16x32_bf16 v[86:89], v[146:149], v[178:181], 0
	v_mfma_f32_16x16x32_bf16 v[86:89], v[150:153], v[182:185], v[86:89]
	v_mfma_f32_16x16x32_bf16 v[82:85], v[158:161], v[182:185], 0
	v_mfma_f32_16x16x32_bf16 v[82:85], v[154:157], v[178:181], v[82:85]
	v_mfma_f32_16x16x32_bf16 v[66:69], v[154:157], v[186:189], 0
	v_mfma_f32_16x16x32_bf16 v[66:69], v[158:161], v[190:193], v[66:69]
	v_mfma_f32_16x16x32_bf16 v[70:73], v[150:153], v[190:193], 0
	v_mfma_f32_16x16x32_bf16 v[70:73], v[146:149], v[186:189], v[70:73]
	v_mfma_f32_16x16x32_bf16 v[74:77], v[138:141], v[186:189], 0
	v_mfma_f32_16x16x32_bf16 v[74:77], v[142:145], v[190:193], v[74:77]
	v_mfma_f32_16x16x32_bf16 v[78:81], v[134:137], v[190:193], 0
	v_mfma_f32_16x16x32_bf16 v[78:81], v[130:133], v[186:189], v[78:81]
	s_barrier
	s_setprio 0
	ds_read_b128 v[162:165], v246 offset:16384
	ds_read_b128 v[166:169], v246 offset:17408
	ds_read_b128 v[170:173], v246 offset:18432
	ds_read_b128 v[174:177], v246 offset:19456
	ds_read_b128 v[178:181], v246 offset:20480
	ds_read_b128 v[182:185], v246 offset:21504
	ds_read_b128 v[186:189], v246 offset:22528
	ds_read_b128 v[190:193], v246 offset:23552
	s_mov_b32 m0, s46
	s_nop 0
	global_load_lds_dwordx4 v195, s[54:55]
	s_add_u32 s58, s54, s38
	s_mov_b32 m0, s26
	s_nop 0
	global_load_lds_dwordx4 v207, s[54:55]
	s_addc_u32 s59, s55, 0
	s_mov_b32 m0, s27
	s_nop 0
	global_load_lds_dwordx4 v195, s[58:59]
	s_nop 0
	s_mov_b32 m0, s30
	s_nop 0
	global_load_lds_dwordx4 v207, s[58:59]
	s_nop 0
	s_mov_b32 m0, s29
	s_nop 0
	global_load_lds_dwordx4 v0, s[56:57]
	s_nop 0
	s_mov_b32 m0, s17
	s_nop 0
	global_load_lds_dwordx4 v206, s[56:57]
	s_waitcnt vmcnt(8)
	s_waitcnt lgkmcnt(0)
	s_setprio 1
	s_barrier
	v_mfma_f32_16x16x32_bf16 v[62:65], v[130:133], v[162:165], 0
	v_mfma_f32_16x16x32_bf16 v[62:65], v[134:137], v[166:169], v[62:65]
	v_mfma_f32_16x16x32_bf16 v[58:61], v[142:145], v[166:169], 0
	v_mfma_f32_16x16x32_bf16 v[58:61], v[138:141], v[162:165], v[58:61]
	v_mfma_f32_16x16x32_bf16 v[54:57], v[146:149], v[162:165], 0
	v_mfma_f32_16x16x32_bf16 v[54:57], v[150:153], v[166:169], v[54:57]
	v_mfma_f32_16x16x32_bf16 v[50:53], v[158:161], v[166:169], 0
	v_mfma_f32_16x16x32_bf16 v[50:53], v[154:157], v[162:165], v[50:53]
	v_mfma_f32_16x16x32_bf16 v[34:37], v[154:157], v[170:173], 0
	v_mfma_f32_16x16x32_bf16 v[34:37], v[158:161], v[174:177], v[34:37]
	v_mfma_f32_16x16x32_bf16 v[38:41], v[150:153], v[174:177], 0
	v_mfma_f32_16x16x32_bf16 v[38:41], v[146:149], v[170:173], v[38:41]
	v_mfma_f32_16x16x32_bf16 v[42:45], v[138:141], v[170:173], 0
	v_mfma_f32_16x16x32_bf16 v[42:45], v[142:145], v[174:177], v[42:45]
	v_mfma_f32_16x16x32_bf16 v[46:49], v[134:137], v[174:177], 0
	v_mfma_f32_16x16x32_bf16 v[46:49], v[130:133], v[170:173], v[46:49]
	v_mfma_f32_16x16x32_bf16 v[30:33], v[130:133], v[178:181], 0
	v_mfma_f32_16x16x32_bf16 v[30:33], v[134:137], v[182:185], v[30:33]
	v_mfma_f32_16x16x32_bf16 v[26:29], v[142:145], v[182:185], 0
	v_mfma_f32_16x16x32_bf16 v[26:29], v[138:141], v[178:181], v[26:29]
	v_mfma_f32_16x16x32_bf16 v[22:25], v[146:149], v[178:181], 0
	v_mfma_f32_16x16x32_bf16 v[22:25], v[150:153], v[182:185], v[22:25]
	v_mfma_f32_16x16x32_bf16 v[18:21], v[158:161], v[182:185], 0
	v_mfma_f32_16x16x32_bf16 v[18:21], v[154:157], v[178:181], v[18:21]
	v_mfma_f32_16x16x32_bf16 v[2:5], v[154:157], v[186:189], 0
	v_mfma_f32_16x16x32_bf16 v[2:5], v[158:161], v[190:193], v[2:5]
	v_mfma_f32_16x16x32_bf16 v[6:9], v[150:153], v[190:193], 0
	v_mfma_f32_16x16x32_bf16 v[6:9], v[146:149], v[186:189], v[6:9]
	v_mfma_f32_16x16x32_bf16 v[10:13], v[138:141], v[186:189], 0
	v_mfma_f32_16x16x32_bf16 v[10:13], v[142:145], v[190:193], v[10:13]
	v_mfma_f32_16x16x32_bf16 v[14:17], v[134:137], v[190:193], 0
	v_mfma_f32_16x16x32_bf16 v[14:17], v[130:133], v[186:189], v[14:17]
	s_barrier
; #define PG8_STAGE(bufoff, gbase, voff) do { _Pragma("unroll") for (int _i = 0; _i < 2; ++_i) { \
;         const unsigned _m0 = ldsb + (unsigned)((bufoff) + _i * 8192); const char* _gb = (const char*)(gbase); \
;         asm volatile("s_mov_b32 m0, %0\n\ts_nop 0\n\tglobal_load_lds_dwordx4 %1, %2" :: "s"(_m0), "v"((voff)[_i]), "s"(_gb) : "m0", "memory"); } } while (0)
; #define PG8_LDA(dst, b, h) do { _Pragma("unroll") for (int m = 0; m < 4; ++m) _Pragma("unroll") for (int k = 0; k < 2; ++k) dst[m][k] = *(const LAS bf16x8*)(lds + PG8_SA(b, h) + aoff + m * 2048 + k * 1024); } while (0)
; #define PG8_LDB(dst, b, h) do { _Pragma("unroll") for (int n = 0; n < 2; ++n) _Pragma("unroll") for (int k = 0; k < 2; ++k) dst[n][k] = *(const LAS bf16x8*)(lds + PG8_SB(b, h) + boff + n * 2048 + k * 1024); } while (0)
; #define PG8_MMA(ai, bj, At, Bt) do { __builtin_amdgcn_s_setprio(1); _Pragma("unroll") for (int m = 0; m < 4; ++m) _Pragma("unroll") for (int n = 0; n < 2; ++n) _Pragma("unroll") for (int k = 0; k < 2; ++k) \
;         acc[ai][bj][m][n] = __builtin_amdgcn_mfma_f32_16x16x32_bf16(Bt[n][k], At[m][k], acc[ai][bj][m][n], 0, 0, 0); __builtin_amdgcn_s_setprio(0); } while (0)
; #define PG8_WAIT_V(n) asm volatile("s_waitcnt vmcnt(" #n ")" ::: "memory")
; #define PG8_WAIT_L(n) asm volatile("s_waitcnt lgkmcnt(" #n ")" ::: "memory")
; #define PG8_BAR __builtin_amdgcn_s_barrier()
; #define PG8_SCHED __builtin_amdgcn_sched_barrier(0)
; template <class Epi, bool ALIGN_EPI>
; __device__ __forceinline__ void gemm_phase(LAS unsigned char* lds, const Gemm g, const StaticOrder& S, const Epi& E) {
;     ...
;             PG8_LDB(B0, 1, 0); PG8_LDB(B1, 1, 1); PG8_SCHED; PG8_LDA(At, 1, 0); PG8_STAGE(PG8_SA(0, 1), a2 + hstepA, voffA);
;             PG8_WAIT_V(8); PG8_WAIT_L(0); PG8_BAR; PG8_MMA(0, 0, At, B0); PG8_MMA(0, 1, At, B1); PG8_BAR; PG8_SCHED;
;             PG8_LDA(At, 1, 1); PG8_STAGE(PG8_SB(1, 0), b3, voffB); PG8_STAGE(PG8_SB(1, 1), b3 + hstepB, voffB); PG8_STAGE(PG8_SA(1, 0), a3, voffA);
;             PG8_WAIT_V(8); PG8_WAIT_L(0); PG8_BAR; PG8_MMA(1, 0, At, B0); PG8_MMA(1, 1, At, B1); PG8_BAR; PG8_SCHED;
;         }
	s_setprio 0
	v_add_u32_e32 v142, 0x18000, v245
	v_add_u32_e32 v158, 0x1c000, v245
	ds_read_b128 v[130:133], v142
	ds_read_b128 v[134:137], v142 offset:1024
	ds_read_b128 v[138:141], v142 offset:2048
	ds_read_b128 v[142:145], v142 offset:3072
	ds_read_b128 v[146:149], v158
	ds_read_b128 v[150:153], v158 offset:1024
	ds_read_b128 v[154:157], v158 offset:2048
	ds_read_b128 v[158:161], v158 offset:3072
	ds_read_b128 v[162:165], v246 offset:32768
	ds_read_b128 v[166:169], v246 offset:33792
	ds_read_b128 v[170:173], v246 offset:34816
	ds_read_b128 v[174:177], v246 offset:35840
	ds_read_b128 v[178:181], v246 offset:36864
	ds_read_b128 v[182:185], v246 offset:37888
	ds_read_b128 v[186:189], v246 offset:38912
	ds_read_b128 v[190:193], v246 offset:39936
	s_add_u32 s56, s56, s38
	s_addc_u32 s57, s57, 0
	s_mov_b32 m0, s31
	s_nop 0
	global_load_lds_dwordx4 v0, s[56:57]
	s_nop 0
	s_mov_b32 m0, s53
	s_nop 0
	global_load_lds_dwordx4 v206, s[56:57]
	s_waitcnt vmcnt(8)
	s_waitcnt lgkmcnt(0)
	s_setprio 1
	s_barrier
	v_mfma_f32_16x16x32_bf16 v[126:129], v[130:133], v[162:165], v[126:129]
	v_mfma_f32_16x16x32_bf16 v[126:129], v[134:137], v[166:169], v[126:129]
	v_mfma_f32_16x16x32_bf16 v[122:125], v[142:145], v[166:169], v[122:125]
	v_mfma_f32_16x16x32_bf16 v[122:125], v[138:141], v[162:165], v[122:125]
	v_mfma_f32_16x16x32_bf16 v[118:121], v[146:149], v[162:165], v[118:121]
	v_mfma_f32_16x16x32_bf16 v[118:121], v[150:153], v[166:169], v[118:121]
	v_mfma_f32_16x16x32_bf16 v[114:117], v[158:161], v[166:169], v[114:117]
	v_mfma_f32_16x16x32_bf16 v[114:117], v[154:157], v[162:165], v[114:117]
	v_mfma_f32_16x16x32_bf16 v[98:101], v[154:157], v[170:173], v[98:101]
	v_mfma_f32_16x16x32_bf16 v[98:101], v[158:161], v[174:177], v[98:101]
	v_mfma_f32_16x16x32_bf16 v[102:105], v[150:153], v[174:177], v[102:105]
	v_mfma_f32_16x16x32_bf16 v[102:105], v[146:149], v[170:173], v[102:105]
	v_mfma_f32_16x16x32_bf16 v[106:109], v[138:141], v[170:173], v[106:109]
	v_mfma_f32_16x16x32_bf16 v[106:109], v[142:145], v[174:177], v[106:109]
	v_mfma_f32_16x16x32_bf16 v[110:113], v[134:137], v[174:177], v[110:113]
	v_mfma_f32_16x16x32_bf16 v[110:113], v[130:133], v[170:173], v[110:113]
	v_mfma_f32_16x16x32_bf16 v[94:97], v[130:133], v[178:181], v[94:97]
	v_mfma_f32_16x16x32_bf16 v[94:97], v[134:137], v[182:185], v[94:97]
	v_mfma_f32_16x16x32_bf16 v[90:93], v[142:145], v[182:185], v[90:93]
	v_mfma_f32_16x16x32_bf16 v[90:93], v[138:141], v[178:181], v[90:93]
	v_mfma_f32_16x16x32_bf16 v[86:89], v[146:149], v[178:181], v[86:89]
	v_mfma_f32_16x16x32_bf16 v[86:89], v[150:153], v[182:185], v[86:89]
	v_mfma_f32_16x16x32_bf16 v[82:85], v[158:161], v[182:185], v[82:85]
	v_mfma_f32_16x16x32_bf16 v[82:85], v[154:157], v[178:181], v[82:85]
	v_mfma_f32_16x16x32_bf16 v[66:69], v[154:157], v[186:189], v[66:69]
	v_mfma_f32_16x16x32_bf16 v[66:69], v[158:161], v[190:193], v[66:69]
	v_mfma_f32_16x16x32_bf16 v[70:73], v[150:153], v[190:193], v[70:73]
	v_mfma_f32_16x16x32_bf16 v[70:73], v[146:149], v[186:189], v[70:73]
	v_mfma_f32_16x16x32_bf16 v[74:77], v[138:141], v[186:189], v[74:77]
	v_mfma_f32_16x16x32_bf16 v[74:77], v[142:145], v[190:193], v[74:77]
	v_mfma_f32_16x16x32_bf16 v[78:81], v[134:137], v[190:193], v[78:81]
	v_mfma_f32_16x16x32_bf16 v[78:81], v[130:133], v[186:189], v[78:81]
	s_barrier
	s_setprio 0
	ds_read_b128 v[162:165], v246 offset:49152
	ds_read_b128 v[166:169], v246 offset:50176
	ds_read_b128 v[170:173], v246 offset:51200
	ds_read_b128 v[174:177], v246 offset:52224
	ds_read_b128 v[178:181], v246 offset:53248
	ds_read_b128 v[182:185], v246 offset:54272
	ds_read_b128 v[186:189], v246 offset:55296
	ds_read_b128 v[190:193], v246 offset:56320
	s_add_u32 s54, s54, 0x80
	s_addc_u32 s55, s55, 0
	s_mov_b32 m0, s85
	s_nop 0
	global_load_lds_dwordx4 v195, s[54:55]
	s_nop 0
	s_mov_b32 m0, s65
	s_nop 0
	global_load_lds_dwordx4 v207, s[54:55]
	s_add_u32 s54, s58, 0x80
	s_addc_u32 s55, s59, 0
	s_mov_b32 m0, s93
	s_nop 0
	global_load_lds_dwordx4 v195, s[54:55]
	s_nop 0
	s_mov_b32 m0, s28
	s_nop 0
	global_load_lds_dwordx4 v207, s[54:55]
	s_nop 0
	s_mov_b32 m0, s67
	s_nop 0
	global_load_lds_dwordx4 v0, s[48:49]
	s_nop 0
	s_mov_b32 m0, s92
	s_nop 0
	global_load_lds_dwordx4 v206, s[48:49]
	s_waitcnt vmcnt(8)
	s_waitcnt lgkmcnt(0)
	s_setprio 1
	s_barrier
	v_mfma_f32_16x16x32_bf16 v[62:65], v[130:133], v[162:165], v[62:65]
	v_mfma_f32_16x16x32_bf16 v[62:65], v[134:137], v[166:169], v[62:65]
	v_mfma_f32_16x16x32_bf16 v[58:61], v[142:145], v[166:169], v[58:61]
	v_mfma_f32_16x16x32_bf16 v[58:61], v[138:141], v[162:165], v[58:61]
	v_mfma_f32_16x16x32_bf16 v[54:57], v[146:149], v[162:165], v[54:57]
	v_mfma_f32_16x16x32_bf16 v[54:57], v[150:153], v[166:169], v[54:57]
	v_mfma_f32_16x16x32_bf16 v[50:53], v[158:161], v[166:169], v[50:53]
	v_mfma_f32_16x16x32_bf16 v[50:53], v[154:157], v[162:165], v[50:53]
	v_mfma_f32_16x16x32_bf16 v[34:37], v[154:157], v[170:173], v[34:37]
	v_mfma_f32_16x16x32_bf16 v[34:37], v[158:161], v[174:177], v[34:37]
	v_mfma_f32_16x16x32_bf16 v[38:41], v[150:153], v[174:177], v[38:41]
	v_mfma_f32_16x16x32_bf16 v[38:41], v[146:149], v[170:173], v[38:41]
	v_mfma_f32_16x16x32_bf16 v[42:45], v[138:141], v[170:173], v[42:45]
	v_mfma_f32_16x16x32_bf16 v[42:45], v[142:145], v[174:177], v[42:45]
	v_mfma_f32_16x16x32_bf16 v[46:49], v[134:137], v[174:177], v[46:49]
	v_mfma_f32_16x16x32_bf16 v[46:49], v[130:133], v[170:173], v[46:49]
	v_mfma_f32_16x16x32_bf16 v[30:33], v[130:133], v[178:181], v[30:33]
	v_mfma_f32_16x16x32_bf16 v[30:33], v[134:137], v[182:185], v[30:33]
	v_mfma_f32_16x16x32_bf16 v[26:29], v[142:145], v[182:185], v[26:29]
	v_mfma_f32_16x16x32_bf16 v[26:29], v[138:141], v[178:181], v[26:29]
	v_mfma_f32_16x16x32_bf16 v[22:25], v[146:149], v[178:181], v[22:25]
	v_mfma_f32_16x16x32_bf16 v[22:25], v[150:153], v[182:185], v[22:25]
	v_mfma_f32_16x16x32_bf16 v[18:21], v[158:161], v[182:185], v[18:21]
	v_mfma_f32_16x16x32_bf16 v[18:21], v[154:157], v[178:181], v[18:21]
	v_mfma_f32_16x16x32_bf16 v[2:5], v[154:157], v[186:189], v[2:5]
	v_mfma_f32_16x16x32_bf16 v[2:5], v[158:161], v[190:193], v[2:5]
	v_mfma_f32_16x16x32_bf16 v[6:9], v[150:153], v[190:193], v[6:9]
	v_mfma_f32_16x16x32_bf16 v[6:9], v[146:149], v[186:189], v[6:9]
	v_mfma_f32_16x16x32_bf16 v[10:13], v[138:141], v[186:189], v[10:13]
	v_mfma_f32_16x16x32_bf16 v[10:13], v[142:145], v[190:193], v[10:13]
	v_mfma_f32_16x16x32_bf16 v[14:17], v[134:137], v[190:193], v[14:17]
	v_mfma_f32_16x16x32_bf16 v[14:17], v[130:133], v[186:189], v[14:17]
	s_barrier
	s_setprio 0
	s_add_u32 s4, s4, 0x100
	s_addc_u32 s5, s5, 0
	s_add_u32 s15, s15, 0x100
	s_addc_u32 s42, s42, 0
	s_cmp_ge_u32 s44, s36
	s_mov_b32 s43, s44
; #define PG8_STAGE(bufoff, gbase, voff) do { _Pragma("unroll") for (int _i = 0; _i < 2; ++_i) { \
;         const unsigned _m0 = ldsb + (unsigned)((bufoff) + _i * 8192); const char* _gb = (const char*)(gbase); \
;         asm volatile("s_mov_b32 m0, %0\n\ts_nop 0\n\tglobal_load_lds_dwordx4 %1, %2" :: "s"(_m0), "v"((voff)[_i]), "s"(_gb) : "m0", "memory"); } } while (0)
; #define PG8_LDA(dst, b, h) do { _Pragma("unroll") for (int m = 0; m < 4; ++m) _Pragma("unroll") for (int k = 0; k < 2; ++k) dst[m][k] = *(const LAS bf16x8*)(lds + PG8_SA(b, h) + aoff + m * 2048 + k * 1024); } while (0)
; #define PG8_LDB(dst, b, h) do { _Pragma("unroll") for (int n = 0; n < 2; ++n) _Pragma("unroll") for (int k = 0; k < 2; ++k) dst[n][k] = *(const LAS bf16x8*)(lds + PG8_SB(b, h) + boff + n * 2048 + k * 1024); } while (0)
; #define PG8_MMA(ai, bj, At, Bt) do { __builtin_amdgcn_s_setprio(1); _Pragma("unroll") for (int m = 0; m < 4; ++m) _Pragma("unroll") for (int n = 0; n < 2; ++n) _Pragma("unroll") for (int k = 0; k < 2; ++k) \
;         acc[ai][bj][m][n] = __builtin_amdgcn_mfma_f32_16x16x32_bf16(Bt[n][k], At[m][k], acc[ai][bj][m][n], 0, 0, 0); __builtin_amdgcn_s_setprio(0); } while (0)
; #define PG8_WAIT_V(n) asm volatile("s_waitcnt vmcnt(" #n ")" ::: "memory")
; #define PG8_WAIT_L(n) asm volatile("s_waitcnt lgkmcnt(" #n ")" ::: "memory")
; template <class Epi, bool ALIGN_EPI>
; __device__ __forceinline__ void gemm_phase(LAS unsigned char* lds, const Gemm g, const StaticOrder& S, const Epi& E) {
;     ...
;         for (int t = 0; t < nt; t += 2) {
;             const bool last = (t == nt - 2);
;             const char* a1 = cA + (size_t)(t + 1) * kstep;
;             const char* a2 = last ? nA : cA + (size_t)(t + 2) * kstep; const char* b2 = last ? nB : cB + (size_t)(t + 2) * kstep;
;             const char* a3 = a2 + kstep; const char* b3 = b2 + kstep;
;             PG8_LDB(B0, 0, 0); PG8_LDB(B1, 0, 1); PG8_SCHED; PG8_LDA(At, 0, 0); PG8_STAGE(PG8_SA(1, 1), a1 + hstepA, voffA);
;             PG8_WAIT_V(8); PG8_WAIT_L(0); PG8_BAR; PG8_MMA(0, 0, At, B0); PG8_MMA(0, 1, At, B1); PG8_BAR; PG8_SCHED;
;             PG8_LDA(At, 0, 1); PG8_STAGE(PG8_SB(0, 0), b2, voffB); PG8_STAGE(PG8_SB(0, 1), b2 + hstepB, voffB); PG8_STAGE(PG8_SA(0, 0), a2, voffA);
;             PG8_WAIT_V(8); PG8_WAIT_L(0); PG8_BAR; PG8_MMA(1, 0, At, B0); PG8_MMA(1, 1, At, B1); PG8_BAR; PG8_SCHED;
.LBB0_201:
	v_add_u32_e32 v142, 0x10000, v245
	v_add_u32_e32 v158, 0x14000, v245
	ds_read_b128 v[130:133], v142
	ds_read_b128 v[134:137], v142 offset:1024
	ds_read_b128 v[138:141], v142 offset:2048
	ds_read_b128 v[142:145], v142 offset:3072
	ds_read_b128 v[146:149], v158
	ds_read_b128 v[150:153], v158 offset:1024
	ds_read_b128 v[154:157], v158 offset:2048
	ds_read_b128 v[158:161], v158 offset:3072
	s_add_i32 s44, s43, 2
	s_cmp_eq_u32 s68, s43
	s_cselect_b32 s56, s0, s15
	s_cselect_b32 s57, s1, s42
	s_cselect_b32 s54, s94, s4
	s_cselect_b32 s55, s95, s5
	s_add_u32 s48, s56, 0x80
	s_addc_u32 s49, s57, 0
	ds_read_b128 v[162:165], v246
	ds_read_b128 v[166:169], v246 offset:1024
	ds_read_b128 v[170:173], v246 offset:2048
	ds_read_b128 v[174:177], v246 offset:3072
	ds_read_b128 v[178:181], v246 offset:4096
	ds_read_b128 v[182:185], v246 offset:5120
	ds_read_b128 v[186:189], v246 offset:6144
	ds_read_b128 v[190:193], v246 offset:7168
	s_add_u32 s43, s15, s38
	s_addc_u32 s45, s42, 0
	s_add_u32 s58, s43, 0xffffff80
	s_addc_u32 s59, s45, -1
	s_mov_b32 m0, s37
	s_nop 0
	global_load_lds_dwordx4 v0, s[58:59]
	s_nop 0
	s_mov_b32 m0, s41
	s_nop 0
	global_load_lds_dwordx4 v206, s[58:59]
	s_waitcnt vmcnt(8)
	s_waitcnt lgkmcnt(0)
	s_setprio 1
	s_barrier
	v_mfma_f32_16x16x32_bf16 v[126:129], v[130:133], v[162:165], v[126:129]
	v_mfma_f32_16x16x32_bf16 v[126:129], v[134:137], v[166:169], v[126:129]
	v_mfma_f32_16x16x32_bf16 v[122:125], v[142:145], v[166:169], v[122:125]
	v_mfma_f32_16x16x32_bf16 v[122:125], v[138:141], v[162:165], v[122:125]
	v_mfma_f32_16x16x32_bf16 v[118:121], v[146:149], v[162:165], v[118:121]
	v_mfma_f32_16x16x32_bf16 v[118:121], v[150:153], v[166:169], v[118:121]
	v_mfma_f32_16x16x32_bf16 v[114:117], v[158:161], v[166:169], v[114:117]
	v_mfma_f32_16x16x32_bf16 v[114:117], v[154:157], v[162:165], v[114:117]
	v_mfma_f32_16x16x32_bf16 v[98:101], v[154:157], v[170:173], v[98:101]
	v_mfma_f32_16x16x32_bf16 v[98:101], v[158:161], v[174:177], v[98:101]
	v_mfma_f32_16x16x32_bf16 v[102:105], v[150:153], v[174:177], v[102:105]
	v_mfma_f32_16x16x32_bf16 v[102:105], v[146:149], v[170:173], v[102:105]
	v_mfma_f32_16x16x32_bf16 v[106:109], v[138:141], v[170:173], v[106:109]
	v_mfma_f32_16x16x32_bf16 v[106:109], v[142:145], v[174:177], v[106:109]
	v_mfma_f32_16x16x32_bf16 v[110:113], v[134:137], v[174:177], v[110:113]
	v_mfma_f32_16x16x32_bf16 v[110:113], v[130:133], v[170:173], v[110:113]
	v_mfma_f32_16x16x32_bf16 v[94:97], v[130:133], v[178:181], v[94:97]
	v_mfma_f32_16x16x32_bf16 v[94:97], v[134:137], v[182:185], v[94:97]
	v_mfma_f32_16x16x32_bf16 v[90:93], v[142:145], v[182:185], v[90:93]
	v_mfma_f32_16x16x32_bf16 v[90:93], v[138:141], v[178:181], v[90:93]
	v_mfma_f32_16x16x32_bf16 v[86:89], v[146:149], v[178:181], v[86:89]
	v_mfma_f32_16x16x32_bf16 v[86:89], v[150:153], v[182:185], v[86:89]
	v_mfma_f32_16x16x32_bf16 v[82:85], v[158:161], v[182:185], v[82:85]
	v_mfma_f32_16x16x32_bf16 v[82:85], v[154:157], v[178:181], v[82:85]
	v_mfma_f32_16x16x32_bf16 v[66:69], v[154:157], v[186:189], v[66:69]
	v_mfma_f32_16x16x32_bf16 v[66:69], v[158:161], v[190:193], v[66:69]
	v_mfma_f32_16x16x32_bf16 v[70:73], v[150:153], v[190:193], v[70:73]
	v_mfma_f32_16x16x32_bf16 v[70:73], v[146:149], v[186:189], v[70:73]
	v_mfma_f32_16x16x32_bf16 v[74:77], v[138:141], v[186:189], v[74:77]
	v_mfma_f32_16x16x32_bf16 v[74:77], v[142:145], v[190:193], v[74:77]
	v_mfma_f32_16x16x32_bf16 v[78:81], v[134:137], v[190:193], v[78:81]
	v_mfma_f32_16x16x32_bf16 v[78:81], v[130:133], v[186:189], v[78:81]
	s_barrier
	s_setprio 0
	ds_read_b128 v[162:165], v246 offset:16384
	ds_read_b128 v[166:169], v246 offset:17408
	ds_read_b128 v[170:173], v246 offset:18432
	ds_read_b128 v[174:177], v246 offset:19456
	ds_read_b128 v[178:181], v246 offset:20480
	ds_read_b128 v[182:185], v246 offset:21504
	ds_read_b128 v[186:189], v246 offset:22528
	ds_read_b128 v[190:193], v246 offset:23552
	s_mov_b32 m0, s46
	s_nop 0
	global_load_lds_dwordx4 v195, s[54:55]
	s_add_u32 s58, s54, s38
	s_mov_b32 m0, s26
	s_nop 0
	global_load_lds_dwordx4 v207, s[54:55]
	s_addc_u32 s59, s55, 0
	s_mov_b32 m0, s27
	s_nop 0
	global_load_lds_dwordx4 v195, s[58:59]
	s_nop 0
	s_mov_b32 m0, s30
	s_nop 0
	global_load_lds_dwordx4 v207, s[58:59]
	s_nop 0
	s_mov_b32 m0, s29
	s_nop 0
	global_load_lds_dwordx4 v0, s[56:57]
	s_nop 0
	s_mov_b32 m0, s17
	s_nop 0
	global_load_lds_dwordx4 v206, s[56:57]
	s_waitcnt vmcnt(8)
	s_waitcnt lgkmcnt(0)
	s_setprio 1
	s_barrier
	v_mfma_f32_16x16x32_bf16 v[62:65], v[130:133], v[162:165], v[62:65]
	v_mfma_f32_16x16x32_bf16 v[62:65], v[134:137], v[166:169], v[62:65]
	v_mfma_f32_16x16x32_bf16 v[58:61], v[142:145], v[166:169], v[58:61]
	v_mfma_f32_16x16x32_bf16 v[58:61], v[138:141], v[162:165], v[58:61]
	v_mfma_f32_16x16x32_bf16 v[54:57], v[146:149], v[162:165], v[54:57]
	v_mfma_f32_16x16x32_bf16 v[54:57], v[150:153], v[166:169], v[54:57]
	v_mfma_f32_16x16x32_bf16 v[50:53], v[158:161], v[166:169], v[50:53]
	v_mfma_f32_16x16x32_bf16 v[50:53], v[154:157], v[162:165], v[50:53]
	v_mfma_f32_16x16x32_bf16 v[34:37], v[154:157], v[170:173], v[34:37]
	v_mfma_f32_16x16x32_bf16 v[34:37], v[158:161], v[174:177], v[34:37]
	v_mfma_f32_16x16x32_bf16 v[38:41], v[150:153], v[174:177], v[38:41]
	v_mfma_f32_16x16x32_bf16 v[38:41], v[146:149], v[170:173], v[38:41]
	v_mfma_f32_16x16x32_bf16 v[42:45], v[138:141], v[170:173], v[42:45]
	v_mfma_f32_16x16x32_bf16 v[42:45], v[142:145], v[174:177], v[42:45]
	v_mfma_f32_16x16x32_bf16 v[46:49], v[134:137], v[174:177], v[46:49]
	v_mfma_f32_16x16x32_bf16 v[46:49], v[130:133], v[170:173], v[46:49]
	v_mfma_f32_16x16x32_bf16 v[30:33], v[130:133], v[178:181], v[30:33]
	v_mfma_f32_16x16x32_bf16 v[30:33], v[134:137], v[182:185], v[30:33]
	v_mfma_f32_16x16x32_bf16 v[26:29], v[142:145], v[182:185], v[26:29]
	v_mfma_f32_16x16x32_bf16 v[26:29], v[138:141], v[178:181], v[26:29]
	v_mfma_f32_16x16x32_bf16 v[22:25], v[146:149], v[178:181], v[22:25]
	v_mfma_f32_16x16x32_bf16 v[22:25], v[150:153], v[182:185], v[22:25]
	v_mfma_f32_16x16x32_bf16 v[18:21], v[158:161], v[182:185], v[18:21]
	v_mfma_f32_16x16x32_bf16 v[18:21], v[154:157], v[178:181], v[18:21]
	v_mfma_f32_16x16x32_bf16 v[2:5], v[154:157], v[186:189], v[2:5]
	v_mfma_f32_16x16x32_bf16 v[2:5], v[158:161], v[190:193], v[2:5]
	v_mfma_f32_16x16x32_bf16 v[6:9], v[150:153], v[190:193], v[6:9]
	v_mfma_f32_16x16x32_bf16 v[6:9], v[146:149], v[186:189], v[6:9]
	v_mfma_f32_16x16x32_bf16 v[10:13], v[138:141], v[186:189], v[10:13]
	v_mfma_f32_16x16x32_bf16 v[10:13], v[142:145], v[190:193], v[10:13]
	v_mfma_f32_16x16x32_bf16 v[14:17], v[134:137], v[190:193], v[14:17]
	v_mfma_f32_16x16x32_bf16 v[14:17], v[130:133], v[186:189], v[14:17]
	s_barrier
; #define PG8_STAGE(bufoff, gbase, voff) do { _Pragma("unroll") for (int _i = 0; _i < 2; ++_i) { \
;         const unsigned _m0 = ldsb + (unsigned)((bufoff) + _i * 8192); const char* _gb = (const char*)(gbase); \
;         asm volatile("s_mov_b32 m0, %0\n\ts_nop 0\n\tglobal_load_lds_dwordx4 %1, %2" :: "s"(_m0), "v"((voff)[_i]), "s"(_gb) : "m0", "memory"); } } while (0)
; #define PG8_LDA(dst, b, h) do { _Pragma("unroll") for (int m = 0; m < 4; ++m) _Pragma("unroll") for (int k = 0; k < 2; ++k) dst[m][k] = *(const LAS bf16x8*)(lds + PG8_SA(b, h) + aoff + m * 2048 + k * 1024); } while (0)
; #define PG8_LDB(dst, b, h) do { _Pragma("unroll") for (int n = 0; n < 2; ++n) _Pragma("unroll") for (int k = 0; k < 2; ++k) dst[n][k] = *(const LAS bf16x8*)(lds + PG8_SB(b, h) + boff + n * 2048 + k * 1024); } while (0)
; #define PG8_MMA(ai, bj, At, Bt) do { __builtin_amdgcn_s_setprio(1); _Pragma("unroll") for (int m = 0; m < 4; ++m) _Pragma("unroll") for (int n = 0; n < 2; ++n) _Pragma("unroll") for (int k = 0; k < 2; ++k) \
;         acc[ai][bj][m][n] = __builtin_amdgcn_mfma_f32_16x16x32_bf16(Bt[n][k], At[m][k], acc[ai][bj][m][n], 0, 0, 0); __builtin_amdgcn_s_setprio(0); } while (0)
; #define PG8_WAIT_V(n) asm volatile("s_waitcnt vmcnt(" #n ")" ::: "memory")
; #define PG8_WAIT_L(n) asm volatile("s_waitcnt lgkmcnt(" #n ")" ::: "memory")
; #define PG8_BAR __builtin_amdgcn_s_barrier()
; #define PG8_SCHED __builtin_amdgcn_sched_barrier(0)
; template <class Epi, bool ALIGN_EPI>
; __device__ __forceinline__ void gemm_phase(LAS unsigned char* lds, const Gemm g, const StaticOrder& S, const Epi& E) {
;     ...
;             PG8_LDB(B0, 1, 0); PG8_LDB(B1, 1, 1); PG8_SCHED; PG8_LDA(At, 1, 0); PG8_STAGE(PG8_SA(0, 1), a2 + hstepA, voffA);
;             PG8_WAIT_V(8); PG8_WAIT_L(0); PG8_BAR; PG8_MMA(0, 0, At, B0); PG8_MMA(0, 1, At, B1); PG8_BAR; PG8_SCHED;
;             PG8_LDA(At, 1, 1); PG8_STAGE(PG8_SB(1, 0), b3, voffB); PG8_STAGE(PG8_SB(1, 1), b3 + hstepB, voffB); PG8_STAGE(PG8_SA(1, 0), a3, voffA);
;             PG8_WAIT_V(8); PG8_WAIT_L(0); PG8_BAR; PG8_MMA(1, 0, At, B0); PG8_MMA(1, 1, At, B1); PG8_BAR; PG8_SCHED;
;         }
;         if constexpr (ALIGN_EPI) { if (wr == 0) PG8_BAR; }
	s_setprio 0
	v_add_u32_e32 v142, 0x18000, v245
	v_add_u32_e32 v158, 0x1c000, v245
	ds_read_b128 v[130:133], v142
	ds_read_b128 v[134:137], v142 offset:1024
	ds_read_b128 v[138:141], v142 offset:2048
	ds_read_b128 v[142:145], v142 offset:3072
	ds_read_b128 v[146:149], v158
	ds_read_b128 v[150:153], v158 offset:1024
	ds_read_b128 v[154:157], v158 offset:2048
	ds_read_b128 v[158:161], v158 offset:3072
	ds_read_b128 v[162:165], v246 offset:32768
	ds_read_b128 v[166:169], v246 offset:33792
	ds_read_b128 v[170:173], v246 offset:34816
	ds_read_b128 v[174:177], v246 offset:35840
	ds_read_b128 v[178:181], v246 offset:36864
	ds_read_b128 v[182:185], v246 offset:37888
	ds_read_b128 v[186:189], v246 offset:38912
	ds_read_b128 v[190:193], v246 offset:39936
	s_add_u32 s56, s56, s38
	s_addc_u32 s57, s57, 0
	s_mov_b32 m0, s31
	s_nop 0
	global_load_lds_dwordx4 v0, s[56:57]
	s_nop 0
	s_mov_b32 m0, s53
	s_nop 0
	global_load_lds_dwordx4 v206, s[56:57]
	s_waitcnt vmcnt(8)
	s_waitcnt lgkmcnt(0)
	s_setprio 1
	s_barrier
	v_mfma_f32_16x16x32_bf16 v[126:129], v[130:133], v[162:165], v[126:129]
	v_mfma_f32_16x16x32_bf16 v[126:129], v[134:137], v[166:169], v[126:129]
	v_mfma_f32_16x16x32_bf16 v[122:125], v[142:145], v[166:169], v[122:125]
	v_mfma_f32_16x16x32_bf16 v[122:125], v[138:141], v[162:165], v[122:125]
	v_mfma_f32_16x16x32_bf16 v[118:121], v[146:149], v[162:165], v[118:121]
	v_mfma_f32_16x16x32_bf16 v[118:121], v[150:153], v[166:169], v[118:121]
	v_mfma_f32_16x16x32_bf16 v[114:117], v[158:161], v[166:169], v[114:117]
	v_mfma_f32_16x16x32_bf16 v[114:117], v[154:157], v[162:165], v[114:117]
	v_mfma_f32_16x16x32_bf16 v[98:101], v[154:157], v[170:173], v[98:101]
	v_mfma_f32_16x16x32_bf16 v[98:101], v[158:161], v[174:177], v[98:101]
	v_mfma_f32_16x16x32_bf16 v[102:105], v[150:153], v[174:177], v[102:105]
	v_mfma_f32_16x16x32_bf16 v[102:105], v[146:149], v[170:173], v[102:105]
	v_mfma_f32_16x16x32_bf16 v[106:109], v[138:141], v[170:173], v[106:109]
	v_mfma_f32_16x16x32_bf16 v[106:109], v[142:145], v[174:177], v[106:109]
	v_mfma_f32_16x16x32_bf16 v[110:113], v[134:137], v[174:177], v[110:113]
	v_mfma_f32_16x16x32_bf16 v[110:113], v[130:133], v[170:173], v[110:113]
	v_mfma_f32_16x16x32_bf16 v[94:97], v[130:133], v[178:181], v[94:97]
	v_mfma_f32_16x16x32_bf16 v[94:97], v[134:137], v[182:185], v[94:97]
	v_mfma_f32_16x16x32_bf16 v[90:93], v[142:145], v[182:185], v[90:93]
	v_mfma_f32_16x16x32_bf16 v[90:93], v[138:141], v[178:181], v[90:93]
	v_mfma_f32_16x16x32_bf16 v[86:89], v[146:149], v[178:181], v[86:89]
	v_mfma_f32_16x16x32_bf16 v[86:89], v[150:153], v[182:185], v[86:89]
	v_mfma_f32_16x16x32_bf16 v[82:85], v[158:161], v[182:185], v[82:85]
	v_mfma_f32_16x16x32_bf16 v[82:85], v[154:157], v[178:181], v[82:85]
	v_mfma_f32_16x16x32_bf16 v[66:69], v[154:157], v[186:189], v[66:69]
	v_mfma_f32_16x16x32_bf16 v[66:69], v[158:161], v[190:193], v[66:69]
	v_mfma_f32_16x16x32_bf16 v[70:73], v[150:153], v[190:193], v[70:73]
	v_mfma_f32_16x16x32_bf16 v[70:73], v[146:149], v[186:189], v[70:73]
	v_mfma_f32_16x16x32_bf16 v[74:77], v[138:141], v[186:189], v[74:77]
	v_mfma_f32_16x16x32_bf16 v[74:77], v[142:145], v[190:193], v[74:77]
	v_mfma_f32_16x16x32_bf16 v[78:81], v[134:137], v[190:193], v[78:81]
	v_mfma_f32_16x16x32_bf16 v[78:81], v[130:133], v[186:189], v[78:81]
	s_barrier
	s_setprio 0
	ds_read_b128 v[162:165], v246 offset:49152
	ds_read_b128 v[166:169], v246 offset:50176
	ds_read_b128 v[170:173], v246 offset:51200
	ds_read_b128 v[174:177], v246 offset:52224
	ds_read_b128 v[178:181], v246 offset:53248
	ds_read_b128 v[182:185], v246 offset:54272
	ds_read_b128 v[186:189], v246 offset:55296
	ds_read_b128 v[190:193], v246 offset:56320
	s_add_u32 s54, s54, 0x80
	s_addc_u32 s55, s55, 0
	s_mov_b32 m0, s85
	s_nop 0
	global_load_lds_dwordx4 v195, s[54:55]
	s_nop 0
	s_mov_b32 m0, s65
	s_nop 0
	global_load_lds_dwordx4 v207, s[54:55]
	s_add_u32 s54, s58, 0x80
	s_addc_u32 s55, s59, 0
	s_mov_b32 m0, s93
	s_nop 0
	global_load_lds_dwordx4 v195, s[54:55]
	s_nop 0
	s_mov_b32 m0, s28
	s_nop 0
	global_load_lds_dwordx4 v207, s[54:55]
	s_nop 0
	s_mov_b32 m0, s67
	s_nop 0
	global_load_lds_dwordx4 v0, s[48:49]
	s_nop 0
	s_mov_b32 m0, s92
	s_nop 0
	global_load_lds_dwordx4 v206, s[48:49]
	s_waitcnt vmcnt(8)
	s_waitcnt lgkmcnt(0)
	s_setprio 1
	s_barrier
	v_mfma_f32_16x16x32_bf16 v[62:65], v[130:133], v[162:165], v[62:65]
	v_mfma_f32_16x16x32_bf16 v[62:65], v[134:137], v[166:169], v[62:65]
	v_mfma_f32_16x16x32_bf16 v[58:61], v[142:145], v[166:169], v[58:61]
	v_mfma_f32_16x16x32_bf16 v[58:61], v[138:141], v[162:165], v[58:61]
	v_mfma_f32_16x16x32_bf16 v[54:57], v[146:149], v[162:165], v[54:57]
	v_mfma_f32_16x16x32_bf16 v[54:57], v[150:153], v[166:169], v[54:57]
	v_mfma_f32_16x16x32_bf16 v[50:53], v[158:161], v[166:169], v[50:53]
	v_mfma_f32_16x16x32_bf16 v[50:53], v[154:157], v[162:165], v[50:53]
	v_mfma_f32_16x16x32_bf16 v[34:37], v[154:157], v[170:173], v[34:37]
	v_mfma_f32_16x16x32_bf16 v[34:37], v[158:161], v[174:177], v[34:37]
	v_mfma_f32_16x16x32_bf16 v[38:41], v[150:153], v[174:177], v[38:41]
	v_mfma_f32_16x16x32_bf16 v[38:41], v[146:149], v[170:173], v[38:41]
	v_mfma_f32_16x16x32_bf16 v[42:45], v[138:141], v[170:173], v[42:45]
	v_mfma_f32_16x16x32_bf16 v[42:45], v[142:145], v[174:177], v[42:45]
	v_mfma_f32_16x16x32_bf16 v[46:49], v[134:137], v[174:177], v[46:49]
	v_mfma_f32_16x16x32_bf16 v[46:49], v[130:133], v[170:173], v[46:49]
	v_mfma_f32_16x16x32_bf16 v[30:33], v[130:133], v[178:181], v[30:33]
	v_mfma_f32_16x16x32_bf16 v[30:33], v[134:137], v[182:185], v[30:33]
	v_mfma_f32_16x16x32_bf16 v[26:29], v[142:145], v[182:185], v[26:29]
	v_mfma_f32_16x16x32_bf16 v[26:29], v[138:141], v[178:181], v[26:29]
	v_mfma_f32_16x16x32_bf16 v[22:25], v[146:149], v[178:181], v[22:25]
	v_mfma_f32_16x16x32_bf16 v[22:25], v[150:153], v[182:185], v[22:25]
	v_mfma_f32_16x16x32_bf16 v[18:21], v[158:161], v[182:185], v[18:21]
	v_mfma_f32_16x16x32_bf16 v[18:21], v[154:157], v[178:181], v[18:21]
	v_mfma_f32_16x16x32_bf16 v[2:5], v[154:157], v[186:189], v[2:5]
	v_mfma_f32_16x16x32_bf16 v[2:5], v[158:161], v[190:193], v[2:5]
	v_mfma_f32_16x16x32_bf16 v[6:9], v[150:153], v[190:193], v[6:9]
	v_mfma_f32_16x16x32_bf16 v[6:9], v[146:149], v[186:189], v[6:9]
	v_mfma_f32_16x16x32_bf16 v[10:13], v[138:141], v[186:189], v[10:13]
	v_mfma_f32_16x16x32_bf16 v[10:13], v[142:145], v[190:193], v[10:13]
	v_mfma_f32_16x16x32_bf16 v[14:17], v[134:137], v[190:193], v[14:17]
	v_mfma_f32_16x16x32_bf16 v[14:17], v[130:133], v[186:189], v[14:17]
	s_barrier
	s_setprio 0
	s_add_u32 s4, s4, 0x100
	s_addc_u32 s5, s5, 0
	s_add_u32 s15, s15, 0x100
	s_addc_u32 s42, s42, 0
	s_cmp_ge_u32 s44, s36
	s_mov_b32 s43, s44
	s_cbranch_scc0 .LBB0_201
	v_readlane_b32 s4, v255, 6
	v_readlane_b32 s5, v255, 7
	s_and_b64 vcc, exec, s[4:5]
	s_cbranch_vccz .LBB0_204
	s_barrier

; #define PG8_STAGE(bufoff, gbase, voff) do { _Pragma("unroll") for (int _i = 0; _i < 2; ++_i) { \
;         const unsigned _m0 = ldsb + (unsigned)((bufoff) + _i * 8192); const char* _gb = (const char*)(gbase); \
;         asm volatile("s_mov_b32 m0, %0\n\ts_nop 0\n\tglobal_load_lds_dwordx4 %1, %2" :: "s"(_m0), "v"((voff)[_i]), "s"(_gb) : "m0", "memory"); } } while (0)
; #define PG8_LDA(dst, b, h) do { _Pragma("unroll") for (int m = 0; m < 4; ++m) _Pragma("unroll") for (int k = 0; k < 2; ++k) dst[m][k] = *(const LAS bf16x8*)(lds + PG8_SA(b, h) + aoff + m * 2048 + k * 1024); } while (0)
; #define PG8_LDB(dst, b, h) do { _Pragma("unroll") for (int n = 0; n < 2; ++n) _Pragma("unroll") for (int k = 0; k < 2; ++k) dst[n][k] = *(const LAS bf16x8*)(lds + PG8_SB(b, h) + boff + n * 2048 + k * 1024); } while (0)
; #define PG8_WAIT_V(n) asm volatile("s_waitcnt vmcnt(" #n ")" ::: "memory")
; #define PG8_WAIT_L(n) asm volatile("s_waitcnt lgkmcnt(" #n ")" ::: "memory")
; #define PG8_BAR __builtin_amdgcn_s_barrier()
; #define PG8_SCHED __builtin_amdgcn_sched_barrier(0)
; template <class Epi, bool ALIGN_EPI>
; __device__ __forceinline__ void gemm_phase(LAS unsigned char* lds, const Gemm g, const StaticOrder& S, const Epi& E) {
;     ...
;         const bool has_next = S.next(ui + 1, nxt);
;         const char* nA = has_next ? (const char*)g.A + (size_t)nxt.pm * tstepA + (size_t)nxt.pn * g.a_pn_off * 2 + (size_t)(nxt.pm >> 4) * g.a_adj : cA; const char* nB = has_next ? (const char*)g.Bt + (size_t)nxt.pn * tstepB : cB;
;         for (int t = 0; t < nt; t += 2) {
;             const bool last = (t == nt - 2);
;             const char* a1 = cA + (size_t)(t + 1) * kstep;
;             const char* a2 = last ? nA : cA + (size_t)(t + 2) * kstep; const char* b2 = last ? nB : cB + (size_t)(t + 2) * kstep;
;             const char* a3 = a2 + kstep; const char* b3 = b2 + kstep;
;             PG8_LDB(B0, 0, 0); PG8_LDB(B1, 0, 1); PG8_SCHED; PG8_LDA(At, 0, 0); PG8_STAGE(PG8_SA(1, 1), a1 + hstepA, voffA);
;             PG8_WAIT_V(8); PG8_WAIT_L(0); PG8_BAR; PG8_MMA(0, 0, At, B0); PG8_MMA(0, 1, At, B1); PG8_BAR; PG8_SCHED;
;             PG8_LDA(At, 0, 1); PG8_STAGE(PG8_SB(0, 0), b2, voffB); PG8_STAGE(PG8_SB(0, 1), b2 + hstepB, voffB); PG8_STAGE(PG8_SA(0, 0), a2, voffA);
;             PG8_WAIT_V(8); PG8_WAIT_L(0); PG8_BAR; PG8_MMA(1, 0, At, B0); PG8_MMA(1, 1, At, B1); PG8_BAR; PG8_SCHED;
.LBB0_270:
	s_add_u32 s4, s56, 0x100
	s_addc_u32 s5, s57, 0
	s_add_u32 s0, s58, 0x40080
	s_addc_u32 s1, s59, 0
	s_mov_b32 s44, 0
	s_add_i32 s55, s44, 2
	s_add_u32 s45, s0, 0xfffc0080
	s_addc_u32 s56, s1, -1
	s_cmp_eq_u32 s68, s44
	s_cselect_b32 s60, s96, s45
	s_cselect_b32 s61, s97, s56
	s_cselect_b32 s58, s48, s4
	s_cselect_b32 s59, s49, s5
	s_add_u32 s56, s60, 0x80
	s_addc_u32 s57, s61, 0
	s_mov_b32 m0, s41
	s_nop 0
	global_load_lds_dwordx4 v165, s[0:1]
	s_nop 0
	s_mov_b32 m0, s30
	s_nop 0
	global_load_lds_dwordx4 v171, s[0:1]
	s_waitcnt vmcnt(8)
	s_waitcnt lgkmcnt(0)
	s_setprio 1
	s_barrier
	v_mfma_f32_16x16x32_bf16 v[126:129], v[130:133], v[182:185], 0
	v_mfma_f32_16x16x32_bf16 v[126:129], v[134:137], v[186:189], v[126:129]
	v_mfma_f32_16x16x32_bf16 v[122:125], v[142:145], v[186:189], 0
	v_mfma_f32_16x16x32_bf16 v[122:125], v[138:141], v[182:185], v[122:125]
	v_mfma_f32_16x16x32_bf16 v[118:121], v[146:149], v[182:185], 0
	v_mfma_f32_16x16x32_bf16 v[118:121], v[150:153], v[186:189], v[118:121]
	v_mfma_f32_16x16x32_bf16 v[110:113], v[158:161], v[186:189], 0
	v_mfma_f32_16x16x32_bf16 v[110:113], v[154:157], v[182:185], v[110:113]
	v_mfma_f32_16x16x32_bf16 v[94:97], v[154:157], v[190:193], 0
	v_mfma_f32_16x16x32_bf16 v[94:97], v[158:161], v[202:205], v[94:97]
	v_mfma_f32_16x16x32_bf16 v[102:105], v[150:153], v[202:205], 0
	v_mfma_f32_16x16x32_bf16 v[102:105], v[146:149], v[190:193], v[102:105]
	v_mfma_f32_16x16x32_bf16 v[106:109], v[138:141], v[190:193], 0
	v_mfma_f32_16x16x32_bf16 v[106:109], v[142:145], v[202:205], v[106:109]
	v_mfma_f32_16x16x32_bf16 v[114:117], v[134:137], v[202:205], 0
	v_mfma_f32_16x16x32_bf16 v[114:117], v[130:133], v[190:193], v[114:117]
	v_mfma_f32_16x16x32_bf16 v[98:101], v[130:133], v[206:209], 0
	v_mfma_f32_16x16x32_bf16 v[98:101], v[134:137], v[210:213], v[98:101]
	v_mfma_f32_16x16x32_bf16 v[90:93], v[142:145], v[210:213], 0
	v_mfma_f32_16x16x32_bf16 v[90:93], v[138:141], v[206:209], v[90:93]
	v_mfma_f32_16x16x32_bf16 v[86:89], v[146:149], v[206:209], 0
	v_mfma_f32_16x16x32_bf16 v[86:89], v[150:153], v[210:213], v[86:89]
	v_mfma_f32_16x16x32_bf16 v[78:81], v[158:161], v[210:213], 0
	v_mfma_f32_16x16x32_bf16 v[78:81], v[154:157], v[206:209], v[78:81]
	v_mfma_f32_16x16x32_bf16 v[66:69], v[154:157], v[214:217], 0
	v_mfma_f32_16x16x32_bf16 v[66:69], v[158:161], v[240:243], v[66:69]
	v_mfma_f32_16x16x32_bf16 v[70:73], v[150:153], v[240:243], 0
	v_mfma_f32_16x16x32_bf16 v[70:73], v[146:149], v[214:217], v[70:73]
	v_mfma_f32_16x16x32_bf16 v[74:77], v[138:141], v[214:217], 0
	v_mfma_f32_16x16x32_bf16 v[74:77], v[142:145], v[240:243], v[74:77]
	v_mfma_f32_16x16x32_bf16 v[82:85], v[134:137], v[240:243], 0
	v_mfma_f32_16x16x32_bf16 v[82:85], v[130:133], v[214:217], v[82:85]
	s_barrier
	s_setprio 0
	ds_read_b128 v[182:185], v180 offset:16384
	ds_read_b128 v[186:189], v180 offset:17408
	ds_read_b128 v[190:193], v180 offset:18432
	ds_read_b128 v[202:205], v180 offset:19456
	ds_read_b128 v[206:209], v180 offset:20480
	ds_read_b128 v[210:213], v180 offset:21504
	ds_read_b128 v[214:217], v180 offset:22528
	ds_read_b128 v[240:243], v180 offset:23552
	s_mov_b32 m0, s42
	s_nop 0
	global_load_lds_dwordx4 v167, s[58:59]
	s_add_u32 s44, s58, s14
	s_mov_b32 m0, s43
	s_nop 0
	global_load_lds_dwordx4 v175, s[58:59]
	s_addc_u32 s45, s59, 0
	s_mov_b32 m0, s46
	s_nop 0
	global_load_lds_dwordx4 v167, s[44:45]
	s_nop 0
	s_mov_b32 m0, s50
	s_nop 0
	global_load_lds_dwordx4 v175, s[44:45]
	s_nop 0
	s_mov_b32 m0, s17
	s_nop 0
	global_load_lds_dwordx4 v165, s[60:61]
	s_nop 0
	s_mov_b32 m0, s53
	s_nop 0
	global_load_lds_dwordx4 v171, s[60:61]
	s_waitcnt vmcnt(8)
	s_waitcnt lgkmcnt(0)
	s_setprio 1
	s_barrier
	v_mfma_f32_16x16x32_bf16 v[62:65], v[130:133], v[182:185], 0
	v_mfma_f32_16x16x32_bf16 v[62:65], v[134:137], v[186:189], v[62:65]
	v_mfma_f32_16x16x32_bf16 v[58:61], v[142:145], v[186:189], 0
	v_mfma_f32_16x16x32_bf16 v[58:61], v[138:141], v[182:185], v[58:61]
	v_mfma_f32_16x16x32_bf16 v[54:57], v[146:149], v[182:185], 0
	v_mfma_f32_16x16x32_bf16 v[54:57], v[150:153], v[186:189], v[54:57]
	v_mfma_f32_16x16x32_bf16 v[50:53], v[158:161], v[186:189], 0
	v_mfma_f32_16x16x32_bf16 v[50:53], v[154:157], v[182:185], v[50:53]
	v_mfma_f32_16x16x32_bf16 v[30:33], v[154:157], v[190:193], 0
	v_mfma_f32_16x16x32_bf16 v[30:33], v[158:161], v[202:205], v[30:33]
	v_mfma_f32_16x16x32_bf16 v[38:41], v[150:153], v[202:205], 0
	v_mfma_f32_16x16x32_bf16 v[38:41], v[146:149], v[190:193], v[38:41]
	v_mfma_f32_16x16x32_bf16 v[42:45], v[138:141], v[190:193], 0
	v_mfma_f32_16x16x32_bf16 v[42:45], v[142:145], v[202:205], v[42:45]
	v_mfma_f32_16x16x32_bf16 v[46:49], v[134:137], v[202:205], 0
	v_mfma_f32_16x16x32_bf16 v[46:49], v[130:133], v[190:193], v[46:49]
	v_mfma_f32_16x16x32_bf16 v[34:37], v[130:133], v[206:209], 0
	v_mfma_f32_16x16x32_bf16 v[34:37], v[134:137], v[210:213], v[34:37]
	v_mfma_f32_16x16x32_bf16 v[26:29], v[142:145], v[210:213], 0
	v_mfma_f32_16x16x32_bf16 v[26:29], v[138:141], v[206:209], v[26:29]
	v_mfma_f32_16x16x32_bf16 v[22:25], v[146:149], v[206:209], 0
	v_mfma_f32_16x16x32_bf16 v[22:25], v[150:153], v[210:213], v[22:25]
	v_mfma_f32_16x16x32_bf16 v[14:17], v[158:161], v[210:213], 0
	v_mfma_f32_16x16x32_bf16 v[14:17], v[154:157], v[206:209], v[14:17]
	v_mfma_f32_16x16x32_bf16 v[2:5], v[154:157], v[214:217], 0
	v_mfma_f32_16x16x32_bf16 v[2:5], v[158:161], v[240:243], v[2:5]
	v_mfma_f32_16x16x32_bf16 v[6:9], v[150:153], v[240:243], 0
	v_mfma_f32_16x16x32_bf16 v[6:9], v[146:149], v[214:217], v[6:9]
	v_mfma_f32_16x16x32_bf16 v[10:13], v[138:141], v[214:217], 0
	v_mfma_f32_16x16x32_bf16 v[10:13], v[142:145], v[240:243], v[10:13]
	v_mfma_f32_16x16x32_bf16 v[18:21], v[134:137], v[240:243], 0
	v_mfma_f32_16x16x32_bf16 v[18:21], v[130:133], v[214:217], v[18:21]
	s_barrier
; #define PG8_STAGE(bufoff, gbase, voff) do { _Pragma("unroll") for (int _i = 0; _i < 2; ++_i) { \
;         const unsigned _m0 = ldsb + (unsigned)((bufoff) + _i * 8192); const char* _gb = (const char*)(gbase); \
;         asm volatile("s_mov_b32 m0, %0\n\ts_nop 0\n\tglobal_load_lds_dwordx4 %1, %2" :: "s"(_m0), "v"((voff)[_i]), "s"(_gb) : "m0", "memory"); } } while (0)
; #define PG8_LDA(dst, b, h) do { _Pragma("unroll") for (int m = 0; m < 4; ++m) _Pragma("unroll") for (int k = 0; k < 2; ++k) dst[m][k] = *(const LAS bf16x8*)(lds + PG8_SA(b, h) + aoff + m * 2048 + k * 1024); } while (0)
; #define PG8_LDB(dst, b, h) do { _Pragma("unroll") for (int n = 0; n < 2; ++n) _Pragma("unroll") for (int k = 0; k < 2; ++k) dst[n][k] = *(const LAS bf16x8*)(lds + PG8_SB(b, h) + boff + n * 2048 + k * 1024); } while (0)
; #define PG8_MMA(ai, bj, At, Bt) do { __builtin_amdgcn_s_setprio(1); _Pragma("unroll") for (int m = 0; m < 4; ++m) _Pragma("unroll") for (int n = 0; n < 2; ++n) _Pragma("unroll") for (int k = 0; k < 2; ++k) \
;         acc[ai][bj][m][n] = __builtin_amdgcn_mfma_f32_16x16x32_bf16(Bt[n][k], At[m][k], acc[ai][bj][m][n], 0, 0, 0); __builtin_amdgcn_s_setprio(0); } while (0)
; #define PG8_WAIT_V(n) asm volatile("s_waitcnt vmcnt(" #n ")" ::: "memory")
; #define PG8_WAIT_L(n) asm volatile("s_waitcnt lgkmcnt(" #n ")" ::: "memory")
; #define PG8_BAR __builtin_amdgcn_s_barrier()
; #define PG8_SCHED __builtin_amdgcn_sched_barrier(0)
; template <class Epi, bool ALIGN_EPI>
; __device__ __forceinline__ void gemm_phase(LAS unsigned char* lds, const Gemm g, const StaticOrder& S, const Epi& E) {
;     ...
;             PG8_LDB(B0, 1, 0); PG8_LDB(B1, 1, 1); PG8_SCHED; PG8_LDA(At, 1, 0); PG8_STAGE(PG8_SA(0, 1), a2 + hstepA, voffA);
;             PG8_WAIT_V(8); PG8_WAIT_L(0); PG8_BAR; PG8_MMA(0, 0, At, B0); PG8_MMA(0, 1, At, B1); PG8_BAR; PG8_SCHED;
;             PG8_LDA(At, 1, 1); PG8_STAGE(PG8_SB(1, 0), b3, voffB); PG8_STAGE(PG8_SB(1, 1), b3 + hstepB, voffB); PG8_STAGE(PG8_SA(1, 0), a3, voffA);
;             PG8_WAIT_V(8); PG8_WAIT_L(0); PG8_BAR; PG8_MMA(1, 0, At, B0); PG8_MMA(1, 1, At, B1); PG8_BAR; PG8_SCHED;
;         }
	s_setprio 0
	v_add_u32_e32 v0, 0x18000, v179
	ds_read_b128 v[130:133], v0
	ds_read_b128 v[134:137], v0 offset:1024
	ds_read_b128 v[138:141], v0 offset:2048
	ds_read_b128 v[142:145], v0 offset:3072
	v_add_u32_e32 v0, 0x1c000, v179
	ds_read_b128 v[146:149], v0
	ds_read_b128 v[150:153], v0 offset:1024
	ds_read_b128 v[154:157], v0 offset:2048
	ds_read_b128 v[158:161], v0 offset:3072
	ds_read_b128 v[182:185], v180 offset:32768
	ds_read_b128 v[186:189], v180 offset:33792
	ds_read_b128 v[190:193], v180 offset:34816
	ds_read_b128 v[202:205], v180 offset:35840
	ds_read_b128 v[206:209], v180 offset:36864
	ds_read_b128 v[210:213], v180 offset:37888
	ds_read_b128 v[214:217], v180 offset:38912
	ds_read_b128 v[240:243], v180 offset:39936
	s_add_u32 s60, s60, 0x40000
	s_addc_u32 s61, s61, 0
	s_mov_b32 m0, s65
	s_nop 0
	global_load_lds_dwordx4 v165, s[60:61]
	s_nop 0
	s_mov_b32 m0, s67
	s_nop 0
	global_load_lds_dwordx4 v171, s[60:61]
	s_waitcnt vmcnt(8)
	s_waitcnt lgkmcnt(0)
	s_setprio 1
	s_barrier
	v_mfma_f32_16x16x32_bf16 v[126:129], v[130:133], v[182:185], v[126:129]
	v_mfma_f32_16x16x32_bf16 v[126:129], v[134:137], v[186:189], v[126:129]
	v_mfma_f32_16x16x32_bf16 v[122:125], v[142:145], v[186:189], v[122:125]
	v_mfma_f32_16x16x32_bf16 v[122:125], v[138:141], v[182:185], v[122:125]
	v_mfma_f32_16x16x32_bf16 v[118:121], v[146:149], v[182:185], v[118:121]
	v_mfma_f32_16x16x32_bf16 v[118:121], v[150:153], v[186:189], v[118:121]
	v_mfma_f32_16x16x32_bf16 v[110:113], v[158:161], v[186:189], v[110:113]
	v_mfma_f32_16x16x32_bf16 v[110:113], v[154:157], v[182:185], v[110:113]
	v_mfma_f32_16x16x32_bf16 v[94:97], v[154:157], v[190:193], v[94:97]
	v_mfma_f32_16x16x32_bf16 v[94:97], v[158:161], v[202:205], v[94:97]
	v_mfma_f32_16x16x32_bf16 v[102:105], v[150:153], v[202:205], v[102:105]
	v_mfma_f32_16x16x32_bf16 v[102:105], v[146:149], v[190:193], v[102:105]
	v_mfma_f32_16x16x32_bf16 v[106:109], v[138:141], v[190:193], v[106:109]
	v_mfma_f32_16x16x32_bf16 v[106:109], v[142:145], v[202:205], v[106:109]
	v_mfma_f32_16x16x32_bf16 v[114:117], v[134:137], v[202:205], v[114:117]
	v_mfma_f32_16x16x32_bf16 v[114:117], v[130:133], v[190:193], v[114:117]
	v_mfma_f32_16x16x32_bf16 v[98:101], v[130:133], v[206:209], v[98:101]
	v_mfma_f32_16x16x32_bf16 v[98:101], v[134:137], v[210:213], v[98:101]
	v_mfma_f32_16x16x32_bf16 v[90:93], v[142:145], v[210:213], v[90:93]
	v_mfma_f32_16x16x32_bf16 v[90:93], v[138:141], v[206:209], v[90:93]
	v_mfma_f32_16x16x32_bf16 v[86:89], v[146:149], v[206:209], v[86:89]
	v_mfma_f32_16x16x32_bf16 v[86:89], v[150:153], v[210:213], v[86:89]
	v_mfma_f32_16x16x32_bf16 v[78:81], v[158:161], v[210:213], v[78:81]
	v_mfma_f32_16x16x32_bf16 v[78:81], v[154:157], v[206:209], v[78:81]
	v_mfma_f32_16x16x32_bf16 v[66:69], v[154:157], v[214:217], v[66:69]
	v_mfma_f32_16x16x32_bf16 v[66:69], v[158:161], v[240:243], v[66:69]
	v_mfma_f32_16x16x32_bf16 v[70:73], v[150:153], v[240:243], v[70:73]
	v_mfma_f32_16x16x32_bf16 v[70:73], v[146:149], v[214:217], v[70:73]
	v_mfma_f32_16x16x32_bf16 v[74:77], v[138:141], v[214:217], v[74:77]
	v_mfma_f32_16x16x32_bf16 v[74:77], v[142:145], v[240:243], v[74:77]
	v_mfma_f32_16x16x32_bf16 v[82:85], v[134:137], v[240:243], v[82:85]
	v_mfma_f32_16x16x32_bf16 v[82:85], v[130:133], v[214:217], v[82:85]
	s_barrier
	s_setprio 0
	ds_read_b128 v[182:185], v180 offset:49152
	ds_read_b128 v[186:189], v180 offset:50176
	ds_read_b128 v[190:193], v180 offset:51200
	ds_read_b128 v[202:205], v180 offset:52224
	ds_read_b128 v[206:209], v180 offset:53248
	ds_read_b128 v[210:213], v180 offset:54272
	ds_read_b128 v[214:217], v180 offset:55296
	ds_read_b128 v[240:243], v180 offset:56320
	s_add_u32 s58, s58, 0x80
	s_addc_u32 s59, s59, 0
	s_mov_b32 m0, s89
	s_nop 0
	global_load_lds_dwordx4 v167, s[58:59]
	s_add_u32 s44, s44, 0x80
	s_mov_b32 m0, s95
	s_nop 0
	global_load_lds_dwordx4 v175, s[58:59]
	s_addc_u32 s45, s45, 0
	s_mov_b32 m0, s26
	s_nop 0
	global_load_lds_dwordx4 v167, s[44:45]
	s_nop 0
	s_mov_b32 m0, s27
	s_nop 0
	global_load_lds_dwordx4 v175, s[44:45]
	s_nop 0
	s_mov_b32 m0, s36
	s_nop 0
	global_load_lds_dwordx4 v165, s[56:57]
	s_nop 0
	s_mov_b32 m0, s37
	s_nop 0
	global_load_lds_dwordx4 v171, s[56:57]
	s_waitcnt vmcnt(8)
	s_waitcnt lgkmcnt(0)
	s_setprio 1
	s_barrier
	v_mfma_f32_16x16x32_bf16 v[62:65], v[130:133], v[182:185], v[62:65]
	v_mfma_f32_16x16x32_bf16 v[62:65], v[134:137], v[186:189], v[62:65]
	v_mfma_f32_16x16x32_bf16 v[58:61], v[142:145], v[186:189], v[58:61]
	v_mfma_f32_16x16x32_bf16 v[58:61], v[138:141], v[182:185], v[58:61]
	v_mfma_f32_16x16x32_bf16 v[54:57], v[146:149], v[182:185], v[54:57]
	v_mfma_f32_16x16x32_bf16 v[54:57], v[150:153], v[186:189], v[54:57]
	v_mfma_f32_16x16x32_bf16 v[50:53], v[158:161], v[186:189], v[50:53]
	v_mfma_f32_16x16x32_bf16 v[50:53], v[154:157], v[182:185], v[50:53]
	v_mfma_f32_16x16x32_bf16 v[30:33], v[154:157], v[190:193], v[30:33]
	v_mfma_f32_16x16x32_bf16 v[30:33], v[158:161], v[202:205], v[30:33]
	v_mfma_f32_16x16x32_bf16 v[38:41], v[150:153], v[202:205], v[38:41]
	v_mfma_f32_16x16x32_bf16 v[38:41], v[146:149], v[190:193], v[38:41]
	v_mfma_f32_16x16x32_bf16 v[42:45], v[138:141], v[190:193], v[42:45]
	v_mfma_f32_16x16x32_bf16 v[42:45], v[142:145], v[202:205], v[42:45]
	v_mfma_f32_16x16x32_bf16 v[46:49], v[134:137], v[202:205], v[46:49]
	v_mfma_f32_16x16x32_bf16 v[46:49], v[130:133], v[190:193], v[46:49]
	v_mfma_f32_16x16x32_bf16 v[34:37], v[130:133], v[206:209], v[34:37]
	v_mfma_f32_16x16x32_bf16 v[34:37], v[134:137], v[210:213], v[34:37]
	v_mfma_f32_16x16x32_bf16 v[26:29], v[142:145], v[210:213], v[26:29]
	v_mfma_f32_16x16x32_bf16 v[26:29], v[138:141], v[206:209], v[26:29]
	v_mfma_f32_16x16x32_bf16 v[22:25], v[146:149], v[206:209], v[22:25]
	v_mfma_f32_16x16x32_bf16 v[22:25], v[150:153], v[210:213], v[22:25]
	v_mfma_f32_16x16x32_bf16 v[14:17], v[158:161], v[210:213], v[14:17]
	v_mfma_f32_16x16x32_bf16 v[14:17], v[154:157], v[206:209], v[14:17]
	v_mfma_f32_16x16x32_bf16 v[2:5], v[154:157], v[214:217], v[2:5]
	v_mfma_f32_16x16x32_bf16 v[2:5], v[158:161], v[240:243], v[2:5]
	v_mfma_f32_16x16x32_bf16 v[6:9], v[150:153], v[240:243], v[6:9]
	v_mfma_f32_16x16x32_bf16 v[6:9], v[146:149], v[214:217], v[6:9]
	v_mfma_f32_16x16x32_bf16 v[10:13], v[138:141], v[214:217], v[10:13]
	v_mfma_f32_16x16x32_bf16 v[10:13], v[142:145], v[240:243], v[10:13]
	v_mfma_f32_16x16x32_bf16 v[18:21], v[134:137], v[240:243], v[18:21]
	v_mfma_f32_16x16x32_bf16 v[18:21], v[130:133], v[214:217], v[18:21]
	s_barrier
	s_setprio 0
	s_add_u32 s4, s4, 0x100
	s_addc_u32 s5, s5, 0
	s_add_u32 s0, s0, 0x100
	s_addc_u32 s1, s1, 0
	s_cmp_ge_u32 s55, s31
	s_mov_b32 s44, s55
; #define PG8_STAGE(bufoff, gbase, voff) do { _Pragma("unroll") for (int _i = 0; _i < 2; ++_i) { \
;         const unsigned _m0 = ldsb + (unsigned)((bufoff) + _i * 8192); const char* _gb = (const char*)(gbase); \
;         asm volatile("s_mov_b32 m0, %0\n\ts_nop 0\n\tglobal_load_lds_dwordx4 %1, %2" :: "s"(_m0), "v"((voff)[_i]), "s"(_gb) : "m0", "memory"); } } while (0)
; #define PG8_LDA(dst, b, h) do { _Pragma("unroll") for (int m = 0; m < 4; ++m) _Pragma("unroll") for (int k = 0; k < 2; ++k) dst[m][k] = *(const LAS bf16x8*)(lds + PG8_SA(b, h) + aoff + m * 2048 + k * 1024); } while (0)
; #define PG8_LDB(dst, b, h) do { _Pragma("unroll") for (int n = 0; n < 2; ++n) _Pragma("unroll") for (int k = 0; k < 2; ++k) dst[n][k] = *(const LAS bf16x8*)(lds + PG8_SB(b, h) + boff + n * 2048 + k * 1024); } while (0)
; #define PG8_MMA(ai, bj, At, Bt) do { __builtin_amdgcn_s_setprio(1); _Pragma("unroll") for (int m = 0; m < 4; ++m) _Pragma("unroll") for (int n = 0; n < 2; ++n) _Pragma("unroll") for (int k = 0; k < 2; ++k) \
;         acc[ai][bj][m][n] = __builtin_amdgcn_mfma_f32_16x16x32_bf16(Bt[n][k], At[m][k], acc[ai][bj][m][n], 0, 0, 0); __builtin_amdgcn_s_setprio(0); } while (0)
; #define PG8_WAIT_V(n) asm volatile("s_waitcnt vmcnt(" #n ")" ::: "memory")
; #define PG8_WAIT_L(n) asm volatile("s_waitcnt lgkmcnt(" #n ")" ::: "memory")
; template <class Epi, bool ALIGN_EPI>
; __device__ __forceinline__ void gemm_phase(LAS unsigned char* lds, const Gemm g, const StaticOrder& S, const Epi& E) {
;     ...
;         for (int t = 0; t < nt; t += 2) {
;             const bool last = (t == nt - 2);
;             const char* a1 = cA + (size_t)(t + 1) * kstep;
;             const char* a2 = last ? nA : cA + (size_t)(t + 2) * kstep; const char* b2 = last ? nB : cB + (size_t)(t + 2) * kstep;
;             const char* a3 = a2 + kstep; const char* b3 = b2 + kstep;
;             PG8_LDB(B0, 0, 0); PG8_LDB(B1, 0, 1); PG8_SCHED; PG8_LDA(At, 0, 0); PG8_STAGE(PG8_SA(1, 1), a1 + hstepA, voffA);
;             PG8_WAIT_V(8); PG8_WAIT_L(0); PG8_BAR; PG8_MMA(0, 0, At, B0); PG8_MMA(0, 1, At, B1); PG8_BAR; PG8_SCHED;
;             PG8_LDA(At, 0, 1); PG8_STAGE(PG8_SB(0, 0), b2, voffB); PG8_STAGE(PG8_SB(0, 1), b2 + hstepB, voffB); PG8_STAGE(PG8_SA(0, 0), a2, voffA);
;             PG8_WAIT_V(8); PG8_WAIT_L(0); PG8_BAR; PG8_MMA(1, 0, At, B0); PG8_MMA(1, 1, At, B1); PG8_BAR; PG8_SCHED;
.LBB0_271:
	v_add_u32_e32 v0, 0x10000, v179
	ds_read_b128 v[130:133], v0
	ds_read_b128 v[134:137], v0 offset:1024
	ds_read_b128 v[138:141], v0 offset:2048
	ds_read_b128 v[142:145], v0 offset:3072
	v_add_u32_e32 v0, 0x14000, v179
	ds_read_b128 v[146:149], v0
	ds_read_b128 v[150:153], v0 offset:1024
	ds_read_b128 v[154:157], v0 offset:2048
	ds_read_b128 v[158:161], v0 offset:3072
	s_add_i32 s55, s44, 2
	s_add_u32 s45, s0, 0xfffc0080
	s_addc_u32 s56, s1, -1
	s_cmp_eq_u32 s68, s44
	s_cselect_b32 s60, s96, s45
	s_cselect_b32 s61, s97, s56
	s_cselect_b32 s58, s48, s4
	s_cselect_b32 s59, s49, s5
	s_add_u32 s56, s60, 0x80
	s_addc_u32 s57, s61, 0
	ds_read_b128 v[182:185], v180
	ds_read_b128 v[186:189], v180 offset:1024
	ds_read_b128 v[190:193], v180 offset:2048
	ds_read_b128 v[202:205], v180 offset:3072
	ds_read_b128 v[206:209], v180 offset:4096
	ds_read_b128 v[210:213], v180 offset:5120
	ds_read_b128 v[214:217], v180 offset:6144
	ds_read_b128 v[240:243], v180 offset:7168
	s_mov_b32 m0, s41
	s_nop 0
	global_load_lds_dwordx4 v165, s[0:1]
	s_nop 0
	s_mov_b32 m0, s30
	s_nop 0
	global_load_lds_dwordx4 v171, s[0:1]
	s_waitcnt vmcnt(8)
	s_waitcnt lgkmcnt(0)
	s_setprio 1
	s_barrier
	v_mfma_f32_16x16x32_bf16 v[126:129], v[130:133], v[182:185], v[126:129]
	v_mfma_f32_16x16x32_bf16 v[126:129], v[134:137], v[186:189], v[126:129]
	v_mfma_f32_16x16x32_bf16 v[122:125], v[142:145], v[186:189], v[122:125]
	v_mfma_f32_16x16x32_bf16 v[122:125], v[138:141], v[182:185], v[122:125]
	v_mfma_f32_16x16x32_bf16 v[118:121], v[146:149], v[182:185], v[118:121]
	v_mfma_f32_16x16x32_bf16 v[118:121], v[150:153], v[186:189], v[118:121]
	v_mfma_f32_16x16x32_bf16 v[110:113], v[158:161], v[186:189], v[110:113]
	v_mfma_f32_16x16x32_bf16 v[110:113], v[154:157], v[182:185], v[110:113]
	v_mfma_f32_16x16x32_bf16 v[94:97], v[154:157], v[190:193], v[94:97]
	v_mfma_f32_16x16x32_bf16 v[94:97], v[158:161], v[202:205], v[94:97]
	v_mfma_f32_16x16x32_bf16 v[102:105], v[150:153], v[202:205], v[102:105]
	v_mfma_f32_16x16x32_bf16 v[102:105], v[146:149], v[190:193], v[102:105]
	v_mfma_f32_16x16x32_bf16 v[106:109], v[138:141], v[190:193], v[106:109]
	v_mfma_f32_16x16x32_bf16 v[106:109], v[142:145], v[202:205], v[106:109]
	v_mfma_f32_16x16x32_bf16 v[114:117], v[134:137], v[202:205], v[114:117]
	v_mfma_f32_16x16x32_bf16 v[114:117], v[130:133], v[190:193], v[114:117]
	v_mfma_f32_16x16x32_bf16 v[98:101], v[130:133], v[206:209], v[98:101]
	v_mfma_f32_16x16x32_bf16 v[98:101], v[134:137], v[210:213], v[98:101]
	v_mfma_f32_16x16x32_bf16 v[90:93], v[142:145], v[210:213], v[90:93]
	v_mfma_f32_16x16x32_bf16 v[90:93], v[138:141], v[206:209], v[90:93]
	v_mfma_f32_16x16x32_bf16 v[86:89], v[146:149], v[206:209], v[86:89]
	v_mfma_f32_16x16x32_bf16 v[86:89], v[150:153], v[210:213], v[86:89]
	v_mfma_f32_16x16x32_bf16 v[78:81], v[158:161], v[210:213], v[78:81]
	v_mfma_f32_16x16x32_bf16 v[78:81], v[154:157], v[206:209], v[78:81]
	v_mfma_f32_16x16x32_bf16 v[66:69], v[154:157], v[214:217], v[66:69]
	v_mfma_f32_16x16x32_bf16 v[66:69], v[158:161], v[240:243], v[66:69]
	v_mfma_f32_16x16x32_bf16 v[70:73], v[150:153], v[240:243], v[70:73]
	v_mfma_f32_16x16x32_bf16 v[70:73], v[146:149], v[214:217], v[70:73]
	v_mfma_f32_16x16x32_bf16 v[74:77], v[138:141], v[214:217], v[74:77]
	v_mfma_f32_16x16x32_bf16 v[74:77], v[142:145], v[240:243], v[74:77]
	v_mfma_f32_16x16x32_bf16 v[82:85], v[134:137], v[240:243], v[82:85]
	v_mfma_f32_16x16x32_bf16 v[82:85], v[130:133], v[214:217], v[82:85]
	s_barrier
	s_setprio 0
	ds_read_b128 v[182:185], v180 offset:16384
	ds_read_b128 v[186:189], v180 offset:17408
	ds_read_b128 v[190:193], v180 offset:18432
	ds_read_b128 v[202:205], v180 offset:19456
	ds_read_b128 v[206:209], v180 offset:20480
	ds_read_b128 v[210:213], v180 offset:21504
	ds_read_b128 v[214:217], v180 offset:22528
	ds_read_b128 v[240:243], v180 offset:23552
	s_mov_b32 m0, s42
	s_nop 0
	global_load_lds_dwordx4 v167, s[58:59]
	s_add_u32 s44, s58, s14
	s_mov_b32 m0, s43
	s_nop 0
	global_load_lds_dwordx4 v175, s[58:59]
	s_addc_u32 s45, s59, 0
	s_mov_b32 m0, s46
	s_nop 0
	global_load_lds_dwordx4 v167, s[44:45]
	s_nop 0
	s_mov_b32 m0, s50
	s_nop 0
	global_load_lds_dwordx4 v175, s[44:45]
	s_nop 0
	s_mov_b32 m0, s17
	s_nop 0
	global_load_lds_dwordx4 v165, s[60:61]
	s_nop 0
	s_mov_b32 m0, s53
	s_nop 0
	global_load_lds_dwordx4 v171, s[60:61]
	s_waitcnt vmcnt(8)
	s_waitcnt lgkmcnt(0)
	s_setprio 1
	s_barrier
	v_mfma_f32_16x16x32_bf16 v[62:65], v[130:133], v[182:185], v[62:65]
	v_mfma_f32_16x16x32_bf16 v[62:65], v[134:137], v[186:189], v[62:65]
	v_mfma_f32_16x16x32_bf16 v[58:61], v[142:145], v[186:189], v[58:61]
	v_mfma_f32_16x16x32_bf16 v[58:61], v[138:141], v[182:185], v[58:61]
	v_mfma_f32_16x16x32_bf16 v[54:57], v[146:149], v[182:185], v[54:57]
	v_mfma_f32_16x16x32_bf16 v[54:57], v[150:153], v[186:189], v[54:57]
	v_mfma_f32_16x16x32_bf16 v[50:53], v[158:161], v[186:189], v[50:53]
	v_mfma_f32_16x16x32_bf16 v[50:53], v[154:157], v[182:185], v[50:53]
	v_mfma_f32_16x16x32_bf16 v[30:33], v[154:157], v[190:193], v[30:33]
	v_mfma_f32_16x16x32_bf16 v[30:33], v[158:161], v[202:205], v[30:33]
	v_mfma_f32_16x16x32_bf16 v[38:41], v[150:153], v[202:205], v[38:41]
	v_mfma_f32_16x16x32_bf16 v[38:41], v[146:149], v[190:193], v[38:41]
	v_mfma_f32_16x16x32_bf16 v[42:45], v[138:141], v[190:193], v[42:45]
	v_mfma_f32_16x16x32_bf16 v[42:45], v[142:145], v[202:205], v[42:45]
	v_mfma_f32_16x16x32_bf16 v[46:49], v[134:137], v[202:205], v[46:49]
	v_mfma_f32_16x16x32_bf16 v[46:49], v[130:133], v[190:193], v[46:49]
	v_mfma_f32_16x16x32_bf16 v[34:37], v[130:133], v[206:209], v[34:37]
	v_mfma_f32_16x16x32_bf16 v[34:37], v[134:137], v[210:213], v[34:37]
	v_mfma_f32_16x16x32_bf16 v[26:29], v[142:145], v[210:213], v[26:29]
	v_mfma_f32_16x16x32_bf16 v[26:29], v[138:141], v[206:209], v[26:29]
	v_mfma_f32_16x16x32_bf16 v[22:25], v[146:149], v[206:209], v[22:25]
	v_mfma_f32_16x16x32_bf16 v[22:25], v[150:153], v[210:213], v[22:25]
	v_mfma_f32_16x16x32_bf16 v[14:17], v[158:161], v[210:213], v[14:17]
	v_mfma_f32_16x16x32_bf16 v[14:17], v[154:157], v[206:209], v[14:17]
	v_mfma_f32_16x16x32_bf16 v[2:5], v[154:157], v[214:217], v[2:5]
	v_mfma_f32_16x16x32_bf16 v[2:5], v[158:161], v[240:243], v[2:5]
	v_mfma_f32_16x16x32_bf16 v[6:9], v[150:153], v[240:243], v[6:9]
	v_mfma_f32_16x16x32_bf16 v[6:9], v[146:149], v[214:217], v[6:9]
	v_mfma_f32_16x16x32_bf16 v[10:13], v[138:141], v[214:217], v[10:13]
	v_mfma_f32_16x16x32_bf16 v[10:13], v[142:145], v[240:243], v[10:13]
	v_mfma_f32_16x16x32_bf16 v[18:21], v[134:137], v[240:243], v[18:21]
	v_mfma_f32_16x16x32_bf16 v[18:21], v[130:133], v[214:217], v[18:21]
	s_barrier
; #define PG8_STAGE(bufoff, gbase, voff) do { _Pragma("unroll") for (int _i = 0; _i < 2; ++_i) { \
;         const unsigned _m0 = ldsb + (unsigned)((bufoff) + _i * 8192); const char* _gb = (const char*)(gbase); \
;         asm volatile("s_mov_b32 m0, %0\n\ts_nop 0\n\tglobal_load_lds_dwordx4 %1, %2" :: "s"(_m0), "v"((voff)[_i]), "s"(_gb) : "m0", "memory"); } } while (0)
; #define PG8_LDA(dst, b, h) do { _Pragma("unroll") for (int m = 0; m < 4; ++m) _Pragma("unroll") for (int k = 0; k < 2; ++k) dst[m][k] = *(const LAS bf16x8*)(lds + PG8_SA(b, h) + aoff + m * 2048 + k * 1024); } while (0)
; #define PG8_LDB(dst, b, h) do { _Pragma("unroll") for (int n = 0; n < 2; ++n) _Pragma("unroll") for (int k = 0; k < 2; ++k) dst[n][k] = *(const LAS bf16x8*)(lds + PG8_SB(b, h) + boff + n * 2048 + k * 1024); } while (0)
; #define PG8_MMA(ai, bj, At, Bt) do { __builtin_amdgcn_s_setprio(1); _Pragma("unroll") for (int m = 0; m < 4; ++m) _Pragma("unroll") for (int n = 0; n < 2; ++n) _Pragma("unroll") for (int k = 0; k < 2; ++k) \
;         acc[ai][bj][m][n] = __builtin_amdgcn_mfma_f32_16x16x32_bf16(Bt[n][k], At[m][k], acc[ai][bj][m][n], 0, 0, 0); __builtin_amdgcn_s_setprio(0); } while (0)
; #define PG8_WAIT_V(n) asm volatile("s_waitcnt vmcnt(" #n ")" ::: "memory")
; #define PG8_WAIT_L(n) asm volatile("s_waitcnt lgkmcnt(" #n ")" ::: "memory")
; #define PG8_BAR __builtin_amdgcn_s_barrier()
; #define PG8_SCHED __builtin_amdgcn_sched_barrier(0)
; template <class Epi, bool ALIGN_EPI>
; __device__ __forceinline__ void gemm_phase(LAS unsigned char* lds, const Gemm g, const StaticOrder& S, const Epi& E) {
;     ...
;             PG8_LDB(B0, 1, 0); PG8_LDB(B1, 1, 1); PG8_SCHED; PG8_LDA(At, 1, 0); PG8_STAGE(PG8_SA(0, 1), a2 + hstepA, voffA);
;             PG8_WAIT_V(8); PG8_WAIT_L(0); PG8_BAR; PG8_MMA(0, 0, At, B0); PG8_MMA(0, 1, At, B1); PG8_BAR; PG8_SCHED;
;             PG8_LDA(At, 1, 1); PG8_STAGE(PG8_SB(1, 0), b3, voffB); PG8_STAGE(PG8_SB(1, 1), b3 + hstepB, voffB); PG8_STAGE(PG8_SA(1, 0), a3, voffA);
;             PG8_WAIT_V(8); PG8_WAIT_L(0); PG8_BAR; PG8_MMA(1, 0, At, B0); PG8_MMA(1, 1, At, B1); PG8_BAR; PG8_SCHED;
;         }
;         if constexpr (ALIGN_EPI) { if (wr == 0) PG8_BAR; }
	s_setprio 0
	v_add_u32_e32 v0, 0x18000, v179
	ds_read_b128 v[130:133], v0
	ds_read_b128 v[134:137], v0 offset:1024
	ds_read_b128 v[138:141], v0 offset:2048
	ds_read_b128 v[142:145], v0 offset:3072
	v_add_u32_e32 v0, 0x1c000, v179
	ds_read_b128 v[146:149], v0
	ds_read_b128 v[150:153], v0 offset:1024
	ds_read_b128 v[154:157], v0 offset:2048
	ds_read_b128 v[158:161], v0 offset:3072
	ds_read_b128 v[182:185], v180 offset:32768
	ds_read_b128 v[186:189], v180 offset:33792
	ds_read_b128 v[190:193], v180 offset:34816
	ds_read_b128 v[202:205], v180 offset:35840
	ds_read_b128 v[206:209], v180 offset:36864
	ds_read_b128 v[210:213], v180 offset:37888
	ds_read_b128 v[214:217], v180 offset:38912
	ds_read_b128 v[240:243], v180 offset:39936
	s_add_u32 s60, s60, 0x40000
	s_addc_u32 s61, s61, 0
	s_mov_b32 m0, s65
	s_nop 0
	global_load_lds_dwordx4 v165, s[60:61]
	s_nop 0
	s_mov_b32 m0, s67
	s_nop 0
	global_load_lds_dwordx4 v171, s[60:61]
	s_waitcnt vmcnt(8)
	s_waitcnt lgkmcnt(0)
	s_setprio 1
	s_barrier
	v_mfma_f32_16x16x32_bf16 v[126:129], v[130:133], v[182:185], v[126:129]
	v_mfma_f32_16x16x32_bf16 v[126:129], v[134:137], v[186:189], v[126:129]
	v_mfma_f32_16x16x32_bf16 v[122:125], v[142:145], v[186:189], v[122:125]
	v_mfma_f32_16x16x32_bf16 v[122:125], v[138:141], v[182:185], v[122:125]
	v_mfma_f32_16x16x32_bf16 v[118:121], v[146:149], v[182:185], v[118:121]
	v_mfma_f32_16x16x32_bf16 v[118:121], v[150:153], v[186:189], v[118:121]
	v_mfma_f32_16x16x32_bf16 v[110:113], v[158:161], v[186:189], v[110:113]
	v_mfma_f32_16x16x32_bf16 v[110:113], v[154:157], v[182:185], v[110:113]
	v_mfma_f32_16x16x32_bf16 v[94:97], v[154:157], v[190:193], v[94:97]
	v_mfma_f32_16x16x32_bf16 v[94:97], v[158:161], v[202:205], v[94:97]
	v_mfma_f32_16x16x32_bf16 v[102:105], v[150:153], v[202:205], v[102:105]
	v_mfma_f32_16x16x32_bf16 v[102:105], v[146:149], v[190:193], v[102:105]
	v_mfma_f32_16x16x32_bf16 v[106:109], v[138:141], v[190:193], v[106:109]
	v_mfma_f32_16x16x32_bf16 v[106:109], v[142:145], v[202:205], v[106:109]
	v_mfma_f32_16x16x32_bf16 v[114:117], v[134:137], v[202:205], v[114:117]
	v_mfma_f32_16x16x32_bf16 v[114:117], v[130:133], v[190:193], v[114:117]
	v_mfma_f32_16x16x32_bf16 v[98:101], v[130:133], v[206:209], v[98:101]
	v_mfma_f32_16x16x32_bf16 v[98:101], v[134:137], v[210:213], v[98:101]
	v_mfma_f32_16x16x32_bf16 v[90:93], v[142:145], v[210:213], v[90:93]
	v_mfma_f32_16x16x32_bf16 v[90:93], v[138:141], v[206:209], v[90:93]
	v_mfma_f32_16x16x32_bf16 v[86:89], v[146:149], v[206:209], v[86:89]
	v_mfma_f32_16x16x32_bf16 v[86:89], v[150:153], v[210:213], v[86:89]
	v_mfma_f32_16x16x32_bf16 v[78:81], v[158:161], v[210:213], v[78:81]
	v_mfma_f32_16x16x32_bf16 v[78:81], v[154:157], v[206:209], v[78:81]
	v_mfma_f32_16x16x32_bf16 v[66:69], v[154:157], v[214:217], v[66:69]
	v_mfma_f32_16x16x32_bf16 v[66:69], v[158:161], v[240:243], v[66:69]
	v_mfma_f32_16x16x32_bf16 v[70:73], v[150:153], v[240:243], v[70:73]
	v_mfma_f32_16x16x32_bf16 v[70:73], v[146:149], v[214:217], v[70:73]
	v_mfma_f32_16x16x32_bf16 v[74:77], v[138:141], v[214:217], v[74:77]
	v_mfma_f32_16x16x32_bf16 v[74:77], v[142:145], v[240:243], v[74:77]
	v_mfma_f32_16x16x32_bf16 v[82:85], v[134:137], v[240:243], v[82:85]
	v_mfma_f32_16x16x32_bf16 v[82:85], v[130:133], v[214:217], v[82:85]
	s_barrier
	s_setprio 0
	ds_read_b128 v[182:185], v180 offset:49152
	ds_read_b128 v[186:189], v180 offset:50176
	ds_read_b128 v[190:193], v180 offset:51200
	ds_read_b128 v[202:205], v180 offset:52224
	ds_read_b128 v[206:209], v180 offset:53248
	ds_read_b128 v[210:213], v180 offset:54272
	ds_read_b128 v[214:217], v180 offset:55296
	ds_read_b128 v[240:243], v180 offset:56320
	s_add_u32 s58, s58, 0x80
	s_addc_u32 s59, s59, 0
	s_mov_b32 m0, s89
	s_nop 0
	global_load_lds_dwordx4 v167, s[58:59]
	s_add_u32 s44, s44, 0x80
	s_mov_b32 m0, s95
	s_nop 0
	global_load_lds_dwordx4 v175, s[58:59]
	s_addc_u32 s45, s45, 0
	s_mov_b32 m0, s26
	s_nop 0
	global_load_lds_dwordx4 v167, s[44:45]
	s_nop 0
	s_mov_b32 m0, s27
	s_nop 0
	global_load_lds_dwordx4 v175, s[44:45]
	s_nop 0
	s_mov_b32 m0, s36
	s_nop 0
	global_load_lds_dwordx4 v165, s[56:57]
	s_nop 0
	s_mov_b32 m0, s37
	s_nop 0
	global_load_lds_dwordx4 v171, s[56:57]
	s_waitcnt vmcnt(8)
	s_waitcnt lgkmcnt(0)
	s_setprio 1
	s_barrier
	v_mfma_f32_16x16x32_bf16 v[62:65], v[130:133], v[182:185], v[62:65]
	v_mfma_f32_16x16x32_bf16 v[62:65], v[134:137], v[186:189], v[62:65]
	v_mfma_f32_16x16x32_bf16 v[58:61], v[142:145], v[186:189], v[58:61]
	v_mfma_f32_16x16x32_bf16 v[58:61], v[138:141], v[182:185], v[58:61]
	v_mfma_f32_16x16x32_bf16 v[54:57], v[146:149], v[182:185], v[54:57]
	v_mfma_f32_16x16x32_bf16 v[54:57], v[150:153], v[186:189], v[54:57]
	v_mfma_f32_16x16x32_bf16 v[50:53], v[158:161], v[186:189], v[50:53]
	v_mfma_f32_16x16x32_bf16 v[50:53], v[154:157], v[182:185], v[50:53]
	v_mfma_f32_16x16x32_bf16 v[30:33], v[154:157], v[190:193], v[30:33]
	v_mfma_f32_16x16x32_bf16 v[30:33], v[158:161], v[202:205], v[30:33]
	v_mfma_f32_16x16x32_bf16 v[38:41], v[150:153], v[202:205], v[38:41]
	v_mfma_f32_16x16x32_bf16 v[38:41], v[146:149], v[190:193], v[38:41]
	v_mfma_f32_16x16x32_bf16 v[42:45], v[138:141], v[190:193], v[42:45]
	v_mfma_f32_16x16x32_bf16 v[42:45], v[142:145], v[202:205], v[42:45]
	v_mfma_f32_16x16x32_bf16 v[46:49], v[134:137], v[202:205], v[46:49]
	v_mfma_f32_16x16x32_bf16 v[46:49], v[130:133], v[190:193], v[46:49]
	v_mfma_f32_16x16x32_bf16 v[34:37], v[130:133], v[206:209], v[34:37]
	v_mfma_f32_16x16x32_bf16 v[34:37], v[134:137], v[210:213], v[34:37]
	v_mfma_f32_16x16x32_bf16 v[26:29], v[142:145], v[210:213], v[26:29]
	v_mfma_f32_16x16x32_bf16 v[26:29], v[138:141], v[206:209], v[26:29]
	v_mfma_f32_16x16x32_bf16 v[22:25], v[146:149], v[206:209], v[22:25]
	v_mfma_f32_16x16x32_bf16 v[22:25], v[150:153], v[210:213], v[22:25]
	v_mfma_f32_16x16x32_bf16 v[14:17], v[158:161], v[210:213], v[14:17]
	v_mfma_f32_16x16x32_bf16 v[14:17], v[154:157], v[206:209], v[14:17]
	v_mfma_f32_16x16x32_bf16 v[2:5], v[154:157], v[214:217], v[2:5]
	v_mfma_f32_16x16x32_bf16 v[2:5], v[158:161], v[240:243], v[2:5]
	v_mfma_f32_16x16x32_bf16 v[6:9], v[150:153], v[240:243], v[6:9]
	v_mfma_f32_16x16x32_bf16 v[6:9], v[146:149], v[214:217], v[6:9]
	v_mfma_f32_16x16x32_bf16 v[10:13], v[138:141], v[214:217], v[10:13]
	v_mfma_f32_16x16x32_bf16 v[10:13], v[142:145], v[240:243], v[10:13]
	v_mfma_f32_16x16x32_bf16 v[18:21], v[134:137], v[240:243], v[18:21]
	v_mfma_f32_16x16x32_bf16 v[18:21], v[130:133], v[214:217], v[18:21]
	s_barrier
	s_setprio 0
	s_add_u32 s4, s4, 0x100
	s_addc_u32 s5, s5, 0
	s_add_u32 s0, s0, 0x100
	s_addc_u32 s1, s1, 0
	s_cmp_ge_u32 s55, s31
	s_mov_b32 s44, s55
	s_cbranch_scc0 .LBB0_271
	v_readlane_b32 s0, v254, 44
	v_readlane_b32 s1, v254, 45
	s_and_b64 vcc, exec, s[0:1]
	s_cbranch_vccz .LBB0_274
	s_barrier

; #define PG8_STAGE(bufoff, gbase, voff) do { _Pragma("unroll") for (int _i = 0; _i < 2; ++_i) { \
;         const unsigned _m0 = ldsb + (unsigned)((bufoff) + _i * 8192); const char* _gb = (const char*)(gbase); \
;         asm volatile("s_mov_b32 m0, %0\n\ts_nop 0\n\tglobal_load_lds_dwordx4 %1, %2" :: "s"(_m0), "v"((voff)[_i]), "s"(_gb) : "m0", "memory"); } } while (0)
; #define PG8_LDA(dst, b, h) do { _Pragma("unroll") for (int m = 0; m < 4; ++m) _Pragma("unroll") for (int k = 0; k < 2; ++k) dst[m][k] = *(const LAS bf16x8*)(lds + PG8_SA(b, h) + aoff + m * 2048 + k * 1024); } while (0)
; #define PG8_WAIT_V(n) asm volatile("s_waitcnt vmcnt(" #n ")" ::: "memory")
; #define PG8_WAIT_L(n) asm volatile("s_waitcnt lgkmcnt(" #n ")" ::: "memory")
;     __device__ bool next(int i, Unit& u) const {
;         const long L = (long)i * G + c; if (L >= nwg) return false;
;         int wgid = (int)L; { const int q = nwg / NXCD, r = nwg % NXCD, xcd = wgid % NXCD, off = wgid / NXCD; wgid = (xcd < r ? xcd * (q + 1) : r * (q + 1) + (xcd - r) * q) + off; }
; template <class Epi, bool ALIGN_EPI>
; __device__ __forceinline__ void gemm_phase(LAS unsigned char* lds, const Gemm g, const StaticOrder& S, const Epi& E) {
;     ...
;         const bool has_next = S.next(ui + 1, nxt);
;         const char* nA = has_next ? (const char*)g.A + (size_t)nxt.pm * tstepA + (size_t)nxt.pn * g.a_pn_off * 2 + (size_t)(nxt.pm >> 4) * g.a_adj : cA; const char* nB = has_next ? (const char*)g.Bt + (size_t)nxt.pn * tstepB : cB;
;         for (int t = 0; t < nt; t += 2) {
;             const bool last = (t == nt - 2);
;             const char* a1 = cA + (size_t)(t + 1) * kstep;
;             const char* a2 = last ? nA : cA + (size_t)(t + 2) * kstep; const char* b2 = last ? nB : cB + (size_t)(t + 2) * kstep;
;             const char* a3 = a2 + kstep; const char* b3 = b2 + kstep;
;             PG8_LDB(B0, 0, 0); PG8_LDB(B1, 0, 1); PG8_SCHED; PG8_LDA(At, 0, 0); PG8_STAGE(PG8_SA(1, 1), a1 + hstepA, voffA);
;             PG8_WAIT_V(8); PG8_WAIT_L(0); PG8_BAR; PG8_MMA(0, 0, At, B0); PG8_MMA(0, 1, At, B1); PG8_BAR; PG8_SCHED;
;             PG8_LDA(At, 0, 1); PG8_STAGE(PG8_SB(0, 0), b2, voffB); PG8_STAGE(PG8_SB(0, 1), b2 + hstepB, voffB); PG8_STAGE(PG8_SA(0, 0), a2, voffA);
;             PG8_WAIT_V(8); PG8_WAIT_L(0); PG8_BAR; PG8_MMA(1, 0, At, B0); PG8_MMA(1, 1, At, B1); PG8_BAR; PG8_SCHED;
.LBB0_305:
	s_add_u32 s41, s56, 0x100
	s_addc_u32 s49, s57, 0
	s_add_u32 s92, s58, 0x40080
	s_addc_u32 s93, s59, 0
	s_mov_b32 s50, -2
	s_add_u32 s30, s92, 0xfffc0080
	s_addc_u32 s31, s93, -1
	s_cmp_eq_u32 s50, 12
	s_cselect_b32 s60, s5, s30
	s_cselect_b32 s61, s4, s31
	s_cselect_b32 s58, s37, s41
	s_cselect_b32 s59, s35, s49
	s_add_u32 s56, s60, 0x80
	s_addc_u32 s57, s61, 0
	s_mov_b32 m0, s67
	s_nop 0
	global_load_lds_dwordx4 v0, s[92:93]
	s_nop 0
	s_mov_b32 m0, s65
	s_nop 0
	global_load_lds_dwordx4 v181, s[92:93]
	s_waitcnt vmcnt(8)
	s_waitcnt lgkmcnt(0)
	s_setprio 1
	s_barrier
	v_mfma_f32_16x16x32_bf16 v[142:145], v[74:77], v[162:165], 0
	v_mfma_f32_16x16x32_bf16 v[142:145], v[94:97], v[166:169], v[142:145]
	v_mfma_f32_16x16x32_bf16 v[138:141], v[134:137], v[166:169], 0
	v_mfma_f32_16x16x32_bf16 v[138:141], v[114:117], v[162:165], v[138:141]
	v_mfma_f32_16x16x32_bf16 v[130:133], v[146:149], v[162:165], 0
	v_mfma_f32_16x16x32_bf16 v[130:133], v[150:153], v[166:169], v[130:133]
	v_mfma_f32_16x16x32_bf16 v[126:129], v[158:161], v[166:169], 0
	v_mfma_f32_16x16x32_bf16 v[126:129], v[154:157], v[162:165], v[126:129]
	v_mfma_f32_16x16x32_bf16 v[106:109], v[154:157], v[170:173], 0
	v_mfma_f32_16x16x32_bf16 v[106:109], v[158:161], v[174:177], v[106:109]
	v_mfma_f32_16x16x32_bf16 v[110:113], v[150:153], v[174:177], 0
	v_mfma_f32_16x16x32_bf16 v[110:113], v[146:149], v[170:173], v[110:113]
	v_mfma_f32_16x16x32_bf16 v[118:121], v[114:117], v[170:173], 0
	v_mfma_f32_16x16x32_bf16 v[118:121], v[134:137], v[174:177], v[118:121]
	v_mfma_f32_16x16x32_bf16 v[122:125], v[94:97], v[174:177], 0
	v_mfma_f32_16x16x32_bf16 v[122:125], v[74:77], v[170:173], v[122:125]
	v_mfma_f32_16x16x32_bf16 v[102:105], v[74:77], v[188:191], 0
	v_mfma_f32_16x16x32_bf16 v[102:105], v[94:97], v[202:205], v[102:105]
	v_mfma_f32_16x16x32_bf16 v[98:101], v[134:137], v[202:205], 0
	v_mfma_f32_16x16x32_bf16 v[98:101], v[114:117], v[188:191], v[98:101]
	v_mfma_f32_16x16x32_bf16 v[90:93], v[146:149], v[188:191], 0
	v_mfma_f32_16x16x32_bf16 v[90:93], v[150:153], v[202:205], v[90:93]
	v_mfma_f32_16x16x32_bf16 v[86:89], v[158:161], v[202:205], 0
	v_mfma_f32_16x16x32_bf16 v[86:89], v[154:157], v[188:191], v[86:89]
	v_mfma_f32_16x16x32_bf16 v[66:69], v[154:157], v[206:209], 0
	v_mfma_f32_16x16x32_bf16 v[66:69], v[158:161], v[210:213], v[66:69]
	v_mfma_f32_16x16x32_bf16 v[70:73], v[150:153], v[210:213], 0
	v_mfma_f32_16x16x32_bf16 v[70:73], v[146:149], v[206:209], v[70:73]
	v_mfma_f32_16x16x32_bf16 v[78:81], v[114:117], v[206:209], 0
	v_mfma_f32_16x16x32_bf16 v[78:81], v[134:137], v[210:213], v[78:81]
	v_mfma_f32_16x16x32_bf16 v[82:85], v[94:97], v[210:213], 0
	v_mfma_f32_16x16x32_bf16 v[82:85], v[74:77], v[206:209], v[82:85]
	s_barrier
	s_setprio 0
	ds_read_b128 v[162:165], v186 offset:16384
	ds_read_b128 v[166:169], v186 offset:17408
	ds_read_b128 v[170:173], v186 offset:18432
	ds_read_b128 v[174:177], v186 offset:19456
	ds_read_b128 v[188:191], v186 offset:20480
	ds_read_b128 v[202:205], v186 offset:21504
	ds_read_b128 v[206:209], v186 offset:22528
	ds_read_b128 v[210:213], v186 offset:23552
	s_mov_b32 m0, s29
	s_nop 0
	global_load_lds_dwordx4 v180, s[58:59]
	s_add_u32 s30, s58, 0x40000
	s_mov_b32 m0, s42
	s_nop 0
	global_load_lds_dwordx4 v182, s[58:59]
	s_addc_u32 s31, s59, 0
	s_mov_b32 m0, s43
	s_nop 0
	global_load_lds_dwordx4 v180, s[30:31]
	s_nop 0
	s_mov_b32 m0, s44
	s_nop 0
	global_load_lds_dwordx4 v182, s[30:31]
	s_nop 0
	s_mov_b32 m0, s15
	s_nop 0
	global_load_lds_dwordx4 v0, s[60:61]
	s_nop 0
	s_mov_b32 m0, s45
	s_nop 0
	global_load_lds_dwordx4 v181, s[60:61]
	s_mul_i32 s4, s85, s27
	s_mul_hi_u32 s5, s85, s87
	s_add_i32 s5, s5, s4
	s_mul_i32 s4, s85, s87
	s_add_u32 s4, s4, s16
	s_addc_u32 s5, s5, s68
	v_mov_b64_e32 v[192:193], s[46:47]
	v_cmp_lt_i64_e64 s[8:9], s[4:5], v[192:193]
	s_ashr_i32 s5, s4, 31
	s_lshr_b32 s5, s5, 29
	s_add_i32 s5, s4, s5
	s_ashr_i32 s90, s5, 3
	s_and_b32 s5, s5, -8
	s_sub_i32 s4, s4, s5
	s_lshr_b32 s5, s4, 31
	s_or_b32 s5, s78, s5
	s_mul_i32 s4, s5, s4
	s_add_i32 s4, s4, s90
	s_abs_i32 s90, s4
	v_readlane_b32 s91, v254, 48
	s_mul_hi_u32 s91, s90, s91
	s_mul_i32 s34, s91, s26
	s_sub_i32 s90, s90, s34
	s_ashr_i32 s5, s4, 31
	s_add_i32 s34, s91, 1
	s_sub_i32 s35, s90, s26
	s_cmp_ge_u32 s90, s26
	s_cselect_b32 s91, s34, s91
	s_cselect_b32 s90, s35, s90
	s_waitcnt vmcnt(8)
	s_waitcnt lgkmcnt(0)
	s_setprio 1
	s_barrier
	v_mfma_f32_16x16x32_bf16 v[62:65], v[74:77], v[162:165], 0
	v_mfma_f32_16x16x32_bf16 v[62:65], v[94:97], v[166:169], v[62:65]
	v_mfma_f32_16x16x32_bf16 v[58:61], v[134:137], v[166:169], 0
	v_mfma_f32_16x16x32_bf16 v[58:61], v[114:117], v[162:165], v[58:61]
	v_mfma_f32_16x16x32_bf16 v[54:57], v[146:149], v[162:165], 0
	v_mfma_f32_16x16x32_bf16 v[54:57], v[150:153], v[166:169], v[54:57]
	v_mfma_f32_16x16x32_bf16 v[50:53], v[158:161], v[166:169], 0
	v_mfma_f32_16x16x32_bf16 v[50:53], v[154:157], v[162:165], v[50:53]
	v_mfma_f32_16x16x32_bf16 v[34:37], v[154:157], v[170:173], 0
	v_mfma_f32_16x16x32_bf16 v[34:37], v[158:161], v[174:177], v[34:37]
	v_mfma_f32_16x16x32_bf16 v[38:41], v[150:153], v[174:177], 0
	v_mfma_f32_16x16x32_bf16 v[38:41], v[146:149], v[170:173], v[38:41]
	v_mfma_f32_16x16x32_bf16 v[42:45], v[114:117], v[170:173], 0
	v_mfma_f32_16x16x32_bf16 v[42:45], v[134:137], v[174:177], v[42:45]
	v_mfma_f32_16x16x32_bf16 v[46:49], v[94:97], v[174:177], 0
	v_mfma_f32_16x16x32_bf16 v[46:49], v[74:77], v[170:173], v[46:49]
	v_mfma_f32_16x16x32_bf16 v[30:33], v[74:77], v[188:191], 0
	v_mfma_f32_16x16x32_bf16 v[30:33], v[94:97], v[202:205], v[30:33]
	v_mfma_f32_16x16x32_bf16 v[26:29], v[134:137], v[202:205], 0
	v_mfma_f32_16x16x32_bf16 v[26:29], v[114:117], v[188:191], v[26:29]
	v_mfma_f32_16x16x32_bf16 v[22:25], v[146:149], v[188:191], 0
	v_mfma_f32_16x16x32_bf16 v[22:25], v[150:153], v[202:205], v[22:25]
	v_mfma_f32_16x16x32_bf16 v[18:21], v[158:161], v[202:205], 0
	v_mfma_f32_16x16x32_bf16 v[18:21], v[154:157], v[188:191], v[18:21]
	v_mfma_f32_16x16x32_bf16 v[2:5], v[154:157], v[206:209], 0
	v_mfma_f32_16x16x32_bf16 v[2:5], v[158:161], v[210:213], v[2:5]
	v_mfma_f32_16x16x32_bf16 v[6:9], v[150:153], v[210:213], 0
	v_mfma_f32_16x16x32_bf16 v[6:9], v[146:149], v[206:209], v[6:9]
	v_mfma_f32_16x16x32_bf16 v[10:13], v[114:117], v[206:209], 0
	v_mfma_f32_16x16x32_bf16 v[10:13], v[134:137], v[210:213], v[10:13]
	v_mfma_f32_16x16x32_bf16 v[14:17], v[94:97], v[210:213], 0
	v_mfma_f32_16x16x32_bf16 v[14:17], v[74:77], v[206:209], v[14:17]
	s_barrier
; #define PG8_STAGE(bufoff, gbase, voff) do { _Pragma("unroll") for (int _i = 0; _i < 2; ++_i) { \
;         const unsigned _m0 = ldsb + (unsigned)((bufoff) + _i * 8192); const char* _gb = (const char*)(gbase); \
;         asm volatile("s_mov_b32 m0, %0\n\ts_nop 0\n\tglobal_load_lds_dwordx4 %1, %2" :: "s"(_m0), "v"((voff)[_i]), "s"(_gb) : "m0", "memory"); } } while (0)
; #define PG8_LDA(dst, b, h) do { _Pragma("unroll") for (int m = 0; m < 4; ++m) _Pragma("unroll") for (int k = 0; k < 2; ++k) dst[m][k] = *(const LAS bf16x8*)(lds + PG8_SA(b, h) + aoff + m * 2048 + k * 1024); } while (0)
; #define PG8_LDB(dst, b, h) do { _Pragma("unroll") for (int n = 0; n < 2; ++n) _Pragma("unroll") for (int k = 0; k < 2; ++k) dst[n][k] = *(const LAS bf16x8*)(lds + PG8_SB(b, h) + boff + n * 2048 + k * 1024); } while (0)
; #define PG8_MMA(ai, bj, At, Bt) do { __builtin_amdgcn_s_setprio(1); _Pragma("unroll") for (int m = 0; m < 4; ++m) _Pragma("unroll") for (int n = 0; n < 2; ++n) _Pragma("unroll") for (int k = 0; k < 2; ++k) \
;         acc[ai][bj][m][n] = __builtin_amdgcn_mfma_f32_16x16x32_bf16(Bt[n][k], At[m][k], acc[ai][bj][m][n], 0, 0, 0); __builtin_amdgcn_s_setprio(0); } while (0)
; #define PG8_WAIT_V(n) asm volatile("s_waitcnt vmcnt(" #n ")" ::: "memory")
;     __device__ bool next(int i, Unit& u) const {
;     ...
;         int wgid = (int)L; { const int q = nwg / NXCD, r = nwg % NXCD, xcd = wgid % NXCD, off = wgid / NXCD; wgid = (xcd < r ? xcd * (q + 1) : r * (q + 1) + (xcd - r) * q) + off; }
;         const int nig = WGM * nN, gid = wgid / nig, fm = gid * WGM, gsz = (nM - fm) < WGM ? (nM - fm) : WGM;
;         u.pm = fm + ((wgid % nig) % gsz); u.pn = (wgid % nig) / gsz; return true;
; template <class Epi, bool ALIGN_EPI>
; __device__ __forceinline__ void gemm_phase(LAS unsigned char* lds, const Gemm g, const StaticOrder& S, const Epi& E) {
;     ...
;             PG8_LDB(B0, 1, 0); PG8_LDB(B1, 1, 1); PG8_SCHED; PG8_LDA(At, 1, 0); PG8_STAGE(PG8_SA(0, 1), a2 + hstepA, voffA);
;             PG8_WAIT_V(8); PG8_WAIT_L(0); PG8_BAR; PG8_MMA(0, 0, At, B0); PG8_MMA(0, 1, At, B1); PG8_BAR; PG8_SCHED;
;             PG8_LDA(At, 1, 1); PG8_STAGE(PG8_SB(1, 0), b3, voffB); PG8_STAGE(PG8_SB(1, 1), b3 + hstepB, voffB); PG8_STAGE(PG8_SA(1, 0), a3, voffA);
;             PG8_WAIT_V(8); PG8_WAIT_L(0); PG8_BAR; PG8_MMA(1, 0, At, B0); PG8_MMA(1, 1, At, B1); PG8_BAR; PG8_SCHED;
	s_setprio 0
	v_add_u32_e32 v134, 0x18000, v185
	v_add_u32_e32 v158, 0x1c000, v185
	ds_read_b128 v[74:77], v134
	ds_read_b128 v[94:97], v134 offset:1024
	ds_read_b128 v[114:117], v134 offset:2048
	ds_read_b128 v[134:137], v134 offset:3072
	ds_read_b128 v[146:149], v158
	ds_read_b128 v[150:153], v158 offset:1024
	ds_read_b128 v[154:157], v158 offset:2048
	ds_read_b128 v[158:161], v158 offset:3072
	ds_read_b128 v[162:165], v186 offset:32768
	ds_read_b128 v[166:169], v186 offset:33792
	ds_read_b128 v[170:173], v186 offset:34816
	ds_read_b128 v[174:177], v186 offset:35840
	ds_read_b128 v[188:191], v186 offset:36864
	ds_read_b128 v[202:205], v186 offset:37888
	ds_read_b128 v[206:209], v186 offset:38912
	ds_read_b128 v[210:213], v186 offset:39936
	s_add_u32 s30, s60, 0x40000
	s_addc_u32 s31, s61, 0
	s_mov_b32 m0, s55
	s_nop 0
	global_load_lds_dwordx4 v0, s[30:31]
	s_nop 0
	s_mov_b32 m0, s88
	s_nop 0
	global_load_lds_dwordx4 v181, s[30:31]
	s_add_i32 s34, s91, 1
	s_cmp_ge_u32 s90, s26
	s_cselect_b32 s90, s34, s91
	s_xor_b32 s90, s90, s5
	s_sub_i32 s5, s90, s5
	s_lshl_b32 s90, s5, 3
	s_sub_i32 s91, 0x80, s90
	s_min_i32 s91, s91, 8
	s_abs_i32 s34, s91
	v_cvt_f32_u32_e32 v192, s34
	s_sub_i32 s36, 0, s34
	s_mul_i32 s5, s5, s26
	s_sub_i32 s4, s4, s5
	v_rcp_iflag_f32_e32 v192, v192
	s_abs_i32 s35, s4
	s_xor_b32 s5, s4, s91
	s_ashr_i32 s5, s5, 31
	v_mul_f32_e32 v192, 0x4f7ffffe, v192
	v_cvt_u32_f32_e32 v192, v192
	s_nop 0
	v_readfirstlane_b32 s37, v192
	s_mul_i32 s36, s36, s37
	s_mul_hi_u32 s36, s37, s36
	s_add_i32 s37, s37, s36
	s_mul_hi_u32 s36, s35, s37
	s_mul_i32 s37, s36, s34
	s_sub_i32 s35, s35, s37
	s_waitcnt vmcnt(8)
	s_waitcnt lgkmcnt(0)
	s_setprio 1
	s_barrier
	v_mfma_f32_16x16x32_bf16 v[142:145], v[74:77], v[162:165], v[142:145]
	v_mfma_f32_16x16x32_bf16 v[142:145], v[94:97], v[166:169], v[142:145]
	v_mfma_f32_16x16x32_bf16 v[138:141], v[134:137], v[166:169], v[138:141]
	v_mfma_f32_16x16x32_bf16 v[138:141], v[114:117], v[162:165], v[138:141]
	v_mfma_f32_16x16x32_bf16 v[130:133], v[146:149], v[162:165], v[130:133]
	v_mfma_f32_16x16x32_bf16 v[130:133], v[150:153], v[166:169], v[130:133]
	v_mfma_f32_16x16x32_bf16 v[126:129], v[158:161], v[166:169], v[126:129]
	v_mfma_f32_16x16x32_bf16 v[126:129], v[154:157], v[162:165], v[126:129]
	v_mfma_f32_16x16x32_bf16 v[106:109], v[154:157], v[170:173], v[106:109]
	v_mfma_f32_16x16x32_bf16 v[106:109], v[158:161], v[174:177], v[106:109]
	v_mfma_f32_16x16x32_bf16 v[110:113], v[150:153], v[174:177], v[110:113]
	v_mfma_f32_16x16x32_bf16 v[110:113], v[146:149], v[170:173], v[110:113]
	v_mfma_f32_16x16x32_bf16 v[118:121], v[114:117], v[170:173], v[118:121]
	v_mfma_f32_16x16x32_bf16 v[118:121], v[134:137], v[174:177], v[118:121]
	v_mfma_f32_16x16x32_bf16 v[122:125], v[94:97], v[174:177], v[122:125]
	v_mfma_f32_16x16x32_bf16 v[122:125], v[74:77], v[170:173], v[122:125]
	v_mfma_f32_16x16x32_bf16 v[102:105], v[74:77], v[188:191], v[102:105]
	v_mfma_f32_16x16x32_bf16 v[102:105], v[94:97], v[202:205], v[102:105]
	v_mfma_f32_16x16x32_bf16 v[98:101], v[134:137], v[202:205], v[98:101]
	v_mfma_f32_16x16x32_bf16 v[98:101], v[114:117], v[188:191], v[98:101]
	v_mfma_f32_16x16x32_bf16 v[90:93], v[146:149], v[188:191], v[90:93]
	v_mfma_f32_16x16x32_bf16 v[90:93], v[150:153], v[202:205], v[90:93]
	v_mfma_f32_16x16x32_bf16 v[86:89], v[158:161], v[202:205], v[86:89]
	v_mfma_f32_16x16x32_bf16 v[86:89], v[154:157], v[188:191], v[86:89]
	v_mfma_f32_16x16x32_bf16 v[66:69], v[154:157], v[206:209], v[66:69]
	v_mfma_f32_16x16x32_bf16 v[66:69], v[158:161], v[210:213], v[66:69]
	v_mfma_f32_16x16x32_bf16 v[70:73], v[150:153], v[210:213], v[70:73]
	v_mfma_f32_16x16x32_bf16 v[70:73], v[146:149], v[206:209], v[70:73]
	v_mfma_f32_16x16x32_bf16 v[78:81], v[114:117], v[206:209], v[78:81]
	v_mfma_f32_16x16x32_bf16 v[78:81], v[134:137], v[210:213], v[78:81]
	v_mfma_f32_16x16x32_bf16 v[82:85], v[94:97], v[210:213], v[82:85]
	v_mfma_f32_16x16x32_bf16 v[82:85], v[74:77], v[206:209], v[82:85]
	s_barrier
	s_setprio 0
	ds_read_b128 v[162:165], v186 offset:49152
	ds_read_b128 v[166:169], v186 offset:50176
	ds_read_b128 v[170:173], v186 offset:51200
	ds_read_b128 v[174:177], v186 offset:52224
	ds_read_b128 v[188:191], v186 offset:53248
	ds_read_b128 v[202:205], v186 offset:54272
	ds_read_b128 v[206:209], v186 offset:55296
	ds_read_b128 v[210:213], v186 offset:56320
	s_add_u32 s30, s58, 0x80
	s_addc_u32 s31, s59, 0
	s_mov_b32 m0, s94
	s_nop 0
	global_load_lds_dwordx4 v180, s[30:31]
	s_nop 0
	s_mov_b32 m0, s95
	s_nop 0
	global_load_lds_dwordx4 v182, s[30:31]
	s_add_u32 s30, s58, 0x40080
	s_addc_u32 s31, s59, 0
	s_mov_b32 m0, s17
	s_nop 0
	global_load_lds_dwordx4 v180, s[30:31]
	s_nop 0
	s_mov_b32 m0, s53
	s_nop 0
	global_load_lds_dwordx4 v182, s[30:31]
	s_nop 0
	s_mov_b32 m0, s96
	s_nop 0
	global_load_lds_dwordx4 v0, s[56:57]
	s_nop 0
	s_mov_b32 m0, s97
	s_nop 0
	global_load_lds_dwordx4 v181, s[56:57]
	s_add_i32 s37, s36, 1
	s_sub_i32 s38, s35, s34
	s_cmp_ge_u32 s35, s34
	s_cselect_b32 s36, s37, s36
	s_cselect_b32 s35, s38, s35
	s_add_i32 s37, s36, 1
	s_cmp_ge_u32 s35, s34
	s_cselect_b32 s34, s37, s36
	s_xor_b32 s34, s34, s5
	s_sub_i32 s34, s34, s5
	s_mul_i32 s5, s34, s91
	s_sub_i32 s4, s4, s5
	s_add_i32 s36, s4, s90
	s_ashr_i32 s37, s36, 31
	s_lshl_b64 s[4:5], s[36:37], 19
	s_add_u32 s38, s18, s4
	s_addc_u32 s39, s19, s5
	s_and_b64 s[4:5], s[8:9], exec
	s_cselect_b32 s4, s39, s59
	s_cselect_b32 s5, s38, s58
	s_ashr_i32 s35, s34, 31
	s_lshl_b64 vcc, s[34:35], 19
	s_add_u32 s90, s1, vcc_lo
	s_addc_u32 s91, s14, vcc_hi
	s_and_b64 vcc, s[8:9], exec
	s_cselect_b32 s35, s91, s57
	s_cselect_b32 s37, s90, s56
	s_waitcnt vmcnt(8)
	s_waitcnt lgkmcnt(0)
	s_setprio 1
	s_barrier
; #define PG8_STAGE(bufoff, gbase, voff) do { _Pragma("unroll") for (int _i = 0; _i < 2; ++_i) { \
;         const unsigned _m0 = ldsb + (unsigned)((bufoff) + _i * 8192); const char* _gb = (const char*)(gbase); \
;         asm volatile("s_mov_b32 m0, %0\n\ts_nop 0\n\tglobal_load_lds_dwordx4 %1, %2" :: "s"(_m0), "v"((voff)[_i]), "s"(_gb) : "m0", "memory"); } } while (0)
; #define PG8_LDA(dst, b, h) do { _Pragma("unroll") for (int m = 0; m < 4; ++m) _Pragma("unroll") for (int k = 0; k < 2; ++k) dst[m][k] = *(const LAS bf16x8*)(lds + PG8_SA(b, h) + aoff + m * 2048 + k * 1024); } while (0)
; #define PG8_LDB(dst, b, h) do { _Pragma("unroll") for (int n = 0; n < 2; ++n) _Pragma("unroll") for (int k = 0; k < 2; ++k) dst[n][k] = *(const LAS bf16x8*)(lds + PG8_SB(b, h) + boff + n * 2048 + k * 1024); } while (0)
; template <class Epi, bool ALIGN_EPI>
; __device__ __forceinline__ void gemm_phase(LAS unsigned char* lds, const Gemm g, const StaticOrder& S, const Epi& E) {
;     ...
;         for (int t = 0; t < nt; t += 2) {
;             const bool last = (t == nt - 2);
;             const char* a1 = cA + (size_t)(t + 1) * kstep;
;             const char* a2 = last ? nA : cA + (size_t)(t + 2) * kstep; const char* b2 = last ? nB : cB + (size_t)(t + 2) * kstep;
;             const char* a3 = a2 + kstep; const char* b3 = b2 + kstep;
;             PG8_LDB(B0, 0, 0); PG8_LDB(B1, 0, 1); PG8_SCHED; PG8_LDA(At, 0, 0); PG8_STAGE(PG8_SA(1, 1), a1 + hstepA, voffA);
;             PG8_WAIT_V(8); PG8_WAIT_L(0); PG8_BAR; PG8_MMA(0, 0, At, B0); PG8_MMA(0, 1, At, B1); PG8_BAR; PG8_SCHED;
;             PG8_LDA(At, 0, 1); PG8_STAGE(PG8_SB(0, 0), b2, voffB); PG8_STAGE(PG8_SB(0, 1), b2 + hstepB, voffB); PG8_STAGE(PG8_SA(0, 0), a2, voffA);
;             PG8_WAIT_V(8); PG8_WAIT_L(0); PG8_BAR; PG8_MMA(1, 0, At, B0); PG8_MMA(1, 1, At, B1); PG8_BAR; PG8_SCHED;
;             PG8_LDB(B0, 1, 0); PG8_LDB(B1, 1, 1); PG8_SCHED; PG8_LDA(At, 1, 0); PG8_STAGE(PG8_SA(0, 1), a2 + hstepA, voffA);
;             PG8_WAIT_V(8); PG8_WAIT_L(0); PG8_BAR; PG8_MMA(0, 0, At, B0); PG8_MMA(0, 1, At, B1); PG8_BAR; PG8_SCHED;
;             PG8_LDA(At, 1, 1); PG8_STAGE(PG8_SB(1, 0), b3, voffB); PG8_STAGE(PG8_SB(1, 1), b3 + hstepB, voffB); PG8_STAGE(PG8_SA(1, 0), a3, voffA);
;             PG8_WAIT_V(8); PG8_WAIT_L(0); PG8_BAR; PG8_MMA(1, 0, At, B0); PG8_MMA(1, 1, At, B1); PG8_BAR; PG8_SCHED;
	v_mfma_f32_16x16x32_bf16 v[62:65], v[74:77], v[162:165], v[62:65]
	v_mfma_f32_16x16x32_bf16 v[62:65], v[94:97], v[166:169], v[62:65]
	v_mfma_f32_16x16x32_bf16 v[58:61], v[134:137], v[166:169], v[58:61]
	v_mfma_f32_16x16x32_bf16 v[58:61], v[114:117], v[162:165], v[58:61]
	v_mfma_f32_16x16x32_bf16 v[54:57], v[146:149], v[162:165], v[54:57]
	v_mfma_f32_16x16x32_bf16 v[54:57], v[150:153], v[166:169], v[54:57]
	v_mfma_f32_16x16x32_bf16 v[50:53], v[158:161], v[166:169], v[50:53]
	v_mfma_f32_16x16x32_bf16 v[50:53], v[154:157], v[162:165], v[50:53]
	v_mfma_f32_16x16x32_bf16 v[34:37], v[154:157], v[170:173], v[34:37]
	v_mfma_f32_16x16x32_bf16 v[34:37], v[158:161], v[174:177], v[34:37]
	v_mfma_f32_16x16x32_bf16 v[38:41], v[150:153], v[174:177], v[38:41]
	v_mfma_f32_16x16x32_bf16 v[38:41], v[146:149], v[170:173], v[38:41]
	v_mfma_f32_16x16x32_bf16 v[42:45], v[114:117], v[170:173], v[42:45]
	v_mfma_f32_16x16x32_bf16 v[42:45], v[134:137], v[174:177], v[42:45]
	v_mfma_f32_16x16x32_bf16 v[46:49], v[94:97], v[174:177], v[46:49]
	v_mfma_f32_16x16x32_bf16 v[46:49], v[74:77], v[170:173], v[46:49]
	v_mfma_f32_16x16x32_bf16 v[30:33], v[74:77], v[188:191], v[30:33]
	v_mfma_f32_16x16x32_bf16 v[30:33], v[94:97], v[202:205], v[30:33]
	v_mfma_f32_16x16x32_bf16 v[26:29], v[134:137], v[202:205], v[26:29]
	v_mfma_f32_16x16x32_bf16 v[26:29], v[114:117], v[188:191], v[26:29]
	v_mfma_f32_16x16x32_bf16 v[22:25], v[146:149], v[188:191], v[22:25]
	v_mfma_f32_16x16x32_bf16 v[22:25], v[150:153], v[202:205], v[22:25]
	v_mfma_f32_16x16x32_bf16 v[18:21], v[158:161], v[202:205], v[18:21]
	v_mfma_f32_16x16x32_bf16 v[18:21], v[154:157], v[188:191], v[18:21]
	v_mfma_f32_16x16x32_bf16 v[2:5], v[154:157], v[206:209], v[2:5]
	v_mfma_f32_16x16x32_bf16 v[2:5], v[158:161], v[210:213], v[2:5]
	v_mfma_f32_16x16x32_bf16 v[6:9], v[150:153], v[210:213], v[6:9]
	v_mfma_f32_16x16x32_bf16 v[6:9], v[146:149], v[206:209], v[6:9]
	v_mfma_f32_16x16x32_bf16 v[10:13], v[114:117], v[206:209], v[10:13]
	v_mfma_f32_16x16x32_bf16 v[10:13], v[134:137], v[210:213], v[10:13]
	v_mfma_f32_16x16x32_bf16 v[14:17], v[94:97], v[210:213], v[14:17]
	v_mfma_f32_16x16x32_bf16 v[14:17], v[74:77], v[206:209], v[14:17]
	s_barrier
	s_setprio 0
	s_add_i32 s50, s50, 2
	s_add_u32 s41, s41, 0x100
	s_addc_u32 s49, s49, 0
	s_add_u32 s92, s92, 0x100
	s_addc_u32 s93, s93, 0
	s_cmp_gt_u32 s50, 13
.LBB0_306:
	v_add_u32_e32 v134, 0x10000, v185
	v_add_u32_e32 v158, 0x14000, v185
	ds_read_b128 v[74:77], v134
	ds_read_b128 v[94:97], v134 offset:1024
	ds_read_b128 v[114:117], v134 offset:2048
	ds_read_b128 v[134:137], v134 offset:3072
	ds_read_b128 v[146:149], v158
	ds_read_b128 v[150:153], v158 offset:1024
	ds_read_b128 v[154:157], v158 offset:2048
	ds_read_b128 v[158:161], v158 offset:3072
	s_add_u32 s30, s92, 0xfffc0080
	s_addc_u32 s31, s93, -1
	s_cmp_eq_u32 s50, 12
	s_cselect_b32 s60, s5, s30
	s_cselect_b32 s61, s4, s31
	s_cselect_b32 s58, s37, s41
	s_cselect_b32 s59, s35, s49
	s_add_u32 s56, s60, 0x80
	s_addc_u32 s57, s61, 0
	ds_read_b128 v[162:165], v186
	ds_read_b128 v[166:169], v186 offset:1024
	ds_read_b128 v[170:173], v186 offset:2048
	ds_read_b128 v[174:177], v186 offset:3072
	ds_read_b128 v[188:191], v186 offset:4096
	ds_read_b128 v[202:205], v186 offset:5120
	ds_read_b128 v[206:209], v186 offset:6144
	ds_read_b128 v[210:213], v186 offset:7168
	s_mov_b32 m0, s67
	s_nop 0
	global_load_lds_dwordx4 v0, s[92:93]
	s_nop 0
	s_mov_b32 m0, s65
	s_nop 0
	global_load_lds_dwordx4 v181, s[92:93]
	s_waitcnt vmcnt(8)
	s_waitcnt lgkmcnt(0)
	s_setprio 1
	s_barrier
	v_mfma_f32_16x16x32_bf16 v[142:145], v[74:77], v[162:165], v[142:145]
	v_mfma_f32_16x16x32_bf16 v[142:145], v[94:97], v[166:169], v[142:145]
	v_mfma_f32_16x16x32_bf16 v[138:141], v[134:137], v[166:169], v[138:141]
	v_mfma_f32_16x16x32_bf16 v[138:141], v[114:117], v[162:165], v[138:141]
	v_mfma_f32_16x16x32_bf16 v[130:133], v[146:149], v[162:165], v[130:133]
	v_mfma_f32_16x16x32_bf16 v[130:133], v[150:153], v[166:169], v[130:133]
	v_mfma_f32_16x16x32_bf16 v[126:129], v[158:161], v[166:169], v[126:129]
	v_mfma_f32_16x16x32_bf16 v[126:129], v[154:157], v[162:165], v[126:129]
	v_mfma_f32_16x16x32_bf16 v[106:109], v[154:157], v[170:173], v[106:109]
	v_mfma_f32_16x16x32_bf16 v[106:109], v[158:161], v[174:177], v[106:109]
	v_mfma_f32_16x16x32_bf16 v[110:113], v[150:153], v[174:177], v[110:113]
	v_mfma_f32_16x16x32_bf16 v[110:113], v[146:149], v[170:173], v[110:113]
	v_mfma_f32_16x16x32_bf16 v[118:121], v[114:117], v[170:173], v[118:121]
	v_mfma_f32_16x16x32_bf16 v[118:121], v[134:137], v[174:177], v[118:121]
	v_mfma_f32_16x16x32_bf16 v[122:125], v[94:97], v[174:177], v[122:125]
	v_mfma_f32_16x16x32_bf16 v[122:125], v[74:77], v[170:173], v[122:125]
	v_mfma_f32_16x16x32_bf16 v[102:105], v[74:77], v[188:191], v[102:105]
	v_mfma_f32_16x16x32_bf16 v[102:105], v[94:97], v[202:205], v[102:105]
	v_mfma_f32_16x16x32_bf16 v[98:101], v[134:137], v[202:205], v[98:101]
	v_mfma_f32_16x16x32_bf16 v[98:101], v[114:117], v[188:191], v[98:101]
	v_mfma_f32_16x16x32_bf16 v[90:93], v[146:149], v[188:191], v[90:93]
	v_mfma_f32_16x16x32_bf16 v[90:93], v[150:153], v[202:205], v[90:93]
	v_mfma_f32_16x16x32_bf16 v[86:89], v[158:161], v[202:205], v[86:89]
	v_mfma_f32_16x16x32_bf16 v[86:89], v[154:157], v[188:191], v[86:89]
	v_mfma_f32_16x16x32_bf16 v[66:69], v[154:157], v[206:209], v[66:69]
	v_mfma_f32_16x16x32_bf16 v[66:69], v[158:161], v[210:213], v[66:69]
	v_mfma_f32_16x16x32_bf16 v[70:73], v[150:153], v[210:213], v[70:73]
	v_mfma_f32_16x16x32_bf16 v[70:73], v[146:149], v[206:209], v[70:73]
	v_mfma_f32_16x16x32_bf16 v[78:81], v[114:117], v[206:209], v[78:81]
	v_mfma_f32_16x16x32_bf16 v[78:81], v[134:137], v[210:213], v[78:81]
	v_mfma_f32_16x16x32_bf16 v[82:85], v[94:97], v[210:213], v[82:85]
	v_mfma_f32_16x16x32_bf16 v[82:85], v[74:77], v[206:209], v[82:85]
	s_barrier
; #define PG8_STAGE(bufoff, gbase, voff) do { _Pragma("unroll") for (int _i = 0; _i < 2; ++_i) { \
;         const unsigned _m0 = ldsb + (unsigned)((bufoff) + _i * 8192); const char* _gb = (const char*)(gbase); \
;         asm volatile("s_mov_b32 m0, %0\n\ts_nop 0\n\tglobal_load_lds_dwordx4 %1, %2" :: "s"(_m0), "v"((voff)[_i]), "s"(_gb) : "m0", "memory"); } } while (0)
; #define PG8_LDA(dst, b, h) do { _Pragma("unroll") for (int m = 0; m < 4; ++m) _Pragma("unroll") for (int k = 0; k < 2; ++k) dst[m][k] = *(const LAS bf16x8*)(lds + PG8_SA(b, h) + aoff + m * 2048 + k * 1024); } while (0)
; #define PG8_LDB(dst, b, h) do { _Pragma("unroll") for (int n = 0; n < 2; ++n) _Pragma("unroll") for (int k = 0; k < 2; ++k) dst[n][k] = *(const LAS bf16x8*)(lds + PG8_SB(b, h) + boff + n * 2048 + k * 1024); } while (0)
; #define PG8_MMA(ai, bj, At, Bt) do { __builtin_amdgcn_s_setprio(1); _Pragma("unroll") for (int m = 0; m < 4; ++m) _Pragma("unroll") for (int n = 0; n < 2; ++n) _Pragma("unroll") for (int k = 0; k < 2; ++k) \
;         acc[ai][bj][m][n] = __builtin_amdgcn_mfma_f32_16x16x32_bf16(Bt[n][k], At[m][k], acc[ai][bj][m][n], 0, 0, 0); __builtin_amdgcn_s_setprio(0); } while (0)
; #define PG8_WAIT_V(n) asm volatile("s_waitcnt vmcnt(" #n ")" ::: "memory")
; #define PG8_WAIT_L(n) asm volatile("s_waitcnt lgkmcnt(" #n ")" ::: "memory")
; #define PG8_BAR __builtin_amdgcn_s_barrier()
; #define PG8_SCHED __builtin_amdgcn_sched_barrier(0)
; template <class Epi, bool ALIGN_EPI>
; __device__ __forceinline__ void gemm_phase(LAS unsigned char* lds, const Gemm g, const StaticOrder& S, const Epi& E) {
;     ...
;             PG8_LDA(At, 0, 1); PG8_STAGE(PG8_SB(0, 0), b2, voffB); PG8_STAGE(PG8_SB(0, 1), b2 + hstepB, voffB); PG8_STAGE(PG8_SA(0, 0), a2, voffA);
;             PG8_WAIT_V(8); PG8_WAIT_L(0); PG8_BAR; PG8_MMA(1, 0, At, B0); PG8_MMA(1, 1, At, B1); PG8_BAR; PG8_SCHED;
;             PG8_LDB(B0, 1, 0); PG8_LDB(B1, 1, 1); PG8_SCHED; PG8_LDA(At, 1, 0); PG8_STAGE(PG8_SA(0, 1), a2 + hstepA, voffA);
;             PG8_WAIT_V(8); PG8_WAIT_L(0); PG8_BAR; PG8_MMA(0, 0, At, B0); PG8_MMA(0, 1, At, B1); PG8_BAR; PG8_SCHED;
;             PG8_LDA(At, 1, 1); PG8_STAGE(PG8_SB(1, 0), b3, voffB); PG8_STAGE(PG8_SB(1, 1), b3 + hstepB, voffB); PG8_STAGE(PG8_SA(1, 0), a3, voffA);
;             PG8_WAIT_V(8); PG8_WAIT_L(0); PG8_BAR; PG8_MMA(1, 0, At, B0); PG8_MMA(1, 1, At, B1); PG8_BAR; PG8_SCHED;
	s_setprio 0
	ds_read_b128 v[162:165], v186 offset:16384
	ds_read_b128 v[166:169], v186 offset:17408
	ds_read_b128 v[170:173], v186 offset:18432
	ds_read_b128 v[174:177], v186 offset:19456
	ds_read_b128 v[188:191], v186 offset:20480
	ds_read_b128 v[202:205], v186 offset:21504
	ds_read_b128 v[206:209], v186 offset:22528
	ds_read_b128 v[210:213], v186 offset:23552
	s_mov_b32 m0, s29
	s_nop 0
	global_load_lds_dwordx4 v180, s[58:59]
	s_add_u32 s30, s58, 0x40000
	s_mov_b32 m0, s42
	s_nop 0
	global_load_lds_dwordx4 v182, s[58:59]
	s_addc_u32 s31, s59, 0
	s_mov_b32 m0, s43
	s_nop 0
	global_load_lds_dwordx4 v180, s[30:31]
	s_nop 0
	s_mov_b32 m0, s44
	s_nop 0
	global_load_lds_dwordx4 v182, s[30:31]
	s_nop 0
	s_mov_b32 m0, s15
	s_nop 0
	global_load_lds_dwordx4 v0, s[60:61]
	s_nop 0
	s_mov_b32 m0, s45
	s_nop 0
	global_load_lds_dwordx4 v181, s[60:61]
	s_waitcnt vmcnt(8)
	s_waitcnt lgkmcnt(0)
	s_setprio 1
	s_barrier
	v_mfma_f32_16x16x32_bf16 v[62:65], v[74:77], v[162:165], v[62:65]
	v_mfma_f32_16x16x32_bf16 v[62:65], v[94:97], v[166:169], v[62:65]
	v_mfma_f32_16x16x32_bf16 v[58:61], v[134:137], v[166:169], v[58:61]
	v_mfma_f32_16x16x32_bf16 v[58:61], v[114:117], v[162:165], v[58:61]
	v_mfma_f32_16x16x32_bf16 v[54:57], v[146:149], v[162:165], v[54:57]
	v_mfma_f32_16x16x32_bf16 v[54:57], v[150:153], v[166:169], v[54:57]
	v_mfma_f32_16x16x32_bf16 v[50:53], v[158:161], v[166:169], v[50:53]
	v_mfma_f32_16x16x32_bf16 v[50:53], v[154:157], v[162:165], v[50:53]
	v_mfma_f32_16x16x32_bf16 v[34:37], v[154:157], v[170:173], v[34:37]
	v_mfma_f32_16x16x32_bf16 v[34:37], v[158:161], v[174:177], v[34:37]
	v_mfma_f32_16x16x32_bf16 v[38:41], v[150:153], v[174:177], v[38:41]
	v_mfma_f32_16x16x32_bf16 v[38:41], v[146:149], v[170:173], v[38:41]
	v_mfma_f32_16x16x32_bf16 v[42:45], v[114:117], v[170:173], v[42:45]
	v_mfma_f32_16x16x32_bf16 v[42:45], v[134:137], v[174:177], v[42:45]
	v_mfma_f32_16x16x32_bf16 v[46:49], v[94:97], v[174:177], v[46:49]
	v_mfma_f32_16x16x32_bf16 v[46:49], v[74:77], v[170:173], v[46:49]
	v_mfma_f32_16x16x32_bf16 v[30:33], v[74:77], v[188:191], v[30:33]
	v_mfma_f32_16x16x32_bf16 v[30:33], v[94:97], v[202:205], v[30:33]
	v_mfma_f32_16x16x32_bf16 v[26:29], v[134:137], v[202:205], v[26:29]
	v_mfma_f32_16x16x32_bf16 v[26:29], v[114:117], v[188:191], v[26:29]
	v_mfma_f32_16x16x32_bf16 v[22:25], v[146:149], v[188:191], v[22:25]
	v_mfma_f32_16x16x32_bf16 v[22:25], v[150:153], v[202:205], v[22:25]
	v_mfma_f32_16x16x32_bf16 v[18:21], v[158:161], v[202:205], v[18:21]
	v_mfma_f32_16x16x32_bf16 v[18:21], v[154:157], v[188:191], v[18:21]
	v_mfma_f32_16x16x32_bf16 v[2:5], v[154:157], v[206:209], v[2:5]
	v_mfma_f32_16x16x32_bf16 v[2:5], v[158:161], v[210:213], v[2:5]
	v_mfma_f32_16x16x32_bf16 v[6:9], v[150:153], v[210:213], v[6:9]
	v_mfma_f32_16x16x32_bf16 v[6:9], v[146:149], v[206:209], v[6:9]
	v_mfma_f32_16x16x32_bf16 v[10:13], v[114:117], v[206:209], v[10:13]
	v_mfma_f32_16x16x32_bf16 v[10:13], v[134:137], v[210:213], v[10:13]
	v_mfma_f32_16x16x32_bf16 v[14:17], v[94:97], v[210:213], v[14:17]
	v_mfma_f32_16x16x32_bf16 v[14:17], v[74:77], v[206:209], v[14:17]
	s_barrier
	s_setprio 0
	v_add_u32_e32 v134, 0x18000, v185
	v_add_u32_e32 v158, 0x1c000, v185
	ds_read_b128 v[74:77], v134
	ds_read_b128 v[94:97], v134 offset:1024
	ds_read_b128 v[114:117], v134 offset:2048
	ds_read_b128 v[134:137], v134 offset:3072
	ds_read_b128 v[146:149], v158
	ds_read_b128 v[150:153], v158 offset:1024
	ds_read_b128 v[154:157], v158 offset:2048
	ds_read_b128 v[158:161], v158 offset:3072
	ds_read_b128 v[162:165], v186 offset:32768
	ds_read_b128 v[166:169], v186 offset:33792
	ds_read_b128 v[170:173], v186 offset:34816
	ds_read_b128 v[174:177], v186 offset:35840
	ds_read_b128 v[188:191], v186 offset:36864
	ds_read_b128 v[202:205], v186 offset:37888
	ds_read_b128 v[206:209], v186 offset:38912
	ds_read_b128 v[210:213], v186 offset:39936
	s_add_u32 s30, s60, 0x40000
	s_addc_u32 s31, s61, 0
	s_mov_b32 m0, s55
	s_nop 0
	global_load_lds_dwordx4 v0, s[30:31]
	s_nop 0
	s_mov_b32 m0, s88
	s_nop 0
	global_load_lds_dwordx4 v181, s[30:31]
	s_waitcnt vmcnt(8)
	s_waitcnt lgkmcnt(0)
	s_setprio 1
	s_barrier
; #define PG8_STAGE(bufoff, gbase, voff) do { _Pragma("unroll") for (int _i = 0; _i < 2; ++_i) { \
;         const unsigned _m0 = ldsb + (unsigned)((bufoff) + _i * 8192); const char* _gb = (const char*)(gbase); \
;         asm volatile("s_mov_b32 m0, %0\n\ts_nop 0\n\tglobal_load_lds_dwordx4 %1, %2" :: "s"(_m0), "v"((voff)[_i]), "s"(_gb) : "m0", "memory"); } } while (0)
; #define PG8_LDA(dst, b, h) do { _Pragma("unroll") for (int m = 0; m < 4; ++m) _Pragma("unroll") for (int k = 0; k < 2; ++k) dst[m][k] = *(const LAS bf16x8*)(lds + PG8_SA(b, h) + aoff + m * 2048 + k * 1024); } while (0)
; #define PG8_MMA(ai, bj, At, Bt) do { __builtin_amdgcn_s_setprio(1); _Pragma("unroll") for (int m = 0; m < 4; ++m) _Pragma("unroll") for (int n = 0; n < 2; ++n) _Pragma("unroll") for (int k = 0; k < 2; ++k) \
;         acc[ai][bj][m][n] = __builtin_amdgcn_mfma_f32_16x16x32_bf16(Bt[n][k], At[m][k], acc[ai][bj][m][n], 0, 0, 0); __builtin_amdgcn_s_setprio(0); } while (0)
; #define PG8_WAIT_V(n) asm volatile("s_waitcnt vmcnt(" #n ")" ::: "memory")
; #define PG8_WAIT_L(n) asm volatile("s_waitcnt lgkmcnt(" #n ")" ::: "memory")
; #define PG8_BAR __builtin_amdgcn_s_barrier()
; #define PG8_SCHED __builtin_amdgcn_sched_barrier(0)
; template <class Epi, bool ALIGN_EPI>
; __device__ __forceinline__ void gemm_phase(LAS unsigned char* lds, const Gemm g, const StaticOrder& S, const Epi& E) {
;     ...
;             PG8_WAIT_V(8); PG8_WAIT_L(0); PG8_BAR; PG8_MMA(0, 0, At, B0); PG8_MMA(0, 1, At, B1); PG8_BAR; PG8_SCHED;
;             PG8_LDA(At, 1, 1); PG8_STAGE(PG8_SB(1, 0), b3, voffB); PG8_STAGE(PG8_SB(1, 1), b3 + hstepB, voffB); PG8_STAGE(PG8_SA(1, 0), a3, voffA);
;             PG8_WAIT_V(8); PG8_WAIT_L(0); PG8_BAR; PG8_MMA(1, 0, At, B0); PG8_MMA(1, 1, At, B1); PG8_BAR; PG8_SCHED;
;         }
;         if constexpr (ALIGN_EPI) { if (wr == 0) PG8_BAR; }
	v_mfma_f32_16x16x32_bf16 v[142:145], v[74:77], v[162:165], v[142:145]
	v_mfma_f32_16x16x32_bf16 v[142:145], v[94:97], v[166:169], v[142:145]
	v_mfma_f32_16x16x32_bf16 v[138:141], v[134:137], v[166:169], v[138:141]
	v_mfma_f32_16x16x32_bf16 v[138:141], v[114:117], v[162:165], v[138:141]
	v_mfma_f32_16x16x32_bf16 v[130:133], v[146:149], v[162:165], v[130:133]
	v_mfma_f32_16x16x32_bf16 v[130:133], v[150:153], v[166:169], v[130:133]
	v_mfma_f32_16x16x32_bf16 v[126:129], v[158:161], v[166:169], v[126:129]
	v_mfma_f32_16x16x32_bf16 v[126:129], v[154:157], v[162:165], v[126:129]
	v_mfma_f32_16x16x32_bf16 v[106:109], v[154:157], v[170:173], v[106:109]
	v_mfma_f32_16x16x32_bf16 v[106:109], v[158:161], v[174:177], v[106:109]
	v_mfma_f32_16x16x32_bf16 v[110:113], v[150:153], v[174:177], v[110:113]
	v_mfma_f32_16x16x32_bf16 v[110:113], v[146:149], v[170:173], v[110:113]
	v_mfma_f32_16x16x32_bf16 v[118:121], v[114:117], v[170:173], v[118:121]
	v_mfma_f32_16x16x32_bf16 v[118:121], v[134:137], v[174:177], v[118:121]
	v_mfma_f32_16x16x32_bf16 v[122:125], v[94:97], v[174:177], v[122:125]
	v_mfma_f32_16x16x32_bf16 v[122:125], v[74:77], v[170:173], v[122:125]
	v_mfma_f32_16x16x32_bf16 v[102:105], v[74:77], v[188:191], v[102:105]
	v_mfma_f32_16x16x32_bf16 v[102:105], v[94:97], v[202:205], v[102:105]
	v_mfma_f32_16x16x32_bf16 v[98:101], v[134:137], v[202:205], v[98:101]
	v_mfma_f32_16x16x32_bf16 v[98:101], v[114:117], v[188:191], v[98:101]
	v_mfma_f32_16x16x32_bf16 v[90:93], v[146:149], v[188:191], v[90:93]
	v_mfma_f32_16x16x32_bf16 v[90:93], v[150:153], v[202:205], v[90:93]
	v_mfma_f32_16x16x32_bf16 v[86:89], v[158:161], v[202:205], v[86:89]
	v_mfma_f32_16x16x32_bf16 v[86:89], v[154:157], v[188:191], v[86:89]
	v_mfma_f32_16x16x32_bf16 v[66:69], v[154:157], v[206:209], v[66:69]
	v_mfma_f32_16x16x32_bf16 v[66:69], v[158:161], v[210:213], v[66:69]
	v_mfma_f32_16x16x32_bf16 v[70:73], v[150:153], v[210:213], v[70:73]
	v_mfma_f32_16x16x32_bf16 v[70:73], v[146:149], v[206:209], v[70:73]
	v_mfma_f32_16x16x32_bf16 v[78:81], v[114:117], v[206:209], v[78:81]
	v_mfma_f32_16x16x32_bf16 v[78:81], v[134:137], v[210:213], v[78:81]
	v_mfma_f32_16x16x32_bf16 v[82:85], v[94:97], v[210:213], v[82:85]
	v_mfma_f32_16x16x32_bf16 v[82:85], v[74:77], v[206:209], v[82:85]
	s_barrier
	s_setprio 0
	ds_read_b128 v[162:165], v186 offset:49152
	ds_read_b128 v[166:169], v186 offset:50176
	ds_read_b128 v[170:173], v186 offset:51200
	ds_read_b128 v[174:177], v186 offset:52224
	ds_read_b128 v[188:191], v186 offset:53248
	ds_read_b128 v[202:205], v186 offset:54272
	ds_read_b128 v[206:209], v186 offset:55296
	ds_read_b128 v[210:213], v186 offset:56320
	s_add_u32 s30, s58, 0x80
	s_addc_u32 s31, s59, 0
	s_mov_b32 m0, s94
	s_nop 0
	global_load_lds_dwordx4 v180, s[30:31]
	s_nop 0
	s_mov_b32 m0, s95
	s_nop 0
	global_load_lds_dwordx4 v182, s[30:31]
	s_add_u32 s30, s58, 0x40080
	s_addc_u32 s31, s59, 0
	s_mov_b32 m0, s17
	s_nop 0
	global_load_lds_dwordx4 v180, s[30:31]
	s_nop 0
	s_mov_b32 m0, s53
	s_nop 0
	global_load_lds_dwordx4 v182, s[30:31]
	s_nop 0
	s_mov_b32 m0, s96
	s_nop 0
	global_load_lds_dwordx4 v0, s[56:57]
	s_nop 0
	s_mov_b32 m0, s97
	s_nop 0
	global_load_lds_dwordx4 v181, s[56:57]
	s_waitcnt vmcnt(8)
	s_waitcnt lgkmcnt(0)
	s_setprio 1
	s_barrier
	v_mfma_f32_16x16x32_bf16 v[62:65], v[74:77], v[162:165], v[62:65]
	v_mfma_f32_16x16x32_bf16 v[62:65], v[94:97], v[166:169], v[62:65]
	v_mfma_f32_16x16x32_bf16 v[58:61], v[134:137], v[166:169], v[58:61]
	v_mfma_f32_16x16x32_bf16 v[58:61], v[114:117], v[162:165], v[58:61]
	v_mfma_f32_16x16x32_bf16 v[54:57], v[146:149], v[162:165], v[54:57]
	v_mfma_f32_16x16x32_bf16 v[54:57], v[150:153], v[166:169], v[54:57]
	v_mfma_f32_16x16x32_bf16 v[50:53], v[158:161], v[166:169], v[50:53]
	v_mfma_f32_16x16x32_bf16 v[50:53], v[154:157], v[162:165], v[50:53]
	v_mfma_f32_16x16x32_bf16 v[34:37], v[154:157], v[170:173], v[34:37]
	v_mfma_f32_16x16x32_bf16 v[34:37], v[158:161], v[174:177], v[34:37]
	v_mfma_f32_16x16x32_bf16 v[38:41], v[150:153], v[174:177], v[38:41]
	v_mfma_f32_16x16x32_bf16 v[38:41], v[146:149], v[170:173], v[38:41]
	v_mfma_f32_16x16x32_bf16 v[42:45], v[114:117], v[170:173], v[42:45]
	v_mfma_f32_16x16x32_bf16 v[42:45], v[134:137], v[174:177], v[42:45]
	v_mfma_f32_16x16x32_bf16 v[46:49], v[94:97], v[174:177], v[46:49]
	v_mfma_f32_16x16x32_bf16 v[46:49], v[74:77], v[170:173], v[46:49]
	v_mfma_f32_16x16x32_bf16 v[30:33], v[74:77], v[188:191], v[30:33]
	v_mfma_f32_16x16x32_bf16 v[30:33], v[94:97], v[202:205], v[30:33]
	v_mfma_f32_16x16x32_bf16 v[26:29], v[134:137], v[202:205], v[26:29]
	v_mfma_f32_16x16x32_bf16 v[26:29], v[114:117], v[188:191], v[26:29]
	v_mfma_f32_16x16x32_bf16 v[22:25], v[146:149], v[188:191], v[22:25]
	v_mfma_f32_16x16x32_bf16 v[22:25], v[150:153], v[202:205], v[22:25]
	v_mfma_f32_16x16x32_bf16 v[18:21], v[158:161], v[202:205], v[18:21]
	v_mfma_f32_16x16x32_bf16 v[18:21], v[154:157], v[188:191], v[18:21]
	v_mfma_f32_16x16x32_bf16 v[2:5], v[154:157], v[206:209], v[2:5]
	v_mfma_f32_16x16x32_bf16 v[2:5], v[158:161], v[210:213], v[2:5]
	v_mfma_f32_16x16x32_bf16 v[6:9], v[150:153], v[210:213], v[6:9]
	v_mfma_f32_16x16x32_bf16 v[6:9], v[146:149], v[206:209], v[6:9]
	v_mfma_f32_16x16x32_bf16 v[10:13], v[114:117], v[206:209], v[10:13]
	v_mfma_f32_16x16x32_bf16 v[10:13], v[134:137], v[210:213], v[10:13]
	v_mfma_f32_16x16x32_bf16 v[14:17], v[94:97], v[210:213], v[14:17]
	v_mfma_f32_16x16x32_bf16 v[14:17], v[74:77], v[206:209], v[14:17]
	s_barrier
	s_setprio 0
	s_add_i32 s50, s50, 2
	s_add_u32 s41, s41, 0x100
	s_addc_u32 s49, s49, 0
	s_add_u32 s92, s92, 0x100
	s_addc_u32 s93, s93, 0
	s_cmp_gt_u32 s50, 13
	s_cbranch_scc0 .LBB0_306
	v_readlane_b32 s4, v254, 46
	v_readlane_b32 s5, v254, 47
	s_and_b64 vcc, exec, s[4:5]
	s_cbranch_vccz .LBB0_309
	s_barrier

; #define PG8_STAGE(bufoff, gbase, voff) do { _Pragma("unroll") for (int _i = 0; _i < 2; ++_i) { \
;         const unsigned _m0 = ldsb + (unsigned)((bufoff) + _i * 8192); const char* _gb = (const char*)(gbase); \
;         asm volatile("s_mov_b32 m0, %0\n\ts_nop 0\n\tglobal_load_lds_dwordx4 %1, %2" :: "s"(_m0), "v"((voff)[_i]), "s"(_gb) : "m0", "memory"); } } while (0)
; #define PG8_LDA(dst, b, h) do { _Pragma("unroll") for (int m = 0; m < 4; ++m) _Pragma("unroll") for (int k = 0; k < 2; ++k) dst[m][k] = *(const LAS bf16x8*)(lds + PG8_SA(b, h) + aoff + m * 2048 + k * 1024); } while (0)
; #define PG8_LDB(dst, b, h) do { _Pragma("unroll") for (int n = 0; n < 2; ++n) _Pragma("unroll") for (int k = 0; k < 2; ++k) dst[n][k] = *(const LAS bf16x8*)(lds + PG8_SB(b, h) + boff + n * 2048 + k * 1024); } while (0)
; #define PG8_MMA(ai, bj, At, Bt) do { __builtin_amdgcn_s_setprio(1); _Pragma("unroll") for (int m = 0; m < 4; ++m) _Pragma("unroll") for (int n = 0; n < 2; ++n) _Pragma("unroll") for (int k = 0; k < 2; ++k) \
;         acc[ai][bj][m][n] = __builtin_amdgcn_mfma_f32_16x16x32_bf16(Bt[n][k], At[m][k], acc[ai][bj][m][n], 0, 0, 0); __builtin_amdgcn_s_setprio(0); } while (0)
; #define PG8_WAIT_V(n) asm volatile("s_waitcnt vmcnt(" #n ")" ::: "memory")
; #define PG8_WAIT_L(n) asm volatile("s_waitcnt lgkmcnt(" #n ")" ::: "memory")
; template <class Epi, bool ALIGN_EPI>
; __device__ __forceinline__ void gemm_phase(LAS unsigned char* lds, const Gemm g, const StaticOrder& S, const Epi& E) {
;     ...
;         for (int t = 0; t < nt; t += 2) {
;             const bool last = (t == nt - 2);
;             const char* a1 = cA + (size_t)(t + 1) * kstep;
;             const char* a2 = last ? nA : cA + (size_t)(t + 2) * kstep; const char* b2 = last ? nB : cB + (size_t)(t + 2) * kstep;
;             const char* a3 = a2 + kstep; const char* b3 = b2 + kstep;
;             PG8_LDB(B0, 0, 0); PG8_LDB(B1, 0, 1); PG8_SCHED; PG8_LDA(At, 0, 0); PG8_STAGE(PG8_SA(1, 1), a1 + hstepA, voffA);
;             PG8_WAIT_V(8); PG8_WAIT_L(0); PG8_BAR; PG8_MMA(0, 0, At, B0); PG8_MMA(0, 1, At, B1); PG8_BAR; PG8_SCHED;
;             PG8_LDA(At, 0, 1); PG8_STAGE(PG8_SB(0, 0), b2, voffB); PG8_STAGE(PG8_SB(0, 1), b2 + hstepB, voffB); PG8_STAGE(PG8_SA(0, 0), a2, voffA);
;             PG8_WAIT_V(8); PG8_WAIT_L(0); PG8_BAR; PG8_MMA(1, 0, At, B0); PG8_MMA(1, 1, At, B1); PG8_BAR; PG8_SCHED;
.LBB0_349:
	v_add_u32_e32 v0, 0x10000, v187
	ds_read_b128 v[34:37], v0
	ds_read_b128 v[54:57], v0 offset:1024
	ds_read_b128 v[74:77], v0 offset:2048
	ds_read_b128 v[94:97], v0 offset:3072
	v_add_u32_e32 v0, 0x14000, v187
	ds_read_b128 v[110:113], v0
	ds_read_b128 v[126:129], v0 offset:1024
	ds_read_b128 v[146:149], v0 offset:2048
	ds_read_b128 v[160:163], v0 offset:3072
	s_add_u32 s38, s36, 0xfffc0080
	s_addc_u32 s39, s37, -1
	s_cmp_eq_u32 s50, 12
	s_cselect_b32 s54, s5, s38
	s_cselect_b32 s55, s4, s39
	s_cselect_b32 s48, s27, s29
	s_cselect_b32 s49, s11, s41
	s_add_u32 s38, s54, 0x80
	s_addc_u32 s39, s55, 0
	ds_read_b128 v[164:167], v188
	ds_read_b128 v[168:171], v188 offset:1024
	ds_read_b128 v[172:175], v188 offset:2048
	ds_read_b128 v[176:179], v188 offset:3072
	ds_read_b128 v[190:193], v188 offset:4096
	ds_read_b128 v[202:205], v188 offset:5120
	ds_read_b128 v[206:209], v188 offset:6144
	ds_read_b128 v[210:213], v188 offset:7168
	s_mov_b32 m0, s91
	s_nop 0
	global_load_lds_dwordx4 v180, s[36:37]
	s_nop 0
	s_mov_b32 m0, s93
	s_nop 0
	global_load_lds_dwordx4 v182, s[36:37]
	s_waitcnt vmcnt(8)
	s_waitcnt lgkmcnt(0)
	s_setprio 1
	s_barrier
	v_mfma_f32_16x16x32_bf16 v[154:157], v[34:37], v[164:167], v[154:157]
	v_mfma_f32_16x16x32_bf16 v[154:157], v[54:57], v[168:171], v[154:157]
	v_mfma_f32_16x16x32_bf16 v[150:153], v[94:97], v[168:171], v[150:153]
	v_mfma_f32_16x16x32_bf16 v[150:153], v[74:77], v[164:167], v[150:153]
	v_mfma_f32_16x16x32_bf16 v[142:145], v[110:113], v[164:167], v[142:145]
	v_mfma_f32_16x16x32_bf16 v[142:145], v[126:129], v[168:171], v[142:145]
	v_mfma_f32_16x16x32_bf16 v[138:141], v[160:163], v[168:171], v[138:141]
	v_mfma_f32_16x16x32_bf16 v[138:141], v[146:149], v[164:167], v[138:141]
	v_mfma_f32_16x16x32_bf16 v[118:121], v[146:149], v[172:175], v[118:121]
	v_mfma_f32_16x16x32_bf16 v[118:121], v[160:163], v[176:179], v[118:121]
	v_mfma_f32_16x16x32_bf16 v[122:125], v[126:129], v[176:179], v[122:125]
	v_mfma_f32_16x16x32_bf16 v[122:125], v[110:113], v[172:175], v[122:125]
	v_mfma_f32_16x16x32_bf16 v[130:133], v[74:77], v[172:175], v[130:133]
	v_mfma_f32_16x16x32_bf16 v[130:133], v[94:97], v[176:179], v[130:133]
	v_mfma_f32_16x16x32_bf16 v[134:137], v[54:57], v[176:179], v[134:137]
	v_mfma_f32_16x16x32_bf16 v[134:137], v[34:37], v[172:175], v[134:137]
	v_mfma_f32_16x16x32_bf16 v[114:117], v[34:37], v[190:193], v[114:117]
	v_mfma_f32_16x16x32_bf16 v[114:117], v[54:57], v[202:205], v[114:117]
	v_mfma_f32_16x16x32_bf16 v[106:109], v[94:97], v[202:205], v[106:109]
	v_mfma_f32_16x16x32_bf16 v[106:109], v[74:77], v[190:193], v[106:109]
	v_mfma_f32_16x16x32_bf16 v[102:105], v[110:113], v[190:193], v[102:105]
	v_mfma_f32_16x16x32_bf16 v[102:105], v[126:129], v[202:205], v[102:105]
	v_mfma_f32_16x16x32_bf16 v[98:101], v[160:163], v[202:205], v[98:101]
	v_mfma_f32_16x16x32_bf16 v[98:101], v[146:149], v[190:193], v[98:101]
	v_mfma_f32_16x16x32_bf16 v[78:81], v[146:149], v[206:209], v[78:81]
	v_mfma_f32_16x16x32_bf16 v[78:81], v[160:163], v[210:213], v[78:81]
	v_mfma_f32_16x16x32_bf16 v[82:85], v[126:129], v[210:213], v[82:85]
	v_mfma_f32_16x16x32_bf16 v[82:85], v[110:113], v[206:209], v[82:85]
	v_mfma_f32_16x16x32_bf16 v[86:89], v[74:77], v[206:209], v[86:89]
	v_mfma_f32_16x16x32_bf16 v[86:89], v[94:97], v[210:213], v[86:89]
	v_mfma_f32_16x16x32_bf16 v[90:93], v[54:57], v[210:213], v[90:93]
	v_mfma_f32_16x16x32_bf16 v[90:93], v[34:37], v[206:209], v[90:93]
	s_barrier
	s_setprio 0
	ds_read_b128 v[164:167], v188 offset:16384
	ds_read_b128 v[168:171], v188 offset:17408
	ds_read_b128 v[172:175], v188 offset:18432
	ds_read_b128 v[176:179], v188 offset:19456
	ds_read_b128 v[190:193], v188 offset:20480
	ds_read_b128 v[202:205], v188 offset:21504
	ds_read_b128 v[206:209], v188 offset:22528
	ds_read_b128 v[210:213], v188 offset:23552
	s_mov_b32 m0, s43
	s_nop 0
	global_load_lds_dwordx4 v181, s[48:49]
	s_add_u32 s96, s48, 0x40000
	s_mov_b32 m0, s44
	s_nop 0
	global_load_lds_dwordx4 v183, s[48:49]
	s_addc_u32 s97, s49, 0
	s_mov_b32 m0, s45
	s_nop 0
	global_load_lds_dwordx4 v181, s[96:97]
	s_nop 0
	s_mov_b32 m0, s56
	s_nop 0
	global_load_lds_dwordx4 v183, s[96:97]
	s_nop 0
	s_mov_b32 m0, s42
	s_nop 0
	global_load_lds_dwordx4 v180, s[54:55]
	s_nop 0
	s_mov_b32 m0, s57
	s_nop 0
	global_load_lds_dwordx4 v182, s[54:55]
	s_waitcnt vmcnt(8)
	s_waitcnt lgkmcnt(0)
	s_setprio 1
	s_barrier
	v_mfma_f32_16x16x32_bf16 v[70:73], v[34:37], v[164:167], v[70:73]
	v_mfma_f32_16x16x32_bf16 v[66:69], v[74:77], v[164:167], v[66:69]
	v_mfma_f32_16x16x32_bf16 v[50:53], v[34:37], v[172:175], v[50:53]
	v_mfma_f32_16x16x32_bf16 v[46:49], v[74:77], v[172:175], v[46:49]
	v_mfma_f32_16x16x32_bf16 v[30:33], v[34:37], v[190:193], v[30:33]
	v_mfma_f32_16x16x32_bf16 v[26:29], v[74:77], v[190:193], v[26:29]
	v_mfma_f32_16x16x32_bf16 v[14:17], v[34:37], v[206:209], v[14:17]
	v_mfma_f32_16x16x32_bf16 v[10:13], v[74:77], v[206:209], v[10:13]
	v_mfma_f32_16x16x32_bf16 v[70:73], v[54:57], v[168:171], v[70:73]
	v_mfma_f32_16x16x32_bf16 v[66:69], v[94:97], v[168:171], v[66:69]
	v_mfma_f32_16x16x32_bf16 v[50:53], v[54:57], v[176:179], v[50:53]
	v_mfma_f32_16x16x32_bf16 v[46:49], v[94:97], v[176:179], v[46:49]
	v_mfma_f32_16x16x32_bf16 v[30:33], v[54:57], v[202:205], v[30:33]
	v_mfma_f32_16x16x32_bf16 v[26:29], v[94:97], v[202:205], v[26:29]
	v_mfma_f32_16x16x32_bf16 v[14:17], v[54:57], v[210:213], v[14:17]
	v_mfma_f32_16x16x32_bf16 v[10:13], v[94:97], v[210:213], v[10:13]
	s_setprio 0
	s_setprio 1
	v_mfma_f32_16x16x32_bf16 v[42:45], v[110:113], v[172:175], v[42:45]
	v_mfma_f32_16x16x32_bf16 v[38:41], v[146:149], v[172:175], v[38:41]
	v_mfma_f32_16x16x32_bf16 v[22:25], v[110:113], v[190:193], v[22:25]
	v_mfma_f32_16x16x32_bf16 v[18:21], v[146:149], v[190:193], v[18:21]
	v_mfma_f32_16x16x32_bf16 v[6:9], v[110:113], v[206:209], v[6:9]
	v_mfma_f32_16x16x32_bf16 v[2:5], v[146:149], v[206:209], v[2:5]
	v_mfma_f32_16x16x32_bf16 v[34:37], v[110:113], v[164:167], v[62:65]
	v_mfma_f32_16x16x32_bf16 v[54:57], v[146:149], v[164:167], v[58:61]
	v_mfma_f32_16x16x32_bf16 v[42:45], v[126:129], v[176:179], v[42:45]
	v_mfma_f32_16x16x32_bf16 v[38:41], v[160:163], v[176:179], v[38:41]
	v_mfma_f32_16x16x32_bf16 v[22:25], v[126:129], v[202:205], v[22:25]
	v_mfma_f32_16x16x32_bf16 v[18:21], v[160:163], v[202:205], v[18:21]
	v_mfma_f32_16x16x32_bf16 v[6:9], v[126:129], v[210:213], v[6:9]
	v_mfma_f32_16x16x32_bf16 v[2:5], v[160:163], v[210:213], v[2:5]
	v_mfma_f32_16x16x32_bf16 v[34:37], v[126:129], v[168:171], v[34:37]
	v_mfma_f32_16x16x32_bf16 v[54:57], v[160:163], v[168:171], v[54:57]
	s_barrier
; #define PG8_STAGE(bufoff, gbase, voff) do { _Pragma("unroll") for (int _i = 0; _i < 2; ++_i) { \
;         const unsigned _m0 = ldsb + (unsigned)((bufoff) + _i * 8192); const char* _gb = (const char*)(gbase); \
;         asm volatile("s_mov_b32 m0, %0\n\ts_nop 0\n\tglobal_load_lds_dwordx4 %1, %2" :: "s"(_m0), "v"((voff)[_i]), "s"(_gb) : "m0", "memory"); } } while (0)
; #define PG8_LDA(dst, b, h) do { _Pragma("unroll") for (int m = 0; m < 4; ++m) _Pragma("unroll") for (int k = 0; k < 2; ++k) dst[m][k] = *(const LAS bf16x8*)(lds + PG8_SA(b, h) + aoff + m * 2048 + k * 1024); } while (0)
; #define PG8_LDB(dst, b, h) do { _Pragma("unroll") for (int n = 0; n < 2; ++n) _Pragma("unroll") for (int k = 0; k < 2; ++k) dst[n][k] = *(const LAS bf16x8*)(lds + PG8_SB(b, h) + boff + n * 2048 + k * 1024); } while (0)
; #define PG8_MMA(ai, bj, At, Bt) do { __builtin_amdgcn_s_setprio(1); _Pragma("unroll") for (int m = 0; m < 4; ++m) _Pragma("unroll") for (int n = 0; n < 2; ++n) _Pragma("unroll") for (int k = 0; k < 2; ++k) \
;         acc[ai][bj][m][n] = __builtin_amdgcn_mfma_f32_16x16x32_bf16(Bt[n][k], At[m][k], acc[ai][bj][m][n], 0, 0, 0); __builtin_amdgcn_s_setprio(0); } while (0)
; #define PG8_WAIT_V(n) asm volatile("s_waitcnt vmcnt(" #n ")" ::: "memory")
; #define PG8_WAIT_L(n) asm volatile("s_waitcnt lgkmcnt(" #n ")" ::: "memory")
; #define PG8_BAR __builtin_amdgcn_s_barrier()
; #define PG8_SCHED __builtin_amdgcn_sched_barrier(0)
; template <class Epi, bool ALIGN_EPI>
; __device__ __forceinline__ void gemm_phase(LAS unsigned char* lds, const Gemm g, const StaticOrder& S, const Epi& E) {
;     ...
;             PG8_LDB(B0, 1, 0); PG8_LDB(B1, 1, 1); PG8_SCHED; PG8_LDA(At, 1, 0); PG8_STAGE(PG8_SA(0, 1), a2 + hstepA, voffA);
;             PG8_WAIT_V(8); PG8_WAIT_L(0); PG8_BAR; PG8_MMA(0, 0, At, B0); PG8_MMA(0, 1, At, B1); PG8_BAR; PG8_SCHED;
;             PG8_LDA(At, 1, 1); PG8_STAGE(PG8_SB(1, 0), b3, voffB); PG8_STAGE(PG8_SB(1, 1), b3 + hstepB, voffB); PG8_STAGE(PG8_SA(1, 0), a3, voffA);
;             PG8_WAIT_V(8); PG8_WAIT_L(0); PG8_BAR; PG8_MMA(1, 0, At, B0); PG8_MMA(1, 1, At, B1); PG8_BAR; PG8_SCHED;
;         }
;         if constexpr (ALIGN_EPI) { if (wr == 0) PG8_BAR; }
	s_setprio 0
	v_add_u32_e32 v0, 0x18000, v187
	ds_read_b128 v[58:61], v0
	ds_read_b128 v[62:65], v0 offset:1024
	ds_read_b128 v[74:77], v0 offset:2048
	ds_read_b128 v[94:97], v0 offset:3072
	v_add_u32_e32 v0, 0x1c000, v187
	ds_read_b128 v[110:113], v0
	ds_read_b128 v[126:129], v0 offset:1024
	ds_read_b128 v[146:149], v0 offset:2048
	ds_read_b128 v[160:163], v0 offset:3072
	ds_read_b128 v[164:167], v188 offset:32768
	ds_read_b128 v[168:171], v188 offset:33792
	ds_read_b128 v[172:175], v188 offset:34816
	ds_read_b128 v[176:179], v188 offset:35840
	ds_read_b128 v[190:193], v188 offset:36864
	ds_read_b128 v[202:205], v188 offset:37888
	ds_read_b128 v[206:209], v188 offset:38912
	ds_read_b128 v[210:213], v188 offset:39936
	s_add_u32 s54, s54, 0x40000
	s_addc_u32 s55, s55, 0
	s_mov_b32 m0, s58
	s_nop 0
	global_load_lds_dwordx4 v180, s[54:55]
	s_nop 0
	s_mov_b32 m0, s59
	s_nop 0
	global_load_lds_dwordx4 v182, s[54:55]
	s_waitcnt vmcnt(8)
	s_waitcnt lgkmcnt(0)
	s_setprio 1
	s_barrier
	v_mfma_f32_16x16x32_bf16 v[154:157], v[58:61], v[164:167], v[154:157]
	v_mfma_f32_16x16x32_bf16 v[154:157], v[62:65], v[168:171], v[154:157]
	v_mfma_f32_16x16x32_bf16 v[150:153], v[94:97], v[168:171], v[150:153]
	v_mfma_f32_16x16x32_bf16 v[150:153], v[74:77], v[164:167], v[150:153]
	v_mfma_f32_16x16x32_bf16 v[142:145], v[110:113], v[164:167], v[142:145]
	v_mfma_f32_16x16x32_bf16 v[142:145], v[126:129], v[168:171], v[142:145]
	v_mfma_f32_16x16x32_bf16 v[138:141], v[160:163], v[168:171], v[138:141]
	v_mfma_f32_16x16x32_bf16 v[138:141], v[146:149], v[164:167], v[138:141]
	v_mfma_f32_16x16x32_bf16 v[118:121], v[146:149], v[172:175], v[118:121]
	v_mfma_f32_16x16x32_bf16 v[118:121], v[160:163], v[176:179], v[118:121]
	v_mfma_f32_16x16x32_bf16 v[122:125], v[126:129], v[176:179], v[122:125]
	v_mfma_f32_16x16x32_bf16 v[122:125], v[110:113], v[172:175], v[122:125]
	v_mfma_f32_16x16x32_bf16 v[130:133], v[74:77], v[172:175], v[130:133]
	v_mfma_f32_16x16x32_bf16 v[130:133], v[94:97], v[176:179], v[130:133]
	v_mfma_f32_16x16x32_bf16 v[134:137], v[62:65], v[176:179], v[134:137]
	v_mfma_f32_16x16x32_bf16 v[134:137], v[58:61], v[172:175], v[134:137]
	v_mfma_f32_16x16x32_bf16 v[114:117], v[58:61], v[190:193], v[114:117]
	v_mfma_f32_16x16x32_bf16 v[114:117], v[62:65], v[202:205], v[114:117]
	v_mfma_f32_16x16x32_bf16 v[106:109], v[94:97], v[202:205], v[106:109]
	v_mfma_f32_16x16x32_bf16 v[106:109], v[74:77], v[190:193], v[106:109]
	v_mfma_f32_16x16x32_bf16 v[102:105], v[110:113], v[190:193], v[102:105]
	v_mfma_f32_16x16x32_bf16 v[102:105], v[126:129], v[202:205], v[102:105]
	v_mfma_f32_16x16x32_bf16 v[98:101], v[160:163], v[202:205], v[98:101]
	v_mfma_f32_16x16x32_bf16 v[98:101], v[146:149], v[190:193], v[98:101]
	v_mfma_f32_16x16x32_bf16 v[78:81], v[146:149], v[206:209], v[78:81]
	v_mfma_f32_16x16x32_bf16 v[78:81], v[160:163], v[210:213], v[78:81]
	v_mfma_f32_16x16x32_bf16 v[82:85], v[126:129], v[210:213], v[82:85]
	v_mfma_f32_16x16x32_bf16 v[82:85], v[110:113], v[206:209], v[82:85]
	v_mfma_f32_16x16x32_bf16 v[86:89], v[74:77], v[206:209], v[86:89]
	v_mfma_f32_16x16x32_bf16 v[86:89], v[94:97], v[210:213], v[86:89]
	v_mfma_f32_16x16x32_bf16 v[90:93], v[62:65], v[210:213], v[90:93]
	v_mfma_f32_16x16x32_bf16 v[90:93], v[58:61], v[206:209], v[90:93]
	s_barrier
	s_setprio 0
	ds_read_b128 v[164:167], v188 offset:49152
	ds_read_b128 v[168:171], v188 offset:50176
	ds_read_b128 v[172:175], v188 offset:51200
	ds_read_b128 v[176:179], v188 offset:52224
	ds_read_b128 v[190:193], v188 offset:53248
	ds_read_b128 v[202:205], v188 offset:54272
	ds_read_b128 v[206:209], v188 offset:55296
	ds_read_b128 v[210:213], v188 offset:56320
	s_add_u32 s54, s48, 0x80
	s_addc_u32 s55, s49, 0
	s_mov_b32 m0, s17
	s_nop 0
	global_load_lds_dwordx4 v181, s[54:55]
	s_add_u32 s48, s48, 0x40080
	s_mov_b32 m0, s60
	s_nop 0
	global_load_lds_dwordx4 v183, s[54:55]
	s_addc_u32 s49, s49, 0
	s_mov_b32 m0, s89
	s_nop 0
	global_load_lds_dwordx4 v181, s[48:49]
	s_nop 0
	s_mov_b32 m0, s90
	s_nop 0
	global_load_lds_dwordx4 v183, s[48:49]
	s_nop 0
	s_mov_b32 m0, s61
	s_nop 0
	global_load_lds_dwordx4 v180, s[38:39]
	s_nop 0
	s_mov_b32 m0, s88
	s_nop 0
	global_load_lds_dwordx4 v182, s[38:39]
	s_waitcnt vmcnt(8)
	s_waitcnt lgkmcnt(0)
	s_setprio 1
	s_barrier
	v_mfma_f32_16x16x32_bf16 v[70:73], v[58:61], v[164:167], v[70:73]
	v_mfma_f32_16x16x32_bf16 v[66:69], v[74:77], v[164:167], v[66:69]
	v_mfma_f32_16x16x32_bf16 v[50:53], v[58:61], v[172:175], v[50:53]
	v_mfma_f32_16x16x32_bf16 v[46:49], v[74:77], v[172:175], v[46:49]
	v_mfma_f32_16x16x32_bf16 v[30:33], v[58:61], v[190:193], v[30:33]
	v_mfma_f32_16x16x32_bf16 v[26:29], v[74:77], v[190:193], v[26:29]
	v_mfma_f32_16x16x32_bf16 v[14:17], v[58:61], v[206:209], v[14:17]
	v_mfma_f32_16x16x32_bf16 v[10:13], v[74:77], v[206:209], v[10:13]
	v_mfma_f32_16x16x32_bf16 v[70:73], v[62:65], v[168:171], v[70:73]
	v_mfma_f32_16x16x32_bf16 v[66:69], v[94:97], v[168:171], v[66:69]
	v_mfma_f32_16x16x32_bf16 v[50:53], v[62:65], v[176:179], v[50:53]
	v_mfma_f32_16x16x32_bf16 v[46:49], v[94:97], v[176:179], v[46:49]
	v_mfma_f32_16x16x32_bf16 v[30:33], v[62:65], v[202:205], v[30:33]
	v_mfma_f32_16x16x32_bf16 v[26:29], v[94:97], v[202:205], v[26:29]
	v_mfma_f32_16x16x32_bf16 v[14:17], v[62:65], v[210:213], v[14:17]
	v_mfma_f32_16x16x32_bf16 v[10:13], v[94:97], v[210:213], v[10:13]
	s_setprio 0
	s_setprio 1
	v_mfma_f32_16x16x32_bf16 v[34:37], v[110:113], v[164:167], v[34:37]
	v_mfma_f32_16x16x32_bf16 v[62:65], v[126:129], v[168:171], v[34:37]
	v_mfma_f32_16x16x32_bf16 v[34:37], v[146:149], v[164:167], v[54:57]
	v_mfma_f32_16x16x32_bf16 v[58:61], v[160:163], v[168:171], v[34:37]
	v_mfma_f32_16x16x32_bf16 v[34:37], v[110:113], v[172:175], v[42:45]
	v_mfma_f32_16x16x32_bf16 v[42:45], v[126:129], v[176:179], v[34:37]
	v_mfma_f32_16x16x32_bf16 v[34:37], v[146:149], v[172:175], v[38:41]
	v_mfma_f32_16x16x32_bf16 v[22:25], v[110:113], v[190:193], v[22:25]
	v_mfma_f32_16x16x32_bf16 v[18:21], v[146:149], v[190:193], v[18:21]
	v_mfma_f32_16x16x32_bf16 v[6:9], v[110:113], v[206:209], v[6:9]
	v_mfma_f32_16x16x32_bf16 v[2:5], v[146:149], v[206:209], v[2:5]
	v_mfma_f32_16x16x32_bf16 v[38:41], v[160:163], v[176:179], v[34:37]
	v_mfma_f32_16x16x32_bf16 v[22:25], v[126:129], v[202:205], v[22:25]
	v_mfma_f32_16x16x32_bf16 v[18:21], v[160:163], v[202:205], v[18:21]
	v_mfma_f32_16x16x32_bf16 v[6:9], v[126:129], v[210:213], v[6:9]
	v_mfma_f32_16x16x32_bf16 v[2:5], v[160:163], v[210:213], v[2:5]
	s_barrier
	s_setprio 0
	s_add_i32 s50, s50, 2
	s_add_u32 s29, s29, 0x100
	s_addc_u32 s41, s41, 0
	s_add_u32 s36, s36, 0x100
	s_addc_u32 s37, s37, 0
	s_cmp_gt_u32 s50, 13
	s_cbranch_scc0 .LBB0_349
	s_and_b64 vcc, exec, s[24:25]
	s_cbranch_vccz .LBB0_352
	s_barrier
